# LayerNorm phases (LN1, LN2) hand-written: next-row prefetch, DPP+readlane wave sums instead of ds_bpermute butterflies, sample rows spread over waves 0-1 of every workgroup
# speedup vs baseline: 1.0178x; 1.0081x over previous
; __device__ __forceinline__ int otid() { int t = threadIdx.x; asm volatile("" : "+v"(t)); return t; }
; __device__ __forceinline__ void phase_ln(float* R, const float* __restrict__ g, const float* __restrict__ b, bf16_t* xbf, float samp_scale, const float* __restrict__ part, int nsplit, bool f32_all) {
;   const int tid = otid(), lane = tid & 63, gw = blockIdx.x * 8 + (tid >> 6), nw = gridDim.x * 8;
;   f32x4 gv[4], bv[4];
; #pragma unroll
;   for (int i = 0; i < 4; ++i) { gv[i] = *(const f32x4*)(g + i * 256 + lane * 4); bv[i] = *(const f32x4*)(b + i * 256 + lane * 4); }
;   for (int r = gw; r < MT; r += nw) {
;     float* row = R + (size_t)r * 1024;
;     f32x4 v[4];
; #pragma unroll
;     for (int i = 0; i < 4; ++i) v[i] = *(const f32x4*)(row + i * 256 + lane * 4);
;     if (r >= MP) {
;       for (int sp = 0; sp < nsplit; ++sp) {
;         const float* prow = part + ((size_t)sp * MS + (r - MP)) * 1024;
; #pragma unroll
;         for (int i = 0; i < 4; ++i) v[i] = v[i] + *(const f32x4*)(prow + i * 256 + lane * 4);
;       }
;     }
;     float s = 0.f;
; #pragma unroll
;     for (int i = 0; i < 4; ++i) s += v[i][0] + v[i][1] + v[i][2] + v[i][3];
; #pragma unroll
;     for (int o = 32; o >= 1; o >>= 1) s += __shfl_xor(s, o);
;     const float mean = s * (1.f / 1024.f);
;     float ss = 0.f;
; #pragma unroll
;     for (int i = 0; i < 4; ++i) { v[i] = v[i] - mean; ss += v[i][0] * v[i][0] + v[i][1] * v[i][1] + v[i][2] * v[i][2] + v[i][3] * v[i][3]; }
; #pragma unroll
;     for (int o = 32; o >= 1; o >>= 1) ss += __shfl_xor(ss, o);
;     const float rstd = rsqrtf(ss * (1.f / 1024.f) + LN_EPS);
; #pragma unroll
;     for (int i = 0; i < 4; ++i) {
;       const f32x4 y = v[i] * rstd * gv[i] + bv[i];
;       if (r >= MP) *(f32x4*)(row + i * 256 + lane * 4) = y * samp_scale;
;       else if (f32_all) *(f32x4*)(row + i * 256 + lane * 4) = y;
;       if (xbf) {
;         u32x2 wv;
;         wv[0] = cvt_pk_bf16(y[0], y[1]); wv[1] = cvt_pk_bf16(y[2], y[3]);
;         *(u32x2*)(xbf + (size_t)r * 1024 + i * 256 + lane * 4) = wv;
;       }
;     }
.LBB0_3720:
	s_or_b64 exec, exec, s[0:1]
	v_readlane_b32 s0, v254, 51
	s_nop 0
	s_cmp_lg_u32 s0, 0
	s_cbranch_scc1 .Lln1_orig
	v_readlane_b32 s6, v254, 2
	v_readlane_b32 s7, v254, 3
	v_readlane_b32 s8, v255, 22
	s_waitcnt lgkmcnt(0)
	s_barrier
	s_load_dwordx4 s[0:3], s[6:7], 0x78
	s_load_dwordx4 s[4:7], s[6:7], 0xa8
	v_readlane_b32 s9, v254, 15
	v_readfirstlane_b32 s10, v244
	v_lshlrev_b32_e32 v114, 4, v252
	v_lshlrev_b32_e32 v115, 3, v252
	s_lshr_b32 s10, s10, 6
	s_add_i32 s9, s9, s10
	s_lshl_b32 s11, s8, 12
	s_waitcnt lgkmcnt(0)
	s_add_u32 s0, s0, s11
	s_addc_u32 s1, s1, 0
	s_add_u32 s2, s2, s11
	s_addc_u32 s3, s3, 0
	global_load_dwordx4 v[34:37], v114, s[0:1] offset:0
	global_load_dwordx4 v[38:41], v114, s[0:1] offset:1024
	global_load_dwordx4 v[42:45], v114, s[0:1] offset:2048
	global_load_dwordx4 v[46:49], v114, s[0:1] offset:3072
	global_load_dwordx4 v[50:53], v114, s[2:3] offset:0
	global_load_dwordx4 v[54:57], v114, s[2:3] offset:1024
	global_load_dwordx4 v[58:61], v114, s[2:3] offset:2048
	global_load_dwordx4 v[62:65], v114, s[2:3] offset:3072
	s_lshl_b32 s11, s9, 12
	s_add_u32 s0, s4, s11
	s_addc_u32 s1, s5, 0
	s_lshl_b32 s11, s9, 11
	s_add_u32 s11, s11, 0x39c0000
	s_add_u32 s2, s6, s11
	s_addc_u32 s3, s7, 0
	global_load_dwordx4 v[0:3], v114, s[0:1] offset:0
	global_load_dwordx4 v[4:7], v114, s[0:1] offset:1024
	global_load_dwordx4 v[8:11], v114, s[0:1] offset:2048
	global_load_dwordx4 v[12:15], v114, s[0:1] offset:3072
	s_add_u32 s0, s0, 0x800000
	s_addc_u32 s1, s1, 0
	global_load_dwordx4 v[18:21], v114, s[0:1] offset:0
	global_load_dwordx4 v[22:25], v114, s[0:1] offset:1024
	global_load_dwordx4 v[26:29], v114, s[0:1] offset:2048
	global_load_dwordx4 v[30:33], v114, s[0:1] offset:3072
	s_waitcnt vmcnt(4)
	v_pk_add_f32 v[66:67], v[0:1], v[2:3]
	v_pk_add_f32 v[68:69], v[4:5], v[6:7]
	v_pk_add_f32 v[70:71], v[8:9], v[10:11]
	v_pk_add_f32 v[72:73], v[12:13], v[14:15]
	v_pk_add_f32 v[66:67], v[66:67], v[68:69]
	v_pk_add_f32 v[70:71], v[70:71], v[72:73]
	v_pk_add_f32 v[66:67], v[66:67], v[70:71]
	v_add_f32_e32 v66, v66, v67
	s_nop 1
	v_add_f32_dpp v66, v66, v66 row_shr:1 row_mask:0xf bank_mask:0xf bound_ctrl:1
	s_nop 1
	v_add_f32_dpp v66, v66, v66 row_shr:2 row_mask:0xf bank_mask:0xf bound_ctrl:1
	s_nop 1
	v_add_f32_dpp v66, v66, v66 row_shr:4 row_mask:0xf bank_mask:0xf bound_ctrl:1
	s_nop 1
	v_add_f32_dpp v66, v66, v66 row_shr:8 row_mask:0xf bank_mask:0xf bound_ctrl:1
	s_nop 0
	v_readlane_b32 s9, v66, 15
	v_readlane_b32 s10, v66, 31
	v_readlane_b32 s11, v66, 47
	v_readlane_b32 vcc_lo, v66, 63
	s_nop 1
	v_mov_b32_e32 v66, s9
	v_add_f32_e32 v66, s10, v66
	v_add_f32_e32 v66, s11, v66
	v_add_f32_e32 v66, vcc_lo, v66
	v_mul_f32_e32 v116, 0x3a800000, v66
	v_mov_b32_e32 v117, v116
	v_pk_add_f32 v[0:1], v[0:1], v[116:117] neg_lo:[0,1] neg_hi:[0,1]
	v_pk_add_f32 v[2:3], v[2:3], v[116:117] neg_lo:[0,1] neg_hi:[0,1]
	v_pk_add_f32 v[4:5], v[4:5], v[116:117] neg_lo:[0,1] neg_hi:[0,1]
	v_pk_add_f32 v[6:7], v[6:7], v[116:117] neg_lo:[0,1] neg_hi:[0,1]
	v_pk_add_f32 v[8:9], v[8:9], v[116:117] neg_lo:[0,1] neg_hi:[0,1]
	v_pk_add_f32 v[10:11], v[10:11], v[116:117] neg_lo:[0,1] neg_hi:[0,1]
	v_pk_add_f32 v[12:13], v[12:13], v[116:117] neg_lo:[0,1] neg_hi:[0,1]
	v_pk_add_f32 v[14:15], v[14:15], v[116:117] neg_lo:[0,1] neg_hi:[0,1]
	v_pk_mul_f32 v[66:67], v[0:1], v[0:1]
	v_pk_mul_f32 v[68:69], v[2:3], v[2:3]
	v_pk_fma_f32 v[66:67], v[4:5], v[4:5], v[66:67]
	v_pk_fma_f32 v[68:69], v[6:7], v[6:7], v[68:69]
	v_pk_fma_f32 v[66:67], v[8:9], v[8:9], v[66:67]
	v_pk_fma_f32 v[68:69], v[10:11], v[10:11], v[68:69]
	v_pk_fma_f32 v[66:67], v[12:13], v[12:13], v[66:67]
	v_pk_fma_f32 v[68:69], v[14:15], v[14:15], v[68:69]
	v_pk_add_f32 v[66:67], v[66:67], v[68:69]
	v_add_f32_e32 v66, v66, v67
	s_nop 1
	v_add_f32_dpp v66, v66, v66 row_shr:1 row_mask:0xf bank_mask:0xf bound_ctrl:1
	s_nop 1
	v_add_f32_dpp v66, v66, v66 row_shr:2 row_mask:0xf bank_mask:0xf bound_ctrl:1
	s_nop 1
	v_add_f32_dpp v66, v66, v66 row_shr:4 row_mask:0xf bank_mask:0xf bound_ctrl:1
	s_nop 1
	v_add_f32_dpp v66, v66, v66 row_shr:8 row_mask:0xf bank_mask:0xf bound_ctrl:1
	s_nop 0
	v_readlane_b32 s9, v66, 15
	v_readlane_b32 s10, v66, 31
	v_readlane_b32 s11, v66, 47
	v_readlane_b32 vcc_lo, v66, 63
	s_nop 1
	v_mov_b32_e32 v66, s9
	v_add_f32_e32 v66, s10, v66
	v_add_f32_e32 v66, s11, v66
	v_add_f32_e32 v66, vcc_lo, v66
	v_mul_f32_e32 v66, 0x3a800000, v66
	v_add_f32_e32 v66, 0x3727c5ac, v66
	v_rsq_f32_e32 v118, v66
	s_nop 0
	v_mov_b32_e32 v119, v118
	v_pk_mul_f32 v[0:1], v[0:1], v[118:119]
	v_pk_mul_f32 v[2:3], v[2:3], v[118:119]
	v_pk_mul_f32 v[4:5], v[4:5], v[118:119]
	v_pk_mul_f32 v[6:7], v[6:7], v[118:119]
	v_pk_mul_f32 v[8:9], v[8:9], v[118:119]
	v_pk_mul_f32 v[10:11], v[10:11], v[118:119]
	v_pk_mul_f32 v[12:13], v[12:13], v[118:119]
	v_pk_mul_f32 v[14:15], v[14:15], v[118:119]
	v_pk_fma_f32 v[76:77], v[0:1], v[34:35], v[50:51]
	v_pk_fma_f32 v[78:79], v[2:3], v[36:37], v[52:53]
	v_pk_fma_f32 v[80:81], v[4:5], v[38:39], v[54:55]
	v_pk_fma_f32 v[82:83], v[6:7], v[40:41], v[56:57]
	v_pk_fma_f32 v[84:85], v[8:9], v[42:43], v[58:59]
	v_pk_fma_f32 v[86:87], v[10:11], v[44:45], v[60:61]
	v_pk_fma_f32 v[88:89], v[12:13], v[46:47], v[62:63]
	v_pk_fma_f32 v[90:91], v[14:15], v[48:49], v[64:65]
	v_cvt_pk_bf16_f32 v92, v76, v77
	v_cvt_pk_bf16_f32 v93, v78, v79
	v_cvt_pk_bf16_f32 v94, v80, v81
	v_cvt_pk_bf16_f32 v95, v82, v83
	v_cvt_pk_bf16_f32 v96, v84, v85
	v_cvt_pk_bf16_f32 v97, v86, v87
	v_cvt_pk_bf16_f32 v98, v88, v89
	v_cvt_pk_bf16_f32 v99, v90, v91
	global_store_dwordx2 v115, v[92:93], s[2:3] offset:0
	global_store_dwordx2 v115, v[94:95], s[2:3] offset:512
	global_store_dwordx2 v115, v[96:97], s[2:3] offset:1024
	global_store_dwordx2 v115, v[98:99], s[2:3] offset:1536
	s_add_u32 s2, s2, 0x400000
	s_addc_u32 s3, s3, 0
	s_add_u32 s0, s0, 0x800000
	s_addc_u32 s1, s1, 0
	global_load_dwordx4 v[0:3], v114, s[0:1] offset:0
	global_load_dwordx4 v[4:7], v114, s[0:1] offset:1024
	global_load_dwordx4 v[8:11], v114, s[0:1] offset:2048
	global_load_dwordx4 v[12:15], v114, s[0:1] offset:3072
	s_waitcnt vmcnt(8)
; __device__ __forceinline__ void phase_ln(float* R, const float* __restrict__ g, const float* __restrict__ b, bf16_t* xbf, float samp_scale, const float* __restrict__ part, int nsplit, bool f32_all) {
;     ...
;   for (int r = gw; r < MT; r += nw) {
;     float* row = R + (size_t)r * 1024;
;     f32x4 v[4];
; #pragma unroll
;     for (int i = 0; i < 4; ++i) v[i] = *(const f32x4*)(row + i * 256 + lane * 4);
;     if (r >= MP) {
;       for (int sp = 0; sp < nsplit; ++sp) {
;         const float* prow = part + ((size_t)sp * MS + (r - MP)) * 1024;
; #pragma unroll
;         for (int i = 0; i < 4; ++i) v[i] = v[i] + *(const f32x4*)(prow + i * 256 + lane * 4);
;       }
;     }
;     float s = 0.f;
; #pragma unroll
;     for (int i = 0; i < 4; ++i) s += v[i][0] + v[i][1] + v[i][2] + v[i][3];
; #pragma unroll
;     for (int o = 32; o >= 1; o >>= 1) s += __shfl_xor(s, o);
;     const float mean = s * (1.f / 1024.f);
;     float ss = 0.f;
; #pragma unroll
;     for (int i = 0; i < 4; ++i) { v[i] = v[i] - mean; ss += v[i][0] * v[i][0] + v[i][1] * v[i][1] + v[i][2] * v[i][2] + v[i][3] * v[i][3]; }
; #pragma unroll
;     for (int o = 32; o >= 1; o >>= 1) ss += __shfl_xor(ss, o);
;     const float rstd = rsqrtf(ss * (1.f / 1024.f) + LN_EPS);
; #pragma unroll
;     for (int i = 0; i < 4; ++i) {
;       const f32x4 y = v[i] * rstd * gv[i] + bv[i];
;       if (r >= MP) *(f32x4*)(row + i * 256 + lane * 4) = y * samp_scale;
;       else if (f32_all) *(f32x4*)(row + i * 256 + lane * 4) = y;
;       if (xbf) {
;         u32x2 wv;
;         wv[0] = cvt_pk_bf16(y[0], y[1]); wv[1] = cvt_pk_bf16(y[2], y[3]);
;         *(u32x2*)(xbf + (size_t)r * 1024 + i * 256 + lane * 4) = wv;
;       }
;     }
	v_pk_add_f32 v[66:67], v[18:19], v[20:21]
	v_pk_add_f32 v[68:69], v[22:23], v[24:25]
	v_pk_add_f32 v[70:71], v[26:27], v[28:29]
	v_pk_add_f32 v[72:73], v[30:31], v[32:33]
	v_pk_add_f32 v[66:67], v[66:67], v[68:69]
	v_pk_add_f32 v[70:71], v[70:71], v[72:73]
	v_pk_add_f32 v[66:67], v[66:67], v[70:71]
	v_add_f32_e32 v66, v66, v67
	s_nop 1
	v_add_f32_dpp v66, v66, v66 row_shr:1 row_mask:0xf bank_mask:0xf bound_ctrl:1
	s_nop 1
	v_add_f32_dpp v66, v66, v66 row_shr:2 row_mask:0xf bank_mask:0xf bound_ctrl:1
	s_nop 1
	v_add_f32_dpp v66, v66, v66 row_shr:4 row_mask:0xf bank_mask:0xf bound_ctrl:1
	s_nop 1
	v_add_f32_dpp v66, v66, v66 row_shr:8 row_mask:0xf bank_mask:0xf bound_ctrl:1
	s_nop 0
	v_readlane_b32 s9, v66, 15
	v_readlane_b32 s10, v66, 31
	v_readlane_b32 s11, v66, 47
	v_readlane_b32 vcc_lo, v66, 63
	s_nop 1
	v_mov_b32_e32 v66, s9
	v_add_f32_e32 v66, s10, v66
	v_add_f32_e32 v66, s11, v66
	v_add_f32_e32 v66, vcc_lo, v66
	v_mul_f32_e32 v116, 0x3a800000, v66
	v_mov_b32_e32 v117, v116
	v_pk_add_f32 v[18:19], v[18:19], v[116:117] neg_lo:[0,1] neg_hi:[0,1]
	v_pk_add_f32 v[20:21], v[20:21], v[116:117] neg_lo:[0,1] neg_hi:[0,1]
	v_pk_add_f32 v[22:23], v[22:23], v[116:117] neg_lo:[0,1] neg_hi:[0,1]
	v_pk_add_f32 v[24:25], v[24:25], v[116:117] neg_lo:[0,1] neg_hi:[0,1]
	v_pk_add_f32 v[26:27], v[26:27], v[116:117] neg_lo:[0,1] neg_hi:[0,1]
	v_pk_add_f32 v[28:29], v[28:29], v[116:117] neg_lo:[0,1] neg_hi:[0,1]
	v_pk_add_f32 v[30:31], v[30:31], v[116:117] neg_lo:[0,1] neg_hi:[0,1]
	v_pk_add_f32 v[32:33], v[32:33], v[116:117] neg_lo:[0,1] neg_hi:[0,1]
	v_pk_mul_f32 v[66:67], v[18:19], v[18:19]
	v_pk_mul_f32 v[68:69], v[20:21], v[20:21]
	v_pk_fma_f32 v[66:67], v[22:23], v[22:23], v[66:67]
	v_pk_fma_f32 v[68:69], v[24:25], v[24:25], v[68:69]
	v_pk_fma_f32 v[66:67], v[26:27], v[26:27], v[66:67]
	v_pk_fma_f32 v[68:69], v[28:29], v[28:29], v[68:69]
	v_pk_fma_f32 v[66:67], v[30:31], v[30:31], v[66:67]
	v_pk_fma_f32 v[68:69], v[32:33], v[32:33], v[68:69]
	v_pk_add_f32 v[66:67], v[66:67], v[68:69]
	v_add_f32_e32 v66, v66, v67
	s_nop 1
	v_add_f32_dpp v66, v66, v66 row_shr:1 row_mask:0xf bank_mask:0xf bound_ctrl:1
	s_nop 1
	v_add_f32_dpp v66, v66, v66 row_shr:2 row_mask:0xf bank_mask:0xf bound_ctrl:1
	s_nop 1
	v_add_f32_dpp v66, v66, v66 row_shr:4 row_mask:0xf bank_mask:0xf bound_ctrl:1
	s_nop 1
	v_add_f32_dpp v66, v66, v66 row_shr:8 row_mask:0xf bank_mask:0xf bound_ctrl:1
	s_nop 0
	v_readlane_b32 s9, v66, 15
	v_readlane_b32 s10, v66, 31
	v_readlane_b32 s11, v66, 47
	v_readlane_b32 vcc_lo, v66, 63
	s_nop 1
	v_mov_b32_e32 v66, s9
	v_add_f32_e32 v66, s10, v66
	v_add_f32_e32 v66, s11, v66
	v_add_f32_e32 v66, vcc_lo, v66
	v_mul_f32_e32 v66, 0x3a800000, v66
	v_add_f32_e32 v66, 0x3727c5ac, v66
	v_rsq_f32_e32 v118, v66
	s_nop 0
	v_mov_b32_e32 v119, v118
	v_pk_mul_f32 v[18:19], v[18:19], v[118:119]
	v_pk_mul_f32 v[20:21], v[20:21], v[118:119]
	v_pk_mul_f32 v[22:23], v[22:23], v[118:119]
	v_pk_mul_f32 v[24:25], v[24:25], v[118:119]
	v_pk_mul_f32 v[26:27], v[26:27], v[118:119]
	v_pk_mul_f32 v[28:29], v[28:29], v[118:119]
	v_pk_mul_f32 v[30:31], v[30:31], v[118:119]
	v_pk_mul_f32 v[32:33], v[32:33], v[118:119]
	v_pk_fma_f32 v[76:77], v[18:19], v[34:35], v[50:51]
	v_pk_fma_f32 v[78:79], v[20:21], v[36:37], v[52:53]
	v_pk_fma_f32 v[80:81], v[22:23], v[38:39], v[54:55]
	v_pk_fma_f32 v[82:83], v[24:25], v[40:41], v[56:57]
	v_pk_fma_f32 v[84:85], v[26:27], v[42:43], v[58:59]
	v_pk_fma_f32 v[86:87], v[28:29], v[44:45], v[60:61]
	v_pk_fma_f32 v[88:89], v[30:31], v[46:47], v[62:63]
	v_pk_fma_f32 v[90:91], v[32:33], v[48:49], v[64:65]
	v_cvt_pk_bf16_f32 v92, v76, v77
	v_cvt_pk_bf16_f32 v93, v78, v79
	v_cvt_pk_bf16_f32 v94, v80, v81
	v_cvt_pk_bf16_f32 v95, v82, v83
	v_cvt_pk_bf16_f32 v96, v84, v85
	v_cvt_pk_bf16_f32 v97, v86, v87
	v_cvt_pk_bf16_f32 v98, v88, v89
	v_cvt_pk_bf16_f32 v99, v90, v91
	global_store_dwordx2 v115, v[92:93], s[2:3] offset:0
	global_store_dwordx2 v115, v[94:95], s[2:3] offset:512
	global_store_dwordx2 v115, v[96:97], s[2:3] offset:1024
	global_store_dwordx2 v115, v[98:99], s[2:3] offset:1536
	s_add_u32 s2, s2, 0x400000
	s_addc_u32 s3, s3, 0
	s_add_u32 s0, s0, 0x800000
	s_addc_u32 s1, s1, 0
	global_load_dwordx4 v[18:21], v114, s[0:1] offset:0
	global_load_dwordx4 v[22:25], v114, s[0:1] offset:1024
	global_load_dwordx4 v[26:29], v114, s[0:1] offset:2048
	global_load_dwordx4 v[30:33], v114, s[0:1] offset:3072
	s_waitcnt vmcnt(8)
; __device__ __forceinline__ void phase_ln(float* R, const float* __restrict__ g, const float* __restrict__ b, bf16_t* xbf, float samp_scale, const float* __restrict__ part, int nsplit, bool f32_all) {
;     ...
;   for (int r = gw; r < MT; r += nw) {
;     float* row = R + (size_t)r * 1024;
;     f32x4 v[4];
; #pragma unroll
;     for (int i = 0; i < 4; ++i) v[i] = *(const f32x4*)(row + i * 256 + lane * 4);
;     if (r >= MP) {
;       for (int sp = 0; sp < nsplit; ++sp) {
;         const float* prow = part + ((size_t)sp * MS + (r - MP)) * 1024;
; #pragma unroll
;         for (int i = 0; i < 4; ++i) v[i] = v[i] + *(const f32x4*)(prow + i * 256 + lane * 4);
;       }
;     }
;     float s = 0.f;
; #pragma unroll
;     for (int i = 0; i < 4; ++i) s += v[i][0] + v[i][1] + v[i][2] + v[i][3];
; #pragma unroll
;     for (int o = 32; o >= 1; o >>= 1) s += __shfl_xor(s, o);
;     const float mean = s * (1.f / 1024.f);
;     float ss = 0.f;
; #pragma unroll
;     for (int i = 0; i < 4; ++i) { v[i] = v[i] - mean; ss += v[i][0] * v[i][0] + v[i][1] * v[i][1] + v[i][2] * v[i][2] + v[i][3] * v[i][3]; }
; #pragma unroll
;     for (int o = 32; o >= 1; o >>= 1) ss += __shfl_xor(ss, o);
;     const float rstd = rsqrtf(ss * (1.f / 1024.f) + LN_EPS);
; #pragma unroll
;     for (int i = 0; i < 4; ++i) {
;       const f32x4 y = v[i] * rstd * gv[i] + bv[i];
;       if (r >= MP) *(f32x4*)(row + i * 256 + lane * 4) = y * samp_scale;
;       else if (f32_all) *(f32x4*)(row + i * 256 + lane * 4) = y;
;       if (xbf) {
;         u32x2 wv;
;         wv[0] = cvt_pk_bf16(y[0], y[1]); wv[1] = cvt_pk_bf16(y[2], y[3]);
;         *(u32x2*)(xbf + (size_t)r * 1024 + i * 256 + lane * 4) = wv;
;       }
;     }
	v_pk_add_f32 v[66:67], v[0:1], v[2:3]
	v_pk_add_f32 v[68:69], v[4:5], v[6:7]
	v_pk_add_f32 v[70:71], v[8:9], v[10:11]
	v_pk_add_f32 v[72:73], v[12:13], v[14:15]
	v_pk_add_f32 v[66:67], v[66:67], v[68:69]
	v_pk_add_f32 v[70:71], v[70:71], v[72:73]
	v_pk_add_f32 v[66:67], v[66:67], v[70:71]
	v_add_f32_e32 v66, v66, v67
	s_nop 1
	v_add_f32_dpp v66, v66, v66 row_shr:1 row_mask:0xf bank_mask:0xf bound_ctrl:1
	s_nop 1
	v_add_f32_dpp v66, v66, v66 row_shr:2 row_mask:0xf bank_mask:0xf bound_ctrl:1
	s_nop 1
	v_add_f32_dpp v66, v66, v66 row_shr:4 row_mask:0xf bank_mask:0xf bound_ctrl:1
	s_nop 1
	v_add_f32_dpp v66, v66, v66 row_shr:8 row_mask:0xf bank_mask:0xf bound_ctrl:1
	s_nop 0
	v_readlane_b32 s9, v66, 15
	v_readlane_b32 s10, v66, 31
	v_readlane_b32 s11, v66, 47
	v_readlane_b32 vcc_lo, v66, 63
	s_nop 1
	v_mov_b32_e32 v66, s9
	v_add_f32_e32 v66, s10, v66
	v_add_f32_e32 v66, s11, v66
	v_add_f32_e32 v66, vcc_lo, v66
	v_mul_f32_e32 v116, 0x3a800000, v66
	v_mov_b32_e32 v117, v116
	v_pk_add_f32 v[0:1], v[0:1], v[116:117] neg_lo:[0,1] neg_hi:[0,1]
	v_pk_add_f32 v[2:3], v[2:3], v[116:117] neg_lo:[0,1] neg_hi:[0,1]
	v_pk_add_f32 v[4:5], v[4:5], v[116:117] neg_lo:[0,1] neg_hi:[0,1]
	v_pk_add_f32 v[6:7], v[6:7], v[116:117] neg_lo:[0,1] neg_hi:[0,1]
	v_pk_add_f32 v[8:9], v[8:9], v[116:117] neg_lo:[0,1] neg_hi:[0,1]
	v_pk_add_f32 v[10:11], v[10:11], v[116:117] neg_lo:[0,1] neg_hi:[0,1]
	v_pk_add_f32 v[12:13], v[12:13], v[116:117] neg_lo:[0,1] neg_hi:[0,1]
	v_pk_add_f32 v[14:15], v[14:15], v[116:117] neg_lo:[0,1] neg_hi:[0,1]
	v_pk_mul_f32 v[66:67], v[0:1], v[0:1]
	v_pk_mul_f32 v[68:69], v[2:3], v[2:3]
	v_pk_fma_f32 v[66:67], v[4:5], v[4:5], v[66:67]
	v_pk_fma_f32 v[68:69], v[6:7], v[6:7], v[68:69]
	v_pk_fma_f32 v[66:67], v[8:9], v[8:9], v[66:67]
	v_pk_fma_f32 v[68:69], v[10:11], v[10:11], v[68:69]
	v_pk_fma_f32 v[66:67], v[12:13], v[12:13], v[66:67]
	v_pk_fma_f32 v[68:69], v[14:15], v[14:15], v[68:69]
	v_pk_add_f32 v[66:67], v[66:67], v[68:69]
	v_add_f32_e32 v66, v66, v67
	s_nop 1
	v_add_f32_dpp v66, v66, v66 row_shr:1 row_mask:0xf bank_mask:0xf bound_ctrl:1
	s_nop 1
	v_add_f32_dpp v66, v66, v66 row_shr:2 row_mask:0xf bank_mask:0xf bound_ctrl:1
	s_nop 1
	v_add_f32_dpp v66, v66, v66 row_shr:4 row_mask:0xf bank_mask:0xf bound_ctrl:1
	s_nop 1
	v_add_f32_dpp v66, v66, v66 row_shr:8 row_mask:0xf bank_mask:0xf bound_ctrl:1
	s_nop 0
	v_readlane_b32 s9, v66, 15
	v_readlane_b32 s10, v66, 31
	v_readlane_b32 s11, v66, 47
	v_readlane_b32 vcc_lo, v66, 63
	s_nop 1
	v_mov_b32_e32 v66, s9
	v_add_f32_e32 v66, s10, v66
	v_add_f32_e32 v66, s11, v66
	v_add_f32_e32 v66, vcc_lo, v66
	v_mul_f32_e32 v66, 0x3a800000, v66
	v_add_f32_e32 v66, 0x3727c5ac, v66
	v_rsq_f32_e32 v118, v66
	s_nop 0
	v_mov_b32_e32 v119, v118
	v_pk_mul_f32 v[0:1], v[0:1], v[118:119]
	v_pk_mul_f32 v[2:3], v[2:3], v[118:119]
	v_pk_mul_f32 v[4:5], v[4:5], v[118:119]
	v_pk_mul_f32 v[6:7], v[6:7], v[118:119]
	v_pk_mul_f32 v[8:9], v[8:9], v[118:119]
	v_pk_mul_f32 v[10:11], v[10:11], v[118:119]
	v_pk_mul_f32 v[12:13], v[12:13], v[118:119]
	v_pk_mul_f32 v[14:15], v[14:15], v[118:119]
	v_pk_fma_f32 v[76:77], v[0:1], v[34:35], v[50:51]
	v_pk_fma_f32 v[78:79], v[2:3], v[36:37], v[52:53]
	v_pk_fma_f32 v[80:81], v[4:5], v[38:39], v[54:55]
	v_pk_fma_f32 v[82:83], v[6:7], v[40:41], v[56:57]
	v_pk_fma_f32 v[84:85], v[8:9], v[42:43], v[58:59]
	v_pk_fma_f32 v[86:87], v[10:11], v[44:45], v[60:61]
	v_pk_fma_f32 v[88:89], v[12:13], v[46:47], v[62:63]
	v_pk_fma_f32 v[90:91], v[14:15], v[48:49], v[64:65]
	v_cvt_pk_bf16_f32 v92, v76, v77
	v_cvt_pk_bf16_f32 v93, v78, v79
	v_cvt_pk_bf16_f32 v94, v80, v81
	v_cvt_pk_bf16_f32 v95, v82, v83
	v_cvt_pk_bf16_f32 v96, v84, v85
	v_cvt_pk_bf16_f32 v97, v86, v87
	v_cvt_pk_bf16_f32 v98, v88, v89
	v_cvt_pk_bf16_f32 v99, v90, v91
	global_store_dwordx2 v115, v[92:93], s[2:3] offset:0
	global_store_dwordx2 v115, v[94:95], s[2:3] offset:512
	global_store_dwordx2 v115, v[96:97], s[2:3] offset:1024
	global_store_dwordx2 v115, v[98:99], s[2:3] offset:1536
	s_add_u32 s2, s2, 0x400000
	s_addc_u32 s3, s3, 0
	s_add_u32 s0, s0, 0x800000
	s_addc_u32 s1, s1, 0
	global_load_dwordx4 v[0:3], v114, s[0:1] offset:0
	global_load_dwordx4 v[4:7], v114, s[0:1] offset:1024
	global_load_dwordx4 v[8:11], v114, s[0:1] offset:2048
	global_load_dwordx4 v[12:15], v114, s[0:1] offset:3072
	s_waitcnt vmcnt(8)
; __device__ __forceinline__ void phase_ln(float* R, const float* __restrict__ g, const float* __restrict__ b, bf16_t* xbf, float samp_scale, const float* __restrict__ part, int nsplit, bool f32_all) {
;     ...
;   for (int r = gw; r < MT; r += nw) {
;     float* row = R + (size_t)r * 1024;
;     f32x4 v[4];
; #pragma unroll
;     for (int i = 0; i < 4; ++i) v[i] = *(const f32x4*)(row + i * 256 + lane * 4);
;     if (r >= MP) {
;       for (int sp = 0; sp < nsplit; ++sp) {
;         const float* prow = part + ((size_t)sp * MS + (r - MP)) * 1024;
; #pragma unroll
;         for (int i = 0; i < 4; ++i) v[i] = v[i] + *(const f32x4*)(prow + i * 256 + lane * 4);
;       }
;     }
;     float s = 0.f;
; #pragma unroll
;     for (int i = 0; i < 4; ++i) s += v[i][0] + v[i][1] + v[i][2] + v[i][3];
; #pragma unroll
;     for (int o = 32; o >= 1; o >>= 1) s += __shfl_xor(s, o);
;     const float mean = s * (1.f / 1024.f);
;     float ss = 0.f;
; #pragma unroll
;     for (int i = 0; i < 4; ++i) { v[i] = v[i] - mean; ss += v[i][0] * v[i][0] + v[i][1] * v[i][1] + v[i][2] * v[i][2] + v[i][3] * v[i][3]; }
; #pragma unroll
;     for (int o = 32; o >= 1; o >>= 1) ss += __shfl_xor(ss, o);
;     const float rstd = rsqrtf(ss * (1.f / 1024.f) + LN_EPS);
; #pragma unroll
;     for (int i = 0; i < 4; ++i) {
;       const f32x4 y = v[i] * rstd * gv[i] + bv[i];
;       if (r >= MP) *(f32x4*)(row + i * 256 + lane * 4) = y * samp_scale;
;       else if (f32_all) *(f32x4*)(row + i * 256 + lane * 4) = y;
;       if (xbf) {
;         u32x2 wv;
;         wv[0] = cvt_pk_bf16(y[0], y[1]); wv[1] = cvt_pk_bf16(y[2], y[3]);
;         *(u32x2*)(xbf + (size_t)r * 1024 + i * 256 + lane * 4) = wv;
;       }
;     }
	v_pk_add_f32 v[66:67], v[18:19], v[20:21]
	v_pk_add_f32 v[68:69], v[22:23], v[24:25]
	v_pk_add_f32 v[70:71], v[26:27], v[28:29]
	v_pk_add_f32 v[72:73], v[30:31], v[32:33]
	v_pk_add_f32 v[66:67], v[66:67], v[68:69]
	v_pk_add_f32 v[70:71], v[70:71], v[72:73]
	v_pk_add_f32 v[66:67], v[66:67], v[70:71]
	v_add_f32_e32 v66, v66, v67
	s_nop 1
	v_add_f32_dpp v66, v66, v66 row_shr:1 row_mask:0xf bank_mask:0xf bound_ctrl:1
	s_nop 1
	v_add_f32_dpp v66, v66, v66 row_shr:2 row_mask:0xf bank_mask:0xf bound_ctrl:1
	s_nop 1
	v_add_f32_dpp v66, v66, v66 row_shr:4 row_mask:0xf bank_mask:0xf bound_ctrl:1
	s_nop 1
	v_add_f32_dpp v66, v66, v66 row_shr:8 row_mask:0xf bank_mask:0xf bound_ctrl:1
	s_nop 0
	v_readlane_b32 s9, v66, 15
	v_readlane_b32 s10, v66, 31
	v_readlane_b32 s11, v66, 47
	v_readlane_b32 vcc_lo, v66, 63
	s_nop 1
	v_mov_b32_e32 v66, s9
	v_add_f32_e32 v66, s10, v66
	v_add_f32_e32 v66, s11, v66
	v_add_f32_e32 v66, vcc_lo, v66
	v_mul_f32_e32 v116, 0x3a800000, v66
	v_mov_b32_e32 v117, v116
	v_pk_add_f32 v[18:19], v[18:19], v[116:117] neg_lo:[0,1] neg_hi:[0,1]
	v_pk_add_f32 v[20:21], v[20:21], v[116:117] neg_lo:[0,1] neg_hi:[0,1]
	v_pk_add_f32 v[22:23], v[22:23], v[116:117] neg_lo:[0,1] neg_hi:[0,1]
	v_pk_add_f32 v[24:25], v[24:25], v[116:117] neg_lo:[0,1] neg_hi:[0,1]
	v_pk_add_f32 v[26:27], v[26:27], v[116:117] neg_lo:[0,1] neg_hi:[0,1]
	v_pk_add_f32 v[28:29], v[28:29], v[116:117] neg_lo:[0,1] neg_hi:[0,1]
	v_pk_add_f32 v[30:31], v[30:31], v[116:117] neg_lo:[0,1] neg_hi:[0,1]
	v_pk_add_f32 v[32:33], v[32:33], v[116:117] neg_lo:[0,1] neg_hi:[0,1]
	v_pk_mul_f32 v[66:67], v[18:19], v[18:19]
	v_pk_mul_f32 v[68:69], v[20:21], v[20:21]
	v_pk_fma_f32 v[66:67], v[22:23], v[22:23], v[66:67]
	v_pk_fma_f32 v[68:69], v[24:25], v[24:25], v[68:69]
	v_pk_fma_f32 v[66:67], v[26:27], v[26:27], v[66:67]
	v_pk_fma_f32 v[68:69], v[28:29], v[28:29], v[68:69]
	v_pk_fma_f32 v[66:67], v[30:31], v[30:31], v[66:67]
	v_pk_fma_f32 v[68:69], v[32:33], v[32:33], v[68:69]
	v_pk_add_f32 v[66:67], v[66:67], v[68:69]
	v_add_f32_e32 v66, v66, v67
	s_nop 1
	v_add_f32_dpp v66, v66, v66 row_shr:1 row_mask:0xf bank_mask:0xf bound_ctrl:1
	s_nop 1
	v_add_f32_dpp v66, v66, v66 row_shr:2 row_mask:0xf bank_mask:0xf bound_ctrl:1
	s_nop 1
	v_add_f32_dpp v66, v66, v66 row_shr:4 row_mask:0xf bank_mask:0xf bound_ctrl:1
	s_nop 1
	v_add_f32_dpp v66, v66, v66 row_shr:8 row_mask:0xf bank_mask:0xf bound_ctrl:1
	s_nop 0
	v_readlane_b32 s9, v66, 15
	v_readlane_b32 s10, v66, 31
	v_readlane_b32 s11, v66, 47
	v_readlane_b32 vcc_lo, v66, 63
	s_nop 1
	v_mov_b32_e32 v66, s9
	v_add_f32_e32 v66, s10, v66
	v_add_f32_e32 v66, s11, v66
	v_add_f32_e32 v66, vcc_lo, v66
	v_mul_f32_e32 v66, 0x3a800000, v66
	v_add_f32_e32 v66, 0x3727c5ac, v66
	v_rsq_f32_e32 v118, v66
	s_nop 0
	v_mov_b32_e32 v119, v118
	v_pk_mul_f32 v[18:19], v[18:19], v[118:119]
	v_pk_mul_f32 v[20:21], v[20:21], v[118:119]
	v_pk_mul_f32 v[22:23], v[22:23], v[118:119]
	v_pk_mul_f32 v[24:25], v[24:25], v[118:119]
	v_pk_mul_f32 v[26:27], v[26:27], v[118:119]
	v_pk_mul_f32 v[28:29], v[28:29], v[118:119]
	v_pk_mul_f32 v[30:31], v[30:31], v[118:119]
	v_pk_mul_f32 v[32:33], v[32:33], v[118:119]
	v_pk_fma_f32 v[76:77], v[18:19], v[34:35], v[50:51]
	v_pk_fma_f32 v[78:79], v[20:21], v[36:37], v[52:53]
	v_pk_fma_f32 v[80:81], v[22:23], v[38:39], v[54:55]
	v_pk_fma_f32 v[82:83], v[24:25], v[40:41], v[56:57]
	v_pk_fma_f32 v[84:85], v[26:27], v[42:43], v[58:59]
	v_pk_fma_f32 v[86:87], v[28:29], v[44:45], v[60:61]
	v_pk_fma_f32 v[88:89], v[30:31], v[46:47], v[62:63]
	v_pk_fma_f32 v[90:91], v[32:33], v[48:49], v[64:65]
	v_cvt_pk_bf16_f32 v92, v76, v77
	v_cvt_pk_bf16_f32 v93, v78, v79
	v_cvt_pk_bf16_f32 v94, v80, v81
	v_cvt_pk_bf16_f32 v95, v82, v83
	v_cvt_pk_bf16_f32 v96, v84, v85
	v_cvt_pk_bf16_f32 v97, v86, v87
	v_cvt_pk_bf16_f32 v98, v88, v89
	v_cvt_pk_bf16_f32 v99, v90, v91
	global_store_dwordx2 v115, v[92:93], s[2:3] offset:0
	global_store_dwordx2 v115, v[94:95], s[2:3] offset:512
	global_store_dwordx2 v115, v[96:97], s[2:3] offset:1024
	global_store_dwordx2 v115, v[98:99], s[2:3] offset:1536
	s_add_u32 s2, s2, 0x400000
	s_addc_u32 s3, s3, 0
	s_add_u32 s0, s0, 0x800000
	s_addc_u32 s1, s1, 0
	global_load_dwordx4 v[18:21], v114, s[0:1] offset:0
	global_load_dwordx4 v[22:25], v114, s[0:1] offset:1024
	global_load_dwordx4 v[26:29], v114, s[0:1] offset:2048
	global_load_dwordx4 v[30:33], v114, s[0:1] offset:3072
	s_waitcnt vmcnt(8)
; __device__ __forceinline__ void phase_ln(float* R, const float* __restrict__ g, const float* __restrict__ b, bf16_t* xbf, float samp_scale, const float* __restrict__ part, int nsplit, bool f32_all) {
;     ...
;   for (int r = gw; r < MT; r += nw) {
;     float* row = R + (size_t)r * 1024;
;     f32x4 v[4];
; #pragma unroll
;     for (int i = 0; i < 4; ++i) v[i] = *(const f32x4*)(row + i * 256 + lane * 4);
;     if (r >= MP) {
;       for (int sp = 0; sp < nsplit; ++sp) {
;         const float* prow = part + ((size_t)sp * MS + (r - MP)) * 1024;
; #pragma unroll
;         for (int i = 0; i < 4; ++i) v[i] = v[i] + *(const f32x4*)(prow + i * 256 + lane * 4);
;       }
;     }
;     float s = 0.f;
; #pragma unroll
;     for (int i = 0; i < 4; ++i) s += v[i][0] + v[i][1] + v[i][2] + v[i][3];
; #pragma unroll
;     for (int o = 32; o >= 1; o >>= 1) s += __shfl_xor(s, o);
;     const float mean = s * (1.f / 1024.f);
;     float ss = 0.f;
; #pragma unroll
;     for (int i = 0; i < 4; ++i) { v[i] = v[i] - mean; ss += v[i][0] * v[i][0] + v[i][1] * v[i][1] + v[i][2] * v[i][2] + v[i][3] * v[i][3]; }
; #pragma unroll
;     for (int o = 32; o >= 1; o >>= 1) ss += __shfl_xor(ss, o);
;     const float rstd = rsqrtf(ss * (1.f / 1024.f) + LN_EPS);
; #pragma unroll
;     for (int i = 0; i < 4; ++i) {
;       const f32x4 y = v[i] * rstd * gv[i] + bv[i];
;       if (r >= MP) *(f32x4*)(row + i * 256 + lane * 4) = y * samp_scale;
;       else if (f32_all) *(f32x4*)(row + i * 256 + lane * 4) = y;
;       if (xbf) {
;         u32x2 wv;
;         wv[0] = cvt_pk_bf16(y[0], y[1]); wv[1] = cvt_pk_bf16(y[2], y[3]);
;         *(u32x2*)(xbf + (size_t)r * 1024 + i * 256 + lane * 4) = wv;
;       }
;     }
	v_pk_add_f32 v[66:67], v[0:1], v[2:3]
	v_pk_add_f32 v[68:69], v[4:5], v[6:7]
	v_pk_add_f32 v[70:71], v[8:9], v[10:11]
	v_pk_add_f32 v[72:73], v[12:13], v[14:15]
	v_pk_add_f32 v[66:67], v[66:67], v[68:69]
	v_pk_add_f32 v[70:71], v[70:71], v[72:73]
	v_pk_add_f32 v[66:67], v[66:67], v[70:71]
	v_add_f32_e32 v66, v66, v67
	s_nop 1
	v_add_f32_dpp v66, v66, v66 row_shr:1 row_mask:0xf bank_mask:0xf bound_ctrl:1
	s_nop 1
	v_add_f32_dpp v66, v66, v66 row_shr:2 row_mask:0xf bank_mask:0xf bound_ctrl:1
	s_nop 1
	v_add_f32_dpp v66, v66, v66 row_shr:4 row_mask:0xf bank_mask:0xf bound_ctrl:1
	s_nop 1
	v_add_f32_dpp v66, v66, v66 row_shr:8 row_mask:0xf bank_mask:0xf bound_ctrl:1
	s_nop 0
	v_readlane_b32 s9, v66, 15
	v_readlane_b32 s10, v66, 31
	v_readlane_b32 s11, v66, 47
	v_readlane_b32 vcc_lo, v66, 63
	s_nop 1
	v_mov_b32_e32 v66, s9
	v_add_f32_e32 v66, s10, v66
	v_add_f32_e32 v66, s11, v66
	v_add_f32_e32 v66, vcc_lo, v66
	v_mul_f32_e32 v116, 0x3a800000, v66
	v_mov_b32_e32 v117, v116
	v_pk_add_f32 v[0:1], v[0:1], v[116:117] neg_lo:[0,1] neg_hi:[0,1]
	v_pk_add_f32 v[2:3], v[2:3], v[116:117] neg_lo:[0,1] neg_hi:[0,1]
	v_pk_add_f32 v[4:5], v[4:5], v[116:117] neg_lo:[0,1] neg_hi:[0,1]
	v_pk_add_f32 v[6:7], v[6:7], v[116:117] neg_lo:[0,1] neg_hi:[0,1]
	v_pk_add_f32 v[8:9], v[8:9], v[116:117] neg_lo:[0,1] neg_hi:[0,1]
	v_pk_add_f32 v[10:11], v[10:11], v[116:117] neg_lo:[0,1] neg_hi:[0,1]
	v_pk_add_f32 v[12:13], v[12:13], v[116:117] neg_lo:[0,1] neg_hi:[0,1]
	v_pk_add_f32 v[14:15], v[14:15], v[116:117] neg_lo:[0,1] neg_hi:[0,1]
	v_pk_mul_f32 v[66:67], v[0:1], v[0:1]
	v_pk_mul_f32 v[68:69], v[2:3], v[2:3]
	v_pk_fma_f32 v[66:67], v[4:5], v[4:5], v[66:67]
	v_pk_fma_f32 v[68:69], v[6:7], v[6:7], v[68:69]
	v_pk_fma_f32 v[66:67], v[8:9], v[8:9], v[66:67]
	v_pk_fma_f32 v[68:69], v[10:11], v[10:11], v[68:69]
	v_pk_fma_f32 v[66:67], v[12:13], v[12:13], v[66:67]
	v_pk_fma_f32 v[68:69], v[14:15], v[14:15], v[68:69]
	v_pk_add_f32 v[66:67], v[66:67], v[68:69]
	v_add_f32_e32 v66, v66, v67
	s_nop 1
	v_add_f32_dpp v66, v66, v66 row_shr:1 row_mask:0xf bank_mask:0xf bound_ctrl:1
	s_nop 1
	v_add_f32_dpp v66, v66, v66 row_shr:2 row_mask:0xf bank_mask:0xf bound_ctrl:1
	s_nop 1
	v_add_f32_dpp v66, v66, v66 row_shr:4 row_mask:0xf bank_mask:0xf bound_ctrl:1
	s_nop 1
	v_add_f32_dpp v66, v66, v66 row_shr:8 row_mask:0xf bank_mask:0xf bound_ctrl:1
	s_nop 0
	v_readlane_b32 s9, v66, 15
	v_readlane_b32 s10, v66, 31
	v_readlane_b32 s11, v66, 47
	v_readlane_b32 vcc_lo, v66, 63
	s_nop 1
	v_mov_b32_e32 v66, s9
	v_add_f32_e32 v66, s10, v66
	v_add_f32_e32 v66, s11, v66
	v_add_f32_e32 v66, vcc_lo, v66
	v_mul_f32_e32 v66, 0x3a800000, v66
	v_add_f32_e32 v66, 0x3727c5ac, v66
	v_rsq_f32_e32 v118, v66
	s_nop 0
	v_mov_b32_e32 v119, v118
	v_pk_mul_f32 v[0:1], v[0:1], v[118:119]
	v_pk_mul_f32 v[2:3], v[2:3], v[118:119]
	v_pk_mul_f32 v[4:5], v[4:5], v[118:119]
	v_pk_mul_f32 v[6:7], v[6:7], v[118:119]
	v_pk_mul_f32 v[8:9], v[8:9], v[118:119]
	v_pk_mul_f32 v[10:11], v[10:11], v[118:119]
	v_pk_mul_f32 v[12:13], v[12:13], v[118:119]
	v_pk_mul_f32 v[14:15], v[14:15], v[118:119]
	v_pk_fma_f32 v[76:77], v[0:1], v[34:35], v[50:51]
	v_pk_fma_f32 v[78:79], v[2:3], v[36:37], v[52:53]
	v_pk_fma_f32 v[80:81], v[4:5], v[38:39], v[54:55]
	v_pk_fma_f32 v[82:83], v[6:7], v[40:41], v[56:57]
	v_pk_fma_f32 v[84:85], v[8:9], v[42:43], v[58:59]
	v_pk_fma_f32 v[86:87], v[10:11], v[44:45], v[60:61]
	v_pk_fma_f32 v[88:89], v[12:13], v[46:47], v[62:63]
	v_pk_fma_f32 v[90:91], v[14:15], v[48:49], v[64:65]
	v_cvt_pk_bf16_f32 v92, v76, v77
	v_cvt_pk_bf16_f32 v93, v78, v79
	v_cvt_pk_bf16_f32 v94, v80, v81
	v_cvt_pk_bf16_f32 v95, v82, v83
	v_cvt_pk_bf16_f32 v96, v84, v85
	v_cvt_pk_bf16_f32 v97, v86, v87
	v_cvt_pk_bf16_f32 v98, v88, v89
	v_cvt_pk_bf16_f32 v99, v90, v91
	global_store_dwordx2 v115, v[92:93], s[2:3] offset:0
	global_store_dwordx2 v115, v[94:95], s[2:3] offset:512
	global_store_dwordx2 v115, v[96:97], s[2:3] offset:1024
	global_store_dwordx2 v115, v[98:99], s[2:3] offset:1536
	s_add_u32 s2, s2, 0x400000
	s_addc_u32 s3, s3, 0
	s_add_u32 s0, s0, 0x800000
	s_addc_u32 s1, s1, 0
	global_load_dwordx4 v[0:3], v114, s[0:1] offset:0
	global_load_dwordx4 v[4:7], v114, s[0:1] offset:1024
	global_load_dwordx4 v[8:11], v114, s[0:1] offset:2048
	global_load_dwordx4 v[12:15], v114, s[0:1] offset:3072
	s_waitcnt vmcnt(8)
; __device__ __forceinline__ void phase_ln(float* R, const float* __restrict__ g, const float* __restrict__ b, bf16_t* xbf, float samp_scale, const float* __restrict__ part, int nsplit, bool f32_all) {
;     ...
;   for (int r = gw; r < MT; r += nw) {
;     float* row = R + (size_t)r * 1024;
;     f32x4 v[4];
; #pragma unroll
;     for (int i = 0; i < 4; ++i) v[i] = *(const f32x4*)(row + i * 256 + lane * 4);
;     if (r >= MP) {
;       for (int sp = 0; sp < nsplit; ++sp) {
;         const float* prow = part + ((size_t)sp * MS + (r - MP)) * 1024;
; #pragma unroll
;         for (int i = 0; i < 4; ++i) v[i] = v[i] + *(const f32x4*)(prow + i * 256 + lane * 4);
;       }
;     }
;     float s = 0.f;
; #pragma unroll
;     for (int i = 0; i < 4; ++i) s += v[i][0] + v[i][1] + v[i][2] + v[i][3];
; #pragma unroll
;     for (int o = 32; o >= 1; o >>= 1) s += __shfl_xor(s, o);
;     const float mean = s * (1.f / 1024.f);
;     float ss = 0.f;
; #pragma unroll
;     for (int i = 0; i < 4; ++i) { v[i] = v[i] - mean; ss += v[i][0] * v[i][0] + v[i][1] * v[i][1] + v[i][2] * v[i][2] + v[i][3] * v[i][3]; }
; #pragma unroll
;     for (int o = 32; o >= 1; o >>= 1) ss += __shfl_xor(ss, o);
;     const float rstd = rsqrtf(ss * (1.f / 1024.f) + LN_EPS);
; #pragma unroll
;     for (int i = 0; i < 4; ++i) {
;       const f32x4 y = v[i] * rstd * gv[i] + bv[i];
;       if (r >= MP) *(f32x4*)(row + i * 256 + lane * 4) = y * samp_scale;
;       else if (f32_all) *(f32x4*)(row + i * 256 + lane * 4) = y;
;       if (xbf) {
;         u32x2 wv;
;         wv[0] = cvt_pk_bf16(y[0], y[1]); wv[1] = cvt_pk_bf16(y[2], y[3]);
;         *(u32x2*)(xbf + (size_t)r * 1024 + i * 256 + lane * 4) = wv;
;       }
;     }
	v_pk_add_f32 v[66:67], v[18:19], v[20:21]
	v_pk_add_f32 v[68:69], v[22:23], v[24:25]
	v_pk_add_f32 v[70:71], v[26:27], v[28:29]
	v_pk_add_f32 v[72:73], v[30:31], v[32:33]
	v_pk_add_f32 v[66:67], v[66:67], v[68:69]
	v_pk_add_f32 v[70:71], v[70:71], v[72:73]
	v_pk_add_f32 v[66:67], v[66:67], v[70:71]
	v_add_f32_e32 v66, v66, v67
	s_nop 1
	v_add_f32_dpp v66, v66, v66 row_shr:1 row_mask:0xf bank_mask:0xf bound_ctrl:1
	s_nop 1
	v_add_f32_dpp v66, v66, v66 row_shr:2 row_mask:0xf bank_mask:0xf bound_ctrl:1
	s_nop 1
	v_add_f32_dpp v66, v66, v66 row_shr:4 row_mask:0xf bank_mask:0xf bound_ctrl:1
	s_nop 1
	v_add_f32_dpp v66, v66, v66 row_shr:8 row_mask:0xf bank_mask:0xf bound_ctrl:1
	s_nop 0
	v_readlane_b32 s9, v66, 15
	v_readlane_b32 s10, v66, 31
	v_readlane_b32 s11, v66, 47
	v_readlane_b32 vcc_lo, v66, 63
	s_nop 1
	v_mov_b32_e32 v66, s9
	v_add_f32_e32 v66, s10, v66
	v_add_f32_e32 v66, s11, v66
	v_add_f32_e32 v66, vcc_lo, v66
	v_mul_f32_e32 v116, 0x3a800000, v66
	v_mov_b32_e32 v117, v116
	v_pk_add_f32 v[18:19], v[18:19], v[116:117] neg_lo:[0,1] neg_hi:[0,1]
	v_pk_add_f32 v[20:21], v[20:21], v[116:117] neg_lo:[0,1] neg_hi:[0,1]
	v_pk_add_f32 v[22:23], v[22:23], v[116:117] neg_lo:[0,1] neg_hi:[0,1]
	v_pk_add_f32 v[24:25], v[24:25], v[116:117] neg_lo:[0,1] neg_hi:[0,1]
	v_pk_add_f32 v[26:27], v[26:27], v[116:117] neg_lo:[0,1] neg_hi:[0,1]
	v_pk_add_f32 v[28:29], v[28:29], v[116:117] neg_lo:[0,1] neg_hi:[0,1]
	v_pk_add_f32 v[30:31], v[30:31], v[116:117] neg_lo:[0,1] neg_hi:[0,1]
	v_pk_add_f32 v[32:33], v[32:33], v[116:117] neg_lo:[0,1] neg_hi:[0,1]
	v_pk_mul_f32 v[66:67], v[18:19], v[18:19]
	v_pk_mul_f32 v[68:69], v[20:21], v[20:21]
	v_pk_fma_f32 v[66:67], v[22:23], v[22:23], v[66:67]
	v_pk_fma_f32 v[68:69], v[24:25], v[24:25], v[68:69]
	v_pk_fma_f32 v[66:67], v[26:27], v[26:27], v[66:67]
	v_pk_fma_f32 v[68:69], v[28:29], v[28:29], v[68:69]
	v_pk_fma_f32 v[66:67], v[30:31], v[30:31], v[66:67]
	v_pk_fma_f32 v[68:69], v[32:33], v[32:33], v[68:69]
	v_pk_add_f32 v[66:67], v[66:67], v[68:69]
	v_add_f32_e32 v66, v66, v67
	s_nop 1
	v_add_f32_dpp v66, v66, v66 row_shr:1 row_mask:0xf bank_mask:0xf bound_ctrl:1
	s_nop 1
	v_add_f32_dpp v66, v66, v66 row_shr:2 row_mask:0xf bank_mask:0xf bound_ctrl:1
	s_nop 1
	v_add_f32_dpp v66, v66, v66 row_shr:4 row_mask:0xf bank_mask:0xf bound_ctrl:1
	s_nop 1
	v_add_f32_dpp v66, v66, v66 row_shr:8 row_mask:0xf bank_mask:0xf bound_ctrl:1
	s_nop 0
	v_readlane_b32 s9, v66, 15
	v_readlane_b32 s10, v66, 31
	v_readlane_b32 s11, v66, 47
	v_readlane_b32 vcc_lo, v66, 63
	s_nop 1
	v_mov_b32_e32 v66, s9
	v_add_f32_e32 v66, s10, v66
	v_add_f32_e32 v66, s11, v66
	v_add_f32_e32 v66, vcc_lo, v66
	v_mul_f32_e32 v66, 0x3a800000, v66
	v_add_f32_e32 v66, 0x3727c5ac, v66
	v_rsq_f32_e32 v118, v66
	s_nop 0
	v_mov_b32_e32 v119, v118
	v_pk_mul_f32 v[18:19], v[18:19], v[118:119]
	v_pk_mul_f32 v[20:21], v[20:21], v[118:119]
	v_pk_mul_f32 v[22:23], v[22:23], v[118:119]
	v_pk_mul_f32 v[24:25], v[24:25], v[118:119]
	v_pk_mul_f32 v[26:27], v[26:27], v[118:119]
	v_pk_mul_f32 v[28:29], v[28:29], v[118:119]
	v_pk_mul_f32 v[30:31], v[30:31], v[118:119]
	v_pk_mul_f32 v[32:33], v[32:33], v[118:119]
	v_pk_fma_f32 v[76:77], v[18:19], v[34:35], v[50:51]
	v_pk_fma_f32 v[78:79], v[20:21], v[36:37], v[52:53]
	v_pk_fma_f32 v[80:81], v[22:23], v[38:39], v[54:55]
	v_pk_fma_f32 v[82:83], v[24:25], v[40:41], v[56:57]
	v_pk_fma_f32 v[84:85], v[26:27], v[42:43], v[58:59]
	v_pk_fma_f32 v[86:87], v[28:29], v[44:45], v[60:61]
	v_pk_fma_f32 v[88:89], v[30:31], v[46:47], v[62:63]
	v_pk_fma_f32 v[90:91], v[32:33], v[48:49], v[64:65]
	v_cvt_pk_bf16_f32 v92, v76, v77
	v_cvt_pk_bf16_f32 v93, v78, v79
	v_cvt_pk_bf16_f32 v94, v80, v81
	v_cvt_pk_bf16_f32 v95, v82, v83
	v_cvt_pk_bf16_f32 v96, v84, v85
	v_cvt_pk_bf16_f32 v97, v86, v87
	v_cvt_pk_bf16_f32 v98, v88, v89
	v_cvt_pk_bf16_f32 v99, v90, v91
	global_store_dwordx2 v115, v[92:93], s[2:3] offset:0
	global_store_dwordx2 v115, v[94:95], s[2:3] offset:512
	global_store_dwordx2 v115, v[96:97], s[2:3] offset:1024
	global_store_dwordx2 v115, v[98:99], s[2:3] offset:1536
	s_add_u32 s2, s2, 0x400000
	s_addc_u32 s3, s3, 0
	s_add_u32 s0, s0, 0x800000
	s_addc_u32 s1, s1, 0
	global_load_dwordx4 v[18:21], v114, s[0:1] offset:0
	global_load_dwordx4 v[22:25], v114, s[0:1] offset:1024
	global_load_dwordx4 v[26:29], v114, s[0:1] offset:2048
	global_load_dwordx4 v[30:33], v114, s[0:1] offset:3072
	s_waitcnt vmcnt(8)
; __device__ __forceinline__ void phase_ln(float* R, const float* __restrict__ g, const float* __restrict__ b, bf16_t* xbf, float samp_scale, const float* __restrict__ part, int nsplit, bool f32_all) {
;     ...
;   for (int r = gw; r < MT; r += nw) {
;     float* row = R + (size_t)r * 1024;
;     f32x4 v[4];
; #pragma unroll
;     for (int i = 0; i < 4; ++i) v[i] = *(const f32x4*)(row + i * 256 + lane * 4);
;     if (r >= MP) {
;       for (int sp = 0; sp < nsplit; ++sp) {
;         const float* prow = part + ((size_t)sp * MS + (r - MP)) * 1024;
; #pragma unroll
;         for (int i = 0; i < 4; ++i) v[i] = v[i] + *(const f32x4*)(prow + i * 256 + lane * 4);
;       }
;     }
;     float s = 0.f;
; #pragma unroll
;     for (int i = 0; i < 4; ++i) s += v[i][0] + v[i][1] + v[i][2] + v[i][3];
; #pragma unroll
;     for (int o = 32; o >= 1; o >>= 1) s += __shfl_xor(s, o);
;     const float mean = s * (1.f / 1024.f);
;     float ss = 0.f;
; #pragma unroll
;     for (int i = 0; i < 4; ++i) { v[i] = v[i] - mean; ss += v[i][0] * v[i][0] + v[i][1] * v[i][1] + v[i][2] * v[i][2] + v[i][3] * v[i][3]; }
; #pragma unroll
;     for (int o = 32; o >= 1; o >>= 1) ss += __shfl_xor(ss, o);
;     const float rstd = rsqrtf(ss * (1.f / 1024.f) + LN_EPS);
; #pragma unroll
;     for (int i = 0; i < 4; ++i) {
;       const f32x4 y = v[i] * rstd * gv[i] + bv[i];
;       if (r >= MP) *(f32x4*)(row + i * 256 + lane * 4) = y * samp_scale;
;       else if (f32_all) *(f32x4*)(row + i * 256 + lane * 4) = y;
;       if (xbf) {
;         u32x2 wv;
;         wv[0] = cvt_pk_bf16(y[0], y[1]); wv[1] = cvt_pk_bf16(y[2], y[3]);
;         *(u32x2*)(xbf + (size_t)r * 1024 + i * 256 + lane * 4) = wv;
;       }
;     }
	v_pk_add_f32 v[66:67], v[0:1], v[2:3]
	v_pk_add_f32 v[68:69], v[4:5], v[6:7]
	v_pk_add_f32 v[70:71], v[8:9], v[10:11]
	v_pk_add_f32 v[72:73], v[12:13], v[14:15]
	v_pk_add_f32 v[66:67], v[66:67], v[68:69]
	v_pk_add_f32 v[70:71], v[70:71], v[72:73]
	v_pk_add_f32 v[66:67], v[66:67], v[70:71]
	v_add_f32_e32 v66, v66, v67
	s_nop 1
	v_add_f32_dpp v66, v66, v66 row_shr:1 row_mask:0xf bank_mask:0xf bound_ctrl:1
	s_nop 1
	v_add_f32_dpp v66, v66, v66 row_shr:2 row_mask:0xf bank_mask:0xf bound_ctrl:1
	s_nop 1
	v_add_f32_dpp v66, v66, v66 row_shr:4 row_mask:0xf bank_mask:0xf bound_ctrl:1
	s_nop 1
	v_add_f32_dpp v66, v66, v66 row_shr:8 row_mask:0xf bank_mask:0xf bound_ctrl:1
	s_nop 0
	v_readlane_b32 s9, v66, 15
	v_readlane_b32 s10, v66, 31
	v_readlane_b32 s11, v66, 47
	v_readlane_b32 vcc_lo, v66, 63
	s_nop 1
	v_mov_b32_e32 v66, s9
	v_add_f32_e32 v66, s10, v66
	v_add_f32_e32 v66, s11, v66
	v_add_f32_e32 v66, vcc_lo, v66
	v_mul_f32_e32 v116, 0x3a800000, v66
	v_mov_b32_e32 v117, v116
	v_pk_add_f32 v[0:1], v[0:1], v[116:117] neg_lo:[0,1] neg_hi:[0,1]
	v_pk_add_f32 v[2:3], v[2:3], v[116:117] neg_lo:[0,1] neg_hi:[0,1]
	v_pk_add_f32 v[4:5], v[4:5], v[116:117] neg_lo:[0,1] neg_hi:[0,1]
	v_pk_add_f32 v[6:7], v[6:7], v[116:117] neg_lo:[0,1] neg_hi:[0,1]
	v_pk_add_f32 v[8:9], v[8:9], v[116:117] neg_lo:[0,1] neg_hi:[0,1]
	v_pk_add_f32 v[10:11], v[10:11], v[116:117] neg_lo:[0,1] neg_hi:[0,1]
	v_pk_add_f32 v[12:13], v[12:13], v[116:117] neg_lo:[0,1] neg_hi:[0,1]
	v_pk_add_f32 v[14:15], v[14:15], v[116:117] neg_lo:[0,1] neg_hi:[0,1]
	v_pk_mul_f32 v[66:67], v[0:1], v[0:1]
	v_pk_mul_f32 v[68:69], v[2:3], v[2:3]
	v_pk_fma_f32 v[66:67], v[4:5], v[4:5], v[66:67]
	v_pk_fma_f32 v[68:69], v[6:7], v[6:7], v[68:69]
	v_pk_fma_f32 v[66:67], v[8:9], v[8:9], v[66:67]
	v_pk_fma_f32 v[68:69], v[10:11], v[10:11], v[68:69]
	v_pk_fma_f32 v[66:67], v[12:13], v[12:13], v[66:67]
	v_pk_fma_f32 v[68:69], v[14:15], v[14:15], v[68:69]
	v_pk_add_f32 v[66:67], v[66:67], v[68:69]
	v_add_f32_e32 v66, v66, v67
	s_nop 1
	v_add_f32_dpp v66, v66, v66 row_shr:1 row_mask:0xf bank_mask:0xf bound_ctrl:1
	s_nop 1
	v_add_f32_dpp v66, v66, v66 row_shr:2 row_mask:0xf bank_mask:0xf bound_ctrl:1
	s_nop 1
	v_add_f32_dpp v66, v66, v66 row_shr:4 row_mask:0xf bank_mask:0xf bound_ctrl:1
	s_nop 1
	v_add_f32_dpp v66, v66, v66 row_shr:8 row_mask:0xf bank_mask:0xf bound_ctrl:1
	s_nop 0
	v_readlane_b32 s9, v66, 15
	v_readlane_b32 s10, v66, 31
	v_readlane_b32 s11, v66, 47
	v_readlane_b32 vcc_lo, v66, 63
	s_nop 1
	v_mov_b32_e32 v66, s9
	v_add_f32_e32 v66, s10, v66
	v_add_f32_e32 v66, s11, v66
	v_add_f32_e32 v66, vcc_lo, v66
	v_mul_f32_e32 v66, 0x3a800000, v66
	v_add_f32_e32 v66, 0x3727c5ac, v66
	v_rsq_f32_e32 v118, v66
	s_nop 0
	v_mov_b32_e32 v119, v118
	v_pk_mul_f32 v[0:1], v[0:1], v[118:119]
	v_pk_mul_f32 v[2:3], v[2:3], v[118:119]
	v_pk_mul_f32 v[4:5], v[4:5], v[118:119]
	v_pk_mul_f32 v[6:7], v[6:7], v[118:119]
	v_pk_mul_f32 v[8:9], v[8:9], v[118:119]
	v_pk_mul_f32 v[10:11], v[10:11], v[118:119]
	v_pk_mul_f32 v[12:13], v[12:13], v[118:119]
	v_pk_mul_f32 v[14:15], v[14:15], v[118:119]
	v_pk_fma_f32 v[76:77], v[0:1], v[34:35], v[50:51]
	v_pk_fma_f32 v[78:79], v[2:3], v[36:37], v[52:53]
	v_pk_fma_f32 v[80:81], v[4:5], v[38:39], v[54:55]
	v_pk_fma_f32 v[82:83], v[6:7], v[40:41], v[56:57]
	v_pk_fma_f32 v[84:85], v[8:9], v[42:43], v[58:59]
	v_pk_fma_f32 v[86:87], v[10:11], v[44:45], v[60:61]
	v_pk_fma_f32 v[88:89], v[12:13], v[46:47], v[62:63]
	v_pk_fma_f32 v[90:91], v[14:15], v[48:49], v[64:65]
	v_cvt_pk_bf16_f32 v92, v76, v77
	v_cvt_pk_bf16_f32 v93, v78, v79
	v_cvt_pk_bf16_f32 v94, v80, v81
	v_cvt_pk_bf16_f32 v95, v82, v83
	v_cvt_pk_bf16_f32 v96, v84, v85
	v_cvt_pk_bf16_f32 v97, v86, v87
	v_cvt_pk_bf16_f32 v98, v88, v89
	v_cvt_pk_bf16_f32 v99, v90, v91
	global_store_dwordx2 v115, v[92:93], s[2:3] offset:0
	global_store_dwordx2 v115, v[94:95], s[2:3] offset:512
	global_store_dwordx2 v115, v[96:97], s[2:3] offset:1024
	global_store_dwordx2 v115, v[98:99], s[2:3] offset:1536
	s_add_u32 s2, s2, 0x400000
	s_addc_u32 s3, s3, 0
	s_add_u32 s0, s0, 0x800000
	s_addc_u32 s1, s1, 0
	global_load_dwordx4 v[0:3], v114, s[0:1] offset:0
	global_load_dwordx4 v[4:7], v114, s[0:1] offset:1024
	global_load_dwordx4 v[8:11], v114, s[0:1] offset:2048
	global_load_dwordx4 v[12:15], v114, s[0:1] offset:3072
	s_waitcnt vmcnt(8)
; __device__ __forceinline__ void phase_ln(float* R, const float* __restrict__ g, const float* __restrict__ b, bf16_t* xbf, float samp_scale, const float* __restrict__ part, int nsplit, bool f32_all) {
;     ...
;   for (int r = gw; r < MT; r += nw) {
;     float* row = R + (size_t)r * 1024;
;     f32x4 v[4];
; #pragma unroll
;     for (int i = 0; i < 4; ++i) v[i] = *(const f32x4*)(row + i * 256 + lane * 4);
;     if (r >= MP) {
;       for (int sp = 0; sp < nsplit; ++sp) {
;         const float* prow = part + ((size_t)sp * MS + (r - MP)) * 1024;
; #pragma unroll
;         for (int i = 0; i < 4; ++i) v[i] = v[i] + *(const f32x4*)(prow + i * 256 + lane * 4);
;       }
;     }
;     float s = 0.f;
; #pragma unroll
;     for (int i = 0; i < 4; ++i) s += v[i][0] + v[i][1] + v[i][2] + v[i][3];
; #pragma unroll
;     for (int o = 32; o >= 1; o >>= 1) s += __shfl_xor(s, o);
;     const float mean = s * (1.f / 1024.f);
;     float ss = 0.f;
; #pragma unroll
;     for (int i = 0; i < 4; ++i) { v[i] = v[i] - mean; ss += v[i][0] * v[i][0] + v[i][1] * v[i][1] + v[i][2] * v[i][2] + v[i][3] * v[i][3]; }
; #pragma unroll
;     for (int o = 32; o >= 1; o >>= 1) ss += __shfl_xor(ss, o);
;     const float rstd = rsqrtf(ss * (1.f / 1024.f) + LN_EPS);
; #pragma unroll
;     for (int i = 0; i < 4; ++i) {
;       const f32x4 y = v[i] * rstd * gv[i] + bv[i];
;       if (r >= MP) *(f32x4*)(row + i * 256 + lane * 4) = y * samp_scale;
;       else if (f32_all) *(f32x4*)(row + i * 256 + lane * 4) = y;
;       if (xbf) {
;         u32x2 wv;
;         wv[0] = cvt_pk_bf16(y[0], y[1]); wv[1] = cvt_pk_bf16(y[2], y[3]);
;         *(u32x2*)(xbf + (size_t)r * 1024 + i * 256 + lane * 4) = wv;
;       }
;     }
	v_pk_add_f32 v[66:67], v[18:19], v[20:21]
	v_pk_add_f32 v[68:69], v[22:23], v[24:25]
	v_pk_add_f32 v[70:71], v[26:27], v[28:29]
	v_pk_add_f32 v[72:73], v[30:31], v[32:33]
	v_pk_add_f32 v[66:67], v[66:67], v[68:69]
	v_pk_add_f32 v[70:71], v[70:71], v[72:73]
	v_pk_add_f32 v[66:67], v[66:67], v[70:71]
	v_add_f32_e32 v66, v66, v67
	s_nop 1
	v_add_f32_dpp v66, v66, v66 row_shr:1 row_mask:0xf bank_mask:0xf bound_ctrl:1
	s_nop 1
	v_add_f32_dpp v66, v66, v66 row_shr:2 row_mask:0xf bank_mask:0xf bound_ctrl:1
	s_nop 1
	v_add_f32_dpp v66, v66, v66 row_shr:4 row_mask:0xf bank_mask:0xf bound_ctrl:1
	s_nop 1
	v_add_f32_dpp v66, v66, v66 row_shr:8 row_mask:0xf bank_mask:0xf bound_ctrl:1
	s_nop 0
	v_readlane_b32 s9, v66, 15
	v_readlane_b32 s10, v66, 31
	v_readlane_b32 s11, v66, 47
	v_readlane_b32 vcc_lo, v66, 63
	s_nop 1
	v_mov_b32_e32 v66, s9
	v_add_f32_e32 v66, s10, v66
	v_add_f32_e32 v66, s11, v66
	v_add_f32_e32 v66, vcc_lo, v66
	v_mul_f32_e32 v116, 0x3a800000, v66
	v_mov_b32_e32 v117, v116
	v_pk_add_f32 v[18:19], v[18:19], v[116:117] neg_lo:[0,1] neg_hi:[0,1]
	v_pk_add_f32 v[20:21], v[20:21], v[116:117] neg_lo:[0,1] neg_hi:[0,1]
	v_pk_add_f32 v[22:23], v[22:23], v[116:117] neg_lo:[0,1] neg_hi:[0,1]
	v_pk_add_f32 v[24:25], v[24:25], v[116:117] neg_lo:[0,1] neg_hi:[0,1]
	v_pk_add_f32 v[26:27], v[26:27], v[116:117] neg_lo:[0,1] neg_hi:[0,1]
	v_pk_add_f32 v[28:29], v[28:29], v[116:117] neg_lo:[0,1] neg_hi:[0,1]
	v_pk_add_f32 v[30:31], v[30:31], v[116:117] neg_lo:[0,1] neg_hi:[0,1]
	v_pk_add_f32 v[32:33], v[32:33], v[116:117] neg_lo:[0,1] neg_hi:[0,1]
	v_pk_mul_f32 v[66:67], v[18:19], v[18:19]
	v_pk_mul_f32 v[68:69], v[20:21], v[20:21]
	v_pk_fma_f32 v[66:67], v[22:23], v[22:23], v[66:67]
	v_pk_fma_f32 v[68:69], v[24:25], v[24:25], v[68:69]
	v_pk_fma_f32 v[66:67], v[26:27], v[26:27], v[66:67]
	v_pk_fma_f32 v[68:69], v[28:29], v[28:29], v[68:69]
	v_pk_fma_f32 v[66:67], v[30:31], v[30:31], v[66:67]
	v_pk_fma_f32 v[68:69], v[32:33], v[32:33], v[68:69]
	v_pk_add_f32 v[66:67], v[66:67], v[68:69]
	v_add_f32_e32 v66, v66, v67
	s_nop 1
	v_add_f32_dpp v66, v66, v66 row_shr:1 row_mask:0xf bank_mask:0xf bound_ctrl:1
	s_nop 1
	v_add_f32_dpp v66, v66, v66 row_shr:2 row_mask:0xf bank_mask:0xf bound_ctrl:1
	s_nop 1
	v_add_f32_dpp v66, v66, v66 row_shr:4 row_mask:0xf bank_mask:0xf bound_ctrl:1
	s_nop 1
	v_add_f32_dpp v66, v66, v66 row_shr:8 row_mask:0xf bank_mask:0xf bound_ctrl:1
	s_nop 0
	v_readlane_b32 s9, v66, 15
	v_readlane_b32 s10, v66, 31
	v_readlane_b32 s11, v66, 47
	v_readlane_b32 vcc_lo, v66, 63
	s_nop 1
	v_mov_b32_e32 v66, s9
	v_add_f32_e32 v66, s10, v66
	v_add_f32_e32 v66, s11, v66
	v_add_f32_e32 v66, vcc_lo, v66
	v_mul_f32_e32 v66, 0x3a800000, v66
	v_add_f32_e32 v66, 0x3727c5ac, v66
	v_rsq_f32_e32 v118, v66
	s_nop 0
	v_mov_b32_e32 v119, v118
	v_pk_mul_f32 v[18:19], v[18:19], v[118:119]
	v_pk_mul_f32 v[20:21], v[20:21], v[118:119]
	v_pk_mul_f32 v[22:23], v[22:23], v[118:119]
	v_pk_mul_f32 v[24:25], v[24:25], v[118:119]
	v_pk_mul_f32 v[26:27], v[26:27], v[118:119]
	v_pk_mul_f32 v[28:29], v[28:29], v[118:119]
	v_pk_mul_f32 v[30:31], v[30:31], v[118:119]
	v_pk_mul_f32 v[32:33], v[32:33], v[118:119]
	v_pk_fma_f32 v[76:77], v[18:19], v[34:35], v[50:51]
	v_pk_fma_f32 v[78:79], v[20:21], v[36:37], v[52:53]
	v_pk_fma_f32 v[80:81], v[22:23], v[38:39], v[54:55]
	v_pk_fma_f32 v[82:83], v[24:25], v[40:41], v[56:57]
	v_pk_fma_f32 v[84:85], v[26:27], v[42:43], v[58:59]
	v_pk_fma_f32 v[86:87], v[28:29], v[44:45], v[60:61]
	v_pk_fma_f32 v[88:89], v[30:31], v[46:47], v[62:63]
	v_pk_fma_f32 v[90:91], v[32:33], v[48:49], v[64:65]
	v_cvt_pk_bf16_f32 v92, v76, v77
	v_cvt_pk_bf16_f32 v93, v78, v79
	v_cvt_pk_bf16_f32 v94, v80, v81
	v_cvt_pk_bf16_f32 v95, v82, v83
	v_cvt_pk_bf16_f32 v96, v84, v85
	v_cvt_pk_bf16_f32 v97, v86, v87
	v_cvt_pk_bf16_f32 v98, v88, v89
	v_cvt_pk_bf16_f32 v99, v90, v91
	global_store_dwordx2 v115, v[92:93], s[2:3] offset:0
	global_store_dwordx2 v115, v[94:95], s[2:3] offset:512
	global_store_dwordx2 v115, v[96:97], s[2:3] offset:1024
	global_store_dwordx2 v115, v[98:99], s[2:3] offset:1536
	s_add_u32 s2, s2, 0x400000
	s_addc_u32 s3, s3, 0
	s_add_u32 s0, s0, 0x800000
	s_addc_u32 s1, s1, 0
	global_load_dwordx4 v[18:21], v114, s[0:1] offset:0
	global_load_dwordx4 v[22:25], v114, s[0:1] offset:1024
	global_load_dwordx4 v[26:29], v114, s[0:1] offset:2048
	global_load_dwordx4 v[30:33], v114, s[0:1] offset:3072
	s_waitcnt vmcnt(8)
; __device__ __forceinline__ void phase_ln(float* R, const float* __restrict__ g, const float* __restrict__ b, bf16_t* xbf, float samp_scale, const float* __restrict__ part, int nsplit, bool f32_all) {
;     ...
;   for (int r = gw; r < MT; r += nw) {
;     float* row = R + (size_t)r * 1024;
;     f32x4 v[4];
; #pragma unroll
;     for (int i = 0; i < 4; ++i) v[i] = *(const f32x4*)(row + i * 256 + lane * 4);
;     if (r >= MP) {
;       for (int sp = 0; sp < nsplit; ++sp) {
;         const float* prow = part + ((size_t)sp * MS + (r - MP)) * 1024;
; #pragma unroll
;         for (int i = 0; i < 4; ++i) v[i] = v[i] + *(const f32x4*)(prow + i * 256 + lane * 4);
;       }
;     }
;     float s = 0.f;
; #pragma unroll
;     for (int i = 0; i < 4; ++i) s += v[i][0] + v[i][1] + v[i][2] + v[i][3];
; #pragma unroll
;     for (int o = 32; o >= 1; o >>= 1) s += __shfl_xor(s, o);
;     const float mean = s * (1.f / 1024.f);
;     float ss = 0.f;
; #pragma unroll
;     for (int i = 0; i < 4; ++i) { v[i] = v[i] - mean; ss += v[i][0] * v[i][0] + v[i][1] * v[i][1] + v[i][2] * v[i][2] + v[i][3] * v[i][3]; }
; #pragma unroll
;     for (int o = 32; o >= 1; o >>= 1) ss += __shfl_xor(ss, o);
;     const float rstd = rsqrtf(ss * (1.f / 1024.f) + LN_EPS);
; #pragma unroll
;     for (int i = 0; i < 4; ++i) {
;       const f32x4 y = v[i] * rstd * gv[i] + bv[i];
;       if (r >= MP) *(f32x4*)(row + i * 256 + lane * 4) = y * samp_scale;
;       else if (f32_all) *(f32x4*)(row + i * 256 + lane * 4) = y;
;       if (xbf) {
;         u32x2 wv;
;         wv[0] = cvt_pk_bf16(y[0], y[1]); wv[1] = cvt_pk_bf16(y[2], y[3]);
;         *(u32x2*)(xbf + (size_t)r * 1024 + i * 256 + lane * 4) = wv;
;       }
;     }
	v_pk_add_f32 v[66:67], v[0:1], v[2:3]
	v_pk_add_f32 v[68:69], v[4:5], v[6:7]
	v_pk_add_f32 v[70:71], v[8:9], v[10:11]
	v_pk_add_f32 v[72:73], v[12:13], v[14:15]
	v_pk_add_f32 v[66:67], v[66:67], v[68:69]
	v_pk_add_f32 v[70:71], v[70:71], v[72:73]
	v_pk_add_f32 v[66:67], v[66:67], v[70:71]
	v_add_f32_e32 v66, v66, v67
	s_nop 1
	v_add_f32_dpp v66, v66, v66 row_shr:1 row_mask:0xf bank_mask:0xf bound_ctrl:1
	s_nop 1
	v_add_f32_dpp v66, v66, v66 row_shr:2 row_mask:0xf bank_mask:0xf bound_ctrl:1
	s_nop 1
	v_add_f32_dpp v66, v66, v66 row_shr:4 row_mask:0xf bank_mask:0xf bound_ctrl:1
	s_nop 1
	v_add_f32_dpp v66, v66, v66 row_shr:8 row_mask:0xf bank_mask:0xf bound_ctrl:1
	s_nop 0
	v_readlane_b32 s9, v66, 15
	v_readlane_b32 s10, v66, 31
	v_readlane_b32 s11, v66, 47
	v_readlane_b32 vcc_lo, v66, 63
	s_nop 1
	v_mov_b32_e32 v66, s9
	v_add_f32_e32 v66, s10, v66
	v_add_f32_e32 v66, s11, v66
	v_add_f32_e32 v66, vcc_lo, v66
	v_mul_f32_e32 v116, 0x3a800000, v66
	v_mov_b32_e32 v117, v116
	v_pk_add_f32 v[0:1], v[0:1], v[116:117] neg_lo:[0,1] neg_hi:[0,1]
	v_pk_add_f32 v[2:3], v[2:3], v[116:117] neg_lo:[0,1] neg_hi:[0,1]
	v_pk_add_f32 v[4:5], v[4:5], v[116:117] neg_lo:[0,1] neg_hi:[0,1]
	v_pk_add_f32 v[6:7], v[6:7], v[116:117] neg_lo:[0,1] neg_hi:[0,1]
	v_pk_add_f32 v[8:9], v[8:9], v[116:117] neg_lo:[0,1] neg_hi:[0,1]
	v_pk_add_f32 v[10:11], v[10:11], v[116:117] neg_lo:[0,1] neg_hi:[0,1]
	v_pk_add_f32 v[12:13], v[12:13], v[116:117] neg_lo:[0,1] neg_hi:[0,1]
	v_pk_add_f32 v[14:15], v[14:15], v[116:117] neg_lo:[0,1] neg_hi:[0,1]
	v_pk_mul_f32 v[66:67], v[0:1], v[0:1]
	v_pk_mul_f32 v[68:69], v[2:3], v[2:3]
	v_pk_fma_f32 v[66:67], v[4:5], v[4:5], v[66:67]
	v_pk_fma_f32 v[68:69], v[6:7], v[6:7], v[68:69]
	v_pk_fma_f32 v[66:67], v[8:9], v[8:9], v[66:67]
	v_pk_fma_f32 v[68:69], v[10:11], v[10:11], v[68:69]
	v_pk_fma_f32 v[66:67], v[12:13], v[12:13], v[66:67]
	v_pk_fma_f32 v[68:69], v[14:15], v[14:15], v[68:69]
	v_pk_add_f32 v[66:67], v[66:67], v[68:69]
	v_add_f32_e32 v66, v66, v67
	s_nop 1
	v_add_f32_dpp v66, v66, v66 row_shr:1 row_mask:0xf bank_mask:0xf bound_ctrl:1
	s_nop 1
	v_add_f32_dpp v66, v66, v66 row_shr:2 row_mask:0xf bank_mask:0xf bound_ctrl:1
	s_nop 1
	v_add_f32_dpp v66, v66, v66 row_shr:4 row_mask:0xf bank_mask:0xf bound_ctrl:1
	s_nop 1
	v_add_f32_dpp v66, v66, v66 row_shr:8 row_mask:0xf bank_mask:0xf bound_ctrl:1
	s_nop 0
	v_readlane_b32 s9, v66, 15
	v_readlane_b32 s10, v66, 31
	v_readlane_b32 s11, v66, 47
	v_readlane_b32 vcc_lo, v66, 63
	s_nop 1
	v_mov_b32_e32 v66, s9
	v_add_f32_e32 v66, s10, v66
	v_add_f32_e32 v66, s11, v66
	v_add_f32_e32 v66, vcc_lo, v66
	v_mul_f32_e32 v66, 0x3a800000, v66
	v_add_f32_e32 v66, 0x3727c5ac, v66
	v_rsq_f32_e32 v118, v66
	s_nop 0
	v_mov_b32_e32 v119, v118
	v_pk_mul_f32 v[0:1], v[0:1], v[118:119]
	v_pk_mul_f32 v[2:3], v[2:3], v[118:119]
	v_pk_mul_f32 v[4:5], v[4:5], v[118:119]
	v_pk_mul_f32 v[6:7], v[6:7], v[118:119]
	v_pk_mul_f32 v[8:9], v[8:9], v[118:119]
	v_pk_mul_f32 v[10:11], v[10:11], v[118:119]
	v_pk_mul_f32 v[12:13], v[12:13], v[118:119]
	v_pk_mul_f32 v[14:15], v[14:15], v[118:119]
	v_pk_fma_f32 v[76:77], v[0:1], v[34:35], v[50:51]
	v_pk_fma_f32 v[78:79], v[2:3], v[36:37], v[52:53]
	v_pk_fma_f32 v[80:81], v[4:5], v[38:39], v[54:55]
	v_pk_fma_f32 v[82:83], v[6:7], v[40:41], v[56:57]
	v_pk_fma_f32 v[84:85], v[8:9], v[42:43], v[58:59]
	v_pk_fma_f32 v[86:87], v[10:11], v[44:45], v[60:61]
	v_pk_fma_f32 v[88:89], v[12:13], v[46:47], v[62:63]
	v_pk_fma_f32 v[90:91], v[14:15], v[48:49], v[64:65]
	v_cvt_pk_bf16_f32 v92, v76, v77
	v_cvt_pk_bf16_f32 v93, v78, v79
	v_cvt_pk_bf16_f32 v94, v80, v81
	v_cvt_pk_bf16_f32 v95, v82, v83
	v_cvt_pk_bf16_f32 v96, v84, v85
	v_cvt_pk_bf16_f32 v97, v86, v87
	v_cvt_pk_bf16_f32 v98, v88, v89
	v_cvt_pk_bf16_f32 v99, v90, v91
	global_store_dwordx2 v115, v[92:93], s[2:3] offset:0
	global_store_dwordx2 v115, v[94:95], s[2:3] offset:512
	global_store_dwordx2 v115, v[96:97], s[2:3] offset:1024
	global_store_dwordx2 v115, v[98:99], s[2:3] offset:1536
	s_add_u32 s2, s2, 0x400000
	s_addc_u32 s3, s3, 0
	s_add_u32 s0, s0, 0x800000
	s_addc_u32 s1, s1, 0
	global_load_dwordx4 v[0:3], v114, s[0:1] offset:0
	global_load_dwordx4 v[4:7], v114, s[0:1] offset:1024
	global_load_dwordx4 v[8:11], v114, s[0:1] offset:2048
	global_load_dwordx4 v[12:15], v114, s[0:1] offset:3072
	s_waitcnt vmcnt(8)
; __device__ __forceinline__ void phase_ln(float* R, const float* __restrict__ g, const float* __restrict__ b, bf16_t* xbf, float samp_scale, const float* __restrict__ part, int nsplit, bool f32_all) {
;     ...
;   for (int r = gw; r < MT; r += nw) {
;     float* row = R + (size_t)r * 1024;
;     f32x4 v[4];
; #pragma unroll
;     for (int i = 0; i < 4; ++i) v[i] = *(const f32x4*)(row + i * 256 + lane * 4);
;     if (r >= MP) {
;       for (int sp = 0; sp < nsplit; ++sp) {
;         const float* prow = part + ((size_t)sp * MS + (r - MP)) * 1024;
; #pragma unroll
;         for (int i = 0; i < 4; ++i) v[i] = v[i] + *(const f32x4*)(prow + i * 256 + lane * 4);
;       }
;     }
;     float s = 0.f;
; #pragma unroll
;     for (int i = 0; i < 4; ++i) s += v[i][0] + v[i][1] + v[i][2] + v[i][3];
; #pragma unroll
;     for (int o = 32; o >= 1; o >>= 1) s += __shfl_xor(s, o);
;     const float mean = s * (1.f / 1024.f);
;     float ss = 0.f;
; #pragma unroll
;     for (int i = 0; i < 4; ++i) { v[i] = v[i] - mean; ss += v[i][0] * v[i][0] + v[i][1] * v[i][1] + v[i][2] * v[i][2] + v[i][3] * v[i][3]; }
; #pragma unroll
;     for (int o = 32; o >= 1; o >>= 1) ss += __shfl_xor(ss, o);
;     const float rstd = rsqrtf(ss * (1.f / 1024.f) + LN_EPS);
; #pragma unroll
;     for (int i = 0; i < 4; ++i) {
;       const f32x4 y = v[i] * rstd * gv[i] + bv[i];
;       if (r >= MP) *(f32x4*)(row + i * 256 + lane * 4) = y * samp_scale;
;       else if (f32_all) *(f32x4*)(row + i * 256 + lane * 4) = y;
;       if (xbf) {
;         u32x2 wv;
;         wv[0] = cvt_pk_bf16(y[0], y[1]); wv[1] = cvt_pk_bf16(y[2], y[3]);
;         *(u32x2*)(xbf + (size_t)r * 1024 + i * 256 + lane * 4) = wv;
;       }
;     }
	v_pk_add_f32 v[66:67], v[18:19], v[20:21]
	v_pk_add_f32 v[68:69], v[22:23], v[24:25]
	v_pk_add_f32 v[70:71], v[26:27], v[28:29]
	v_pk_add_f32 v[72:73], v[30:31], v[32:33]
	v_pk_add_f32 v[66:67], v[66:67], v[68:69]
	v_pk_add_f32 v[70:71], v[70:71], v[72:73]
	v_pk_add_f32 v[66:67], v[66:67], v[70:71]
	v_add_f32_e32 v66, v66, v67
	s_nop 1
	v_add_f32_dpp v66, v66, v66 row_shr:1 row_mask:0xf bank_mask:0xf bound_ctrl:1
	s_nop 1
	v_add_f32_dpp v66, v66, v66 row_shr:2 row_mask:0xf bank_mask:0xf bound_ctrl:1
	s_nop 1
	v_add_f32_dpp v66, v66, v66 row_shr:4 row_mask:0xf bank_mask:0xf bound_ctrl:1
	s_nop 1
	v_add_f32_dpp v66, v66, v66 row_shr:8 row_mask:0xf bank_mask:0xf bound_ctrl:1
	s_nop 0
	v_readlane_b32 s9, v66, 15
	v_readlane_b32 s10, v66, 31
	v_readlane_b32 s11, v66, 47
	v_readlane_b32 vcc_lo, v66, 63
	s_nop 1
	v_mov_b32_e32 v66, s9
	v_add_f32_e32 v66, s10, v66
	v_add_f32_e32 v66, s11, v66
	v_add_f32_e32 v66, vcc_lo, v66
	v_mul_f32_e32 v116, 0x3a800000, v66
	v_mov_b32_e32 v117, v116
	v_pk_add_f32 v[18:19], v[18:19], v[116:117] neg_lo:[0,1] neg_hi:[0,1]
	v_pk_add_f32 v[20:21], v[20:21], v[116:117] neg_lo:[0,1] neg_hi:[0,1]
	v_pk_add_f32 v[22:23], v[22:23], v[116:117] neg_lo:[0,1] neg_hi:[0,1]
	v_pk_add_f32 v[24:25], v[24:25], v[116:117] neg_lo:[0,1] neg_hi:[0,1]
	v_pk_add_f32 v[26:27], v[26:27], v[116:117] neg_lo:[0,1] neg_hi:[0,1]
	v_pk_add_f32 v[28:29], v[28:29], v[116:117] neg_lo:[0,1] neg_hi:[0,1]
	v_pk_add_f32 v[30:31], v[30:31], v[116:117] neg_lo:[0,1] neg_hi:[0,1]
	v_pk_add_f32 v[32:33], v[32:33], v[116:117] neg_lo:[0,1] neg_hi:[0,1]
	v_pk_mul_f32 v[66:67], v[18:19], v[18:19]
	v_pk_mul_f32 v[68:69], v[20:21], v[20:21]
	v_pk_fma_f32 v[66:67], v[22:23], v[22:23], v[66:67]
	v_pk_fma_f32 v[68:69], v[24:25], v[24:25], v[68:69]
	v_pk_fma_f32 v[66:67], v[26:27], v[26:27], v[66:67]
	v_pk_fma_f32 v[68:69], v[28:29], v[28:29], v[68:69]
	v_pk_fma_f32 v[66:67], v[30:31], v[30:31], v[66:67]
	v_pk_fma_f32 v[68:69], v[32:33], v[32:33], v[68:69]
	v_pk_add_f32 v[66:67], v[66:67], v[68:69]
	v_add_f32_e32 v66, v66, v67
	s_nop 1
	v_add_f32_dpp v66, v66, v66 row_shr:1 row_mask:0xf bank_mask:0xf bound_ctrl:1
	s_nop 1
	v_add_f32_dpp v66, v66, v66 row_shr:2 row_mask:0xf bank_mask:0xf bound_ctrl:1
	s_nop 1
	v_add_f32_dpp v66, v66, v66 row_shr:4 row_mask:0xf bank_mask:0xf bound_ctrl:1
	s_nop 1
	v_add_f32_dpp v66, v66, v66 row_shr:8 row_mask:0xf bank_mask:0xf bound_ctrl:1
	s_nop 0
	v_readlane_b32 s9, v66, 15
	v_readlane_b32 s10, v66, 31
	v_readlane_b32 s11, v66, 47
	v_readlane_b32 vcc_lo, v66, 63
	s_nop 1
	v_mov_b32_e32 v66, s9
	v_add_f32_e32 v66, s10, v66
	v_add_f32_e32 v66, s11, v66
	v_add_f32_e32 v66, vcc_lo, v66
	v_mul_f32_e32 v66, 0x3a800000, v66
	v_add_f32_e32 v66, 0x3727c5ac, v66
	v_rsq_f32_e32 v118, v66
	s_nop 0
	v_mov_b32_e32 v119, v118
	v_pk_mul_f32 v[18:19], v[18:19], v[118:119]
	v_pk_mul_f32 v[20:21], v[20:21], v[118:119]
	v_pk_mul_f32 v[22:23], v[22:23], v[118:119]
	v_pk_mul_f32 v[24:25], v[24:25], v[118:119]
	v_pk_mul_f32 v[26:27], v[26:27], v[118:119]
	v_pk_mul_f32 v[28:29], v[28:29], v[118:119]
	v_pk_mul_f32 v[30:31], v[30:31], v[118:119]
	v_pk_mul_f32 v[32:33], v[32:33], v[118:119]
	v_pk_fma_f32 v[76:77], v[18:19], v[34:35], v[50:51]
	v_pk_fma_f32 v[78:79], v[20:21], v[36:37], v[52:53]
	v_pk_fma_f32 v[80:81], v[22:23], v[38:39], v[54:55]
	v_pk_fma_f32 v[82:83], v[24:25], v[40:41], v[56:57]
	v_pk_fma_f32 v[84:85], v[26:27], v[42:43], v[58:59]
	v_pk_fma_f32 v[86:87], v[28:29], v[44:45], v[60:61]
	v_pk_fma_f32 v[88:89], v[30:31], v[46:47], v[62:63]
	v_pk_fma_f32 v[90:91], v[32:33], v[48:49], v[64:65]
	v_cvt_pk_bf16_f32 v92, v76, v77
	v_cvt_pk_bf16_f32 v93, v78, v79
	v_cvt_pk_bf16_f32 v94, v80, v81
	v_cvt_pk_bf16_f32 v95, v82, v83
	v_cvt_pk_bf16_f32 v96, v84, v85
	v_cvt_pk_bf16_f32 v97, v86, v87
	v_cvt_pk_bf16_f32 v98, v88, v89
	v_cvt_pk_bf16_f32 v99, v90, v91
	global_store_dwordx2 v115, v[92:93], s[2:3] offset:0
	global_store_dwordx2 v115, v[94:95], s[2:3] offset:512
	global_store_dwordx2 v115, v[96:97], s[2:3] offset:1024
	global_store_dwordx2 v115, v[98:99], s[2:3] offset:1536
	s_add_u32 s2, s2, 0x400000
	s_addc_u32 s3, s3, 0
	s_add_u32 s0, s0, 0x800000
	s_addc_u32 s1, s1, 0
	global_load_dwordx4 v[18:21], v114, s[0:1] offset:0
	global_load_dwordx4 v[22:25], v114, s[0:1] offset:1024
	global_load_dwordx4 v[26:29], v114, s[0:1] offset:2048
	global_load_dwordx4 v[30:33], v114, s[0:1] offset:3072
	s_waitcnt vmcnt(8)
; __device__ __forceinline__ void phase_ln(float* R, const float* __restrict__ g, const float* __restrict__ b, bf16_t* xbf, float samp_scale, const float* __restrict__ part, int nsplit, bool f32_all) {
;     ...
;   for (int r = gw; r < MT; r += nw) {
;     float* row = R + (size_t)r * 1024;
;     f32x4 v[4];
; #pragma unroll
;     for (int i = 0; i < 4; ++i) v[i] = *(const f32x4*)(row + i * 256 + lane * 4);
;     if (r >= MP) {
;       for (int sp = 0; sp < nsplit; ++sp) {
;         const float* prow = part + ((size_t)sp * MS + (r - MP)) * 1024;
; #pragma unroll
;         for (int i = 0; i < 4; ++i) v[i] = v[i] + *(const f32x4*)(prow + i * 256 + lane * 4);
;       }
;     }
;     float s = 0.f;
; #pragma unroll
;     for (int i = 0; i < 4; ++i) s += v[i][0] + v[i][1] + v[i][2] + v[i][3];
; #pragma unroll
;     for (int o = 32; o >= 1; o >>= 1) s += __shfl_xor(s, o);
;     const float mean = s * (1.f / 1024.f);
;     float ss = 0.f;
; #pragma unroll
;     for (int i = 0; i < 4; ++i) { v[i] = v[i] - mean; ss += v[i][0] * v[i][0] + v[i][1] * v[i][1] + v[i][2] * v[i][2] + v[i][3] * v[i][3]; }
; #pragma unroll
;     for (int o = 32; o >= 1; o >>= 1) ss += __shfl_xor(ss, o);
;     const float rstd = rsqrtf(ss * (1.f / 1024.f) + LN_EPS);
; #pragma unroll
;     for (int i = 0; i < 4; ++i) {
;       const f32x4 y = v[i] * rstd * gv[i] + bv[i];
;       if (r >= MP) *(f32x4*)(row + i * 256 + lane * 4) = y * samp_scale;
;       else if (f32_all) *(f32x4*)(row + i * 256 + lane * 4) = y;
;       if (xbf) {
;         u32x2 wv;
;         wv[0] = cvt_pk_bf16(y[0], y[1]); wv[1] = cvt_pk_bf16(y[2], y[3]);
;         *(u32x2*)(xbf + (size_t)r * 1024 + i * 256 + lane * 4) = wv;
;       }
;     }
	v_pk_add_f32 v[66:67], v[0:1], v[2:3]
	v_pk_add_f32 v[68:69], v[4:5], v[6:7]
	v_pk_add_f32 v[70:71], v[8:9], v[10:11]
	v_pk_add_f32 v[72:73], v[12:13], v[14:15]
	v_pk_add_f32 v[66:67], v[66:67], v[68:69]
	v_pk_add_f32 v[70:71], v[70:71], v[72:73]
	v_pk_add_f32 v[66:67], v[66:67], v[70:71]
	v_add_f32_e32 v66, v66, v67
	s_nop 1
	v_add_f32_dpp v66, v66, v66 row_shr:1 row_mask:0xf bank_mask:0xf bound_ctrl:1
	s_nop 1
	v_add_f32_dpp v66, v66, v66 row_shr:2 row_mask:0xf bank_mask:0xf bound_ctrl:1
	s_nop 1
	v_add_f32_dpp v66, v66, v66 row_shr:4 row_mask:0xf bank_mask:0xf bound_ctrl:1
	s_nop 1
	v_add_f32_dpp v66, v66, v66 row_shr:8 row_mask:0xf bank_mask:0xf bound_ctrl:1
	s_nop 0
	v_readlane_b32 s9, v66, 15
	v_readlane_b32 s10, v66, 31
	v_readlane_b32 s11, v66, 47
	v_readlane_b32 vcc_lo, v66, 63
	s_nop 1
	v_mov_b32_e32 v66, s9
	v_add_f32_e32 v66, s10, v66
	v_add_f32_e32 v66, s11, v66
	v_add_f32_e32 v66, vcc_lo, v66
	v_mul_f32_e32 v116, 0x3a800000, v66
	v_mov_b32_e32 v117, v116
	v_pk_add_f32 v[0:1], v[0:1], v[116:117] neg_lo:[0,1] neg_hi:[0,1]
	v_pk_add_f32 v[2:3], v[2:3], v[116:117] neg_lo:[0,1] neg_hi:[0,1]
	v_pk_add_f32 v[4:5], v[4:5], v[116:117] neg_lo:[0,1] neg_hi:[0,1]
	v_pk_add_f32 v[6:7], v[6:7], v[116:117] neg_lo:[0,1] neg_hi:[0,1]
	v_pk_add_f32 v[8:9], v[8:9], v[116:117] neg_lo:[0,1] neg_hi:[0,1]
	v_pk_add_f32 v[10:11], v[10:11], v[116:117] neg_lo:[0,1] neg_hi:[0,1]
	v_pk_add_f32 v[12:13], v[12:13], v[116:117] neg_lo:[0,1] neg_hi:[0,1]
	v_pk_add_f32 v[14:15], v[14:15], v[116:117] neg_lo:[0,1] neg_hi:[0,1]
	v_pk_mul_f32 v[66:67], v[0:1], v[0:1]
	v_pk_mul_f32 v[68:69], v[2:3], v[2:3]
	v_pk_fma_f32 v[66:67], v[4:5], v[4:5], v[66:67]
	v_pk_fma_f32 v[68:69], v[6:7], v[6:7], v[68:69]
	v_pk_fma_f32 v[66:67], v[8:9], v[8:9], v[66:67]
	v_pk_fma_f32 v[68:69], v[10:11], v[10:11], v[68:69]
	v_pk_fma_f32 v[66:67], v[12:13], v[12:13], v[66:67]
	v_pk_fma_f32 v[68:69], v[14:15], v[14:15], v[68:69]
	v_pk_add_f32 v[66:67], v[66:67], v[68:69]
	v_add_f32_e32 v66, v66, v67
	s_nop 1
	v_add_f32_dpp v66, v66, v66 row_shr:1 row_mask:0xf bank_mask:0xf bound_ctrl:1
	s_nop 1
	v_add_f32_dpp v66, v66, v66 row_shr:2 row_mask:0xf bank_mask:0xf bound_ctrl:1
	s_nop 1
	v_add_f32_dpp v66, v66, v66 row_shr:4 row_mask:0xf bank_mask:0xf bound_ctrl:1
	s_nop 1
	v_add_f32_dpp v66, v66, v66 row_shr:8 row_mask:0xf bank_mask:0xf bound_ctrl:1
	s_nop 0
	v_readlane_b32 s9, v66, 15
	v_readlane_b32 s10, v66, 31
	v_readlane_b32 s11, v66, 47
	v_readlane_b32 vcc_lo, v66, 63
	s_nop 1
	v_mov_b32_e32 v66, s9
	v_add_f32_e32 v66, s10, v66
	v_add_f32_e32 v66, s11, v66
	v_add_f32_e32 v66, vcc_lo, v66
	v_mul_f32_e32 v66, 0x3a800000, v66
	v_add_f32_e32 v66, 0x3727c5ac, v66
	v_rsq_f32_e32 v118, v66
	s_nop 0
	v_mov_b32_e32 v119, v118
	v_pk_mul_f32 v[0:1], v[0:1], v[118:119]
	v_pk_mul_f32 v[2:3], v[2:3], v[118:119]
	v_pk_mul_f32 v[4:5], v[4:5], v[118:119]
	v_pk_mul_f32 v[6:7], v[6:7], v[118:119]
	v_pk_mul_f32 v[8:9], v[8:9], v[118:119]
	v_pk_mul_f32 v[10:11], v[10:11], v[118:119]
	v_pk_mul_f32 v[12:13], v[12:13], v[118:119]
	v_pk_mul_f32 v[14:15], v[14:15], v[118:119]
	v_pk_fma_f32 v[76:77], v[0:1], v[34:35], v[50:51]
	v_pk_fma_f32 v[78:79], v[2:3], v[36:37], v[52:53]
	v_pk_fma_f32 v[80:81], v[4:5], v[38:39], v[54:55]
	v_pk_fma_f32 v[82:83], v[6:7], v[40:41], v[56:57]
	v_pk_fma_f32 v[84:85], v[8:9], v[42:43], v[58:59]
	v_pk_fma_f32 v[86:87], v[10:11], v[44:45], v[60:61]
	v_pk_fma_f32 v[88:89], v[12:13], v[46:47], v[62:63]
	v_pk_fma_f32 v[90:91], v[14:15], v[48:49], v[64:65]
	v_cvt_pk_bf16_f32 v92, v76, v77
	v_cvt_pk_bf16_f32 v93, v78, v79
	v_cvt_pk_bf16_f32 v94, v80, v81
	v_cvt_pk_bf16_f32 v95, v82, v83
	v_cvt_pk_bf16_f32 v96, v84, v85
	v_cvt_pk_bf16_f32 v97, v86, v87
	v_cvt_pk_bf16_f32 v98, v88, v89
	v_cvt_pk_bf16_f32 v99, v90, v91
	global_store_dwordx2 v115, v[92:93], s[2:3] offset:0
	global_store_dwordx2 v115, v[94:95], s[2:3] offset:512
	global_store_dwordx2 v115, v[96:97], s[2:3] offset:1024
	global_store_dwordx2 v115, v[98:99], s[2:3] offset:1536
	s_add_u32 s2, s2, 0x400000
	s_addc_u32 s3, s3, 0
	s_add_u32 s0, s0, 0x800000
	s_addc_u32 s1, s1, 0
	global_load_dwordx4 v[0:3], v114, s[0:1] offset:0
	global_load_dwordx4 v[4:7], v114, s[0:1] offset:1024
	global_load_dwordx4 v[8:11], v114, s[0:1] offset:2048
	global_load_dwordx4 v[12:15], v114, s[0:1] offset:3072
	s_waitcnt vmcnt(8)
; __device__ __forceinline__ void phase_ln(float* R, const float* __restrict__ g, const float* __restrict__ b, bf16_t* xbf, float samp_scale, const float* __restrict__ part, int nsplit, bool f32_all) {
;     ...
;   for (int r = gw; r < MT; r += nw) {
;     float* row = R + (size_t)r * 1024;
;     f32x4 v[4];
; #pragma unroll
;     for (int i = 0; i < 4; ++i) v[i] = *(const f32x4*)(row + i * 256 + lane * 4);
;     if (r >= MP) {
;       for (int sp = 0; sp < nsplit; ++sp) {
;         const float* prow = part + ((size_t)sp * MS + (r - MP)) * 1024;
; #pragma unroll
;         for (int i = 0; i < 4; ++i) v[i] = v[i] + *(const f32x4*)(prow + i * 256 + lane * 4);
;       }
;     }
;     float s = 0.f;
; #pragma unroll
;     for (int i = 0; i < 4; ++i) s += v[i][0] + v[i][1] + v[i][2] + v[i][3];
; #pragma unroll
;     for (int o = 32; o >= 1; o >>= 1) s += __shfl_xor(s, o);
;     const float mean = s * (1.f / 1024.f);
;     float ss = 0.f;
; #pragma unroll
;     for (int i = 0; i < 4; ++i) { v[i] = v[i] - mean; ss += v[i][0] * v[i][0] + v[i][1] * v[i][1] + v[i][2] * v[i][2] + v[i][3] * v[i][3]; }
; #pragma unroll
;     for (int o = 32; o >= 1; o >>= 1) ss += __shfl_xor(ss, o);
;     const float rstd = rsqrtf(ss * (1.f / 1024.f) + LN_EPS);
; #pragma unroll
;     for (int i = 0; i < 4; ++i) {
;       const f32x4 y = v[i] * rstd * gv[i] + bv[i];
;       if (r >= MP) *(f32x4*)(row + i * 256 + lane * 4) = y * samp_scale;
;       else if (f32_all) *(f32x4*)(row + i * 256 + lane * 4) = y;
;       if (xbf) {
;         u32x2 wv;
;         wv[0] = cvt_pk_bf16(y[0], y[1]); wv[1] = cvt_pk_bf16(y[2], y[3]);
;         *(u32x2*)(xbf + (size_t)r * 1024 + i * 256 + lane * 4) = wv;
;       }
;     }
	v_pk_add_f32 v[66:67], v[18:19], v[20:21]
	v_pk_add_f32 v[68:69], v[22:23], v[24:25]
	v_pk_add_f32 v[70:71], v[26:27], v[28:29]
	v_pk_add_f32 v[72:73], v[30:31], v[32:33]
	v_pk_add_f32 v[66:67], v[66:67], v[68:69]
	v_pk_add_f32 v[70:71], v[70:71], v[72:73]
	v_pk_add_f32 v[66:67], v[66:67], v[70:71]
	v_add_f32_e32 v66, v66, v67
	s_nop 1
	v_add_f32_dpp v66, v66, v66 row_shr:1 row_mask:0xf bank_mask:0xf bound_ctrl:1
	s_nop 1
	v_add_f32_dpp v66, v66, v66 row_shr:2 row_mask:0xf bank_mask:0xf bound_ctrl:1
	s_nop 1
	v_add_f32_dpp v66, v66, v66 row_shr:4 row_mask:0xf bank_mask:0xf bound_ctrl:1
	s_nop 1
	v_add_f32_dpp v66, v66, v66 row_shr:8 row_mask:0xf bank_mask:0xf bound_ctrl:1
	s_nop 0
	v_readlane_b32 s9, v66, 15
	v_readlane_b32 s10, v66, 31
	v_readlane_b32 s11, v66, 47
	v_readlane_b32 vcc_lo, v66, 63
	s_nop 1
	v_mov_b32_e32 v66, s9
	v_add_f32_e32 v66, s10, v66
	v_add_f32_e32 v66, s11, v66
	v_add_f32_e32 v66, vcc_lo, v66
	v_mul_f32_e32 v116, 0x3a800000, v66
	v_mov_b32_e32 v117, v116
	v_pk_add_f32 v[18:19], v[18:19], v[116:117] neg_lo:[0,1] neg_hi:[0,1]
	v_pk_add_f32 v[20:21], v[20:21], v[116:117] neg_lo:[0,1] neg_hi:[0,1]
	v_pk_add_f32 v[22:23], v[22:23], v[116:117] neg_lo:[0,1] neg_hi:[0,1]
	v_pk_add_f32 v[24:25], v[24:25], v[116:117] neg_lo:[0,1] neg_hi:[0,1]
	v_pk_add_f32 v[26:27], v[26:27], v[116:117] neg_lo:[0,1] neg_hi:[0,1]
	v_pk_add_f32 v[28:29], v[28:29], v[116:117] neg_lo:[0,1] neg_hi:[0,1]
	v_pk_add_f32 v[30:31], v[30:31], v[116:117] neg_lo:[0,1] neg_hi:[0,1]
	v_pk_add_f32 v[32:33], v[32:33], v[116:117] neg_lo:[0,1] neg_hi:[0,1]
	v_pk_mul_f32 v[66:67], v[18:19], v[18:19]
	v_pk_mul_f32 v[68:69], v[20:21], v[20:21]
	v_pk_fma_f32 v[66:67], v[22:23], v[22:23], v[66:67]
	v_pk_fma_f32 v[68:69], v[24:25], v[24:25], v[68:69]
	v_pk_fma_f32 v[66:67], v[26:27], v[26:27], v[66:67]
	v_pk_fma_f32 v[68:69], v[28:29], v[28:29], v[68:69]
	v_pk_fma_f32 v[66:67], v[30:31], v[30:31], v[66:67]
	v_pk_fma_f32 v[68:69], v[32:33], v[32:33], v[68:69]
	v_pk_add_f32 v[66:67], v[66:67], v[68:69]
	v_add_f32_e32 v66, v66, v67
	s_nop 1
	v_add_f32_dpp v66, v66, v66 row_shr:1 row_mask:0xf bank_mask:0xf bound_ctrl:1
	s_nop 1
	v_add_f32_dpp v66, v66, v66 row_shr:2 row_mask:0xf bank_mask:0xf bound_ctrl:1
	s_nop 1
	v_add_f32_dpp v66, v66, v66 row_shr:4 row_mask:0xf bank_mask:0xf bound_ctrl:1
	s_nop 1
	v_add_f32_dpp v66, v66, v66 row_shr:8 row_mask:0xf bank_mask:0xf bound_ctrl:1
	s_nop 0
	v_readlane_b32 s9, v66, 15
	v_readlane_b32 s10, v66, 31
	v_readlane_b32 s11, v66, 47
	v_readlane_b32 vcc_lo, v66, 63
	s_nop 1
	v_mov_b32_e32 v66, s9
	v_add_f32_e32 v66, s10, v66
	v_add_f32_e32 v66, s11, v66
	v_add_f32_e32 v66, vcc_lo, v66
	v_mul_f32_e32 v66, 0x3a800000, v66
	v_add_f32_e32 v66, 0x3727c5ac, v66
	v_rsq_f32_e32 v118, v66
	s_nop 0
	v_mov_b32_e32 v119, v118
	v_pk_mul_f32 v[18:19], v[18:19], v[118:119]
	v_pk_mul_f32 v[20:21], v[20:21], v[118:119]
	v_pk_mul_f32 v[22:23], v[22:23], v[118:119]
	v_pk_mul_f32 v[24:25], v[24:25], v[118:119]
	v_pk_mul_f32 v[26:27], v[26:27], v[118:119]
	v_pk_mul_f32 v[28:29], v[28:29], v[118:119]
	v_pk_mul_f32 v[30:31], v[30:31], v[118:119]
	v_pk_mul_f32 v[32:33], v[32:33], v[118:119]
	v_pk_fma_f32 v[76:77], v[18:19], v[34:35], v[50:51]
	v_pk_fma_f32 v[78:79], v[20:21], v[36:37], v[52:53]
	v_pk_fma_f32 v[80:81], v[22:23], v[38:39], v[54:55]
	v_pk_fma_f32 v[82:83], v[24:25], v[40:41], v[56:57]
	v_pk_fma_f32 v[84:85], v[26:27], v[42:43], v[58:59]
	v_pk_fma_f32 v[86:87], v[28:29], v[44:45], v[60:61]
	v_pk_fma_f32 v[88:89], v[30:31], v[46:47], v[62:63]
	v_pk_fma_f32 v[90:91], v[32:33], v[48:49], v[64:65]
	v_cvt_pk_bf16_f32 v92, v76, v77
	v_cvt_pk_bf16_f32 v93, v78, v79
	v_cvt_pk_bf16_f32 v94, v80, v81
	v_cvt_pk_bf16_f32 v95, v82, v83
	v_cvt_pk_bf16_f32 v96, v84, v85
	v_cvt_pk_bf16_f32 v97, v86, v87
	v_cvt_pk_bf16_f32 v98, v88, v89
	v_cvt_pk_bf16_f32 v99, v90, v91
	global_store_dwordx2 v115, v[92:93], s[2:3] offset:0
	global_store_dwordx2 v115, v[94:95], s[2:3] offset:512
	global_store_dwordx2 v115, v[96:97], s[2:3] offset:1024
	global_store_dwordx2 v115, v[98:99], s[2:3] offset:1536
	s_add_u32 s2, s2, 0x400000
	s_addc_u32 s3, s3, 0
	s_add_u32 s0, s0, 0x800000
	s_addc_u32 s1, s1, 0
	global_load_dwordx4 v[18:21], v114, s[0:1] offset:0
	global_load_dwordx4 v[22:25], v114, s[0:1] offset:1024
	global_load_dwordx4 v[26:29], v114, s[0:1] offset:2048
	global_load_dwordx4 v[30:33], v114, s[0:1] offset:3072
	s_waitcnt vmcnt(8)
; __device__ __forceinline__ void phase_ln(float* R, const float* __restrict__ g, const float* __restrict__ b, bf16_t* xbf, float samp_scale, const float* __restrict__ part, int nsplit, bool f32_all) {
;     ...
;   for (int r = gw; r < MT; r += nw) {
;     float* row = R + (size_t)r * 1024;
;     f32x4 v[4];
; #pragma unroll
;     for (int i = 0; i < 4; ++i) v[i] = *(const f32x4*)(row + i * 256 + lane * 4);
;     if (r >= MP) {
;       for (int sp = 0; sp < nsplit; ++sp) {
;         const float* prow = part + ((size_t)sp * MS + (r - MP)) * 1024;
; #pragma unroll
;         for (int i = 0; i < 4; ++i) v[i] = v[i] + *(const f32x4*)(prow + i * 256 + lane * 4);
;       }
;     }
;     float s = 0.f;
; #pragma unroll
;     for (int i = 0; i < 4; ++i) s += v[i][0] + v[i][1] + v[i][2] + v[i][3];
; #pragma unroll
;     for (int o = 32; o >= 1; o >>= 1) s += __shfl_xor(s, o);
;     const float mean = s * (1.f / 1024.f);
;     float ss = 0.f;
; #pragma unroll
;     for (int i = 0; i < 4; ++i) { v[i] = v[i] - mean; ss += v[i][0] * v[i][0] + v[i][1] * v[i][1] + v[i][2] * v[i][2] + v[i][3] * v[i][3]; }
; #pragma unroll
;     for (int o = 32; o >= 1; o >>= 1) ss += __shfl_xor(ss, o);
;     const float rstd = rsqrtf(ss * (1.f / 1024.f) + LN_EPS);
; #pragma unroll
;     for (int i = 0; i < 4; ++i) {
;       const f32x4 y = v[i] * rstd * gv[i] + bv[i];
;       if (r >= MP) *(f32x4*)(row + i * 256 + lane * 4) = y * samp_scale;
;       else if (f32_all) *(f32x4*)(row + i * 256 + lane * 4) = y;
;       if (xbf) {
;         u32x2 wv;
;         wv[0] = cvt_pk_bf16(y[0], y[1]); wv[1] = cvt_pk_bf16(y[2], y[3]);
;         *(u32x2*)(xbf + (size_t)r * 1024 + i * 256 + lane * 4) = wv;
;       }
;     }
	v_pk_add_f32 v[66:67], v[0:1], v[2:3]
	v_pk_add_f32 v[68:69], v[4:5], v[6:7]
	v_pk_add_f32 v[70:71], v[8:9], v[10:11]
	v_pk_add_f32 v[72:73], v[12:13], v[14:15]
	v_pk_add_f32 v[66:67], v[66:67], v[68:69]
	v_pk_add_f32 v[70:71], v[70:71], v[72:73]
	v_pk_add_f32 v[66:67], v[66:67], v[70:71]
	v_add_f32_e32 v66, v66, v67
	s_nop 1
	v_add_f32_dpp v66, v66, v66 row_shr:1 row_mask:0xf bank_mask:0xf bound_ctrl:1
	s_nop 1
	v_add_f32_dpp v66, v66, v66 row_shr:2 row_mask:0xf bank_mask:0xf bound_ctrl:1
	s_nop 1
	v_add_f32_dpp v66, v66, v66 row_shr:4 row_mask:0xf bank_mask:0xf bound_ctrl:1
	s_nop 1
	v_add_f32_dpp v66, v66, v66 row_shr:8 row_mask:0xf bank_mask:0xf bound_ctrl:1
	s_nop 0
	v_readlane_b32 s9, v66, 15
	v_readlane_b32 s10, v66, 31
	v_readlane_b32 s11, v66, 47
	v_readlane_b32 vcc_lo, v66, 63
	s_nop 1
	v_mov_b32_e32 v66, s9
	v_add_f32_e32 v66, s10, v66
	v_add_f32_e32 v66, s11, v66
	v_add_f32_e32 v66, vcc_lo, v66
	v_mul_f32_e32 v116, 0x3a800000, v66
	v_mov_b32_e32 v117, v116
	v_pk_add_f32 v[0:1], v[0:1], v[116:117] neg_lo:[0,1] neg_hi:[0,1]
	v_pk_add_f32 v[2:3], v[2:3], v[116:117] neg_lo:[0,1] neg_hi:[0,1]
	v_pk_add_f32 v[4:5], v[4:5], v[116:117] neg_lo:[0,1] neg_hi:[0,1]
	v_pk_add_f32 v[6:7], v[6:7], v[116:117] neg_lo:[0,1] neg_hi:[0,1]
	v_pk_add_f32 v[8:9], v[8:9], v[116:117] neg_lo:[0,1] neg_hi:[0,1]
	v_pk_add_f32 v[10:11], v[10:11], v[116:117] neg_lo:[0,1] neg_hi:[0,1]
	v_pk_add_f32 v[12:13], v[12:13], v[116:117] neg_lo:[0,1] neg_hi:[0,1]
	v_pk_add_f32 v[14:15], v[14:15], v[116:117] neg_lo:[0,1] neg_hi:[0,1]
	v_pk_mul_f32 v[66:67], v[0:1], v[0:1]
	v_pk_mul_f32 v[68:69], v[2:3], v[2:3]
	v_pk_fma_f32 v[66:67], v[4:5], v[4:5], v[66:67]
	v_pk_fma_f32 v[68:69], v[6:7], v[6:7], v[68:69]
	v_pk_fma_f32 v[66:67], v[8:9], v[8:9], v[66:67]
	v_pk_fma_f32 v[68:69], v[10:11], v[10:11], v[68:69]
	v_pk_fma_f32 v[66:67], v[12:13], v[12:13], v[66:67]
	v_pk_fma_f32 v[68:69], v[14:15], v[14:15], v[68:69]
	v_pk_add_f32 v[66:67], v[66:67], v[68:69]
	v_add_f32_e32 v66, v66, v67
	s_nop 1
	v_add_f32_dpp v66, v66, v66 row_shr:1 row_mask:0xf bank_mask:0xf bound_ctrl:1
	s_nop 1
	v_add_f32_dpp v66, v66, v66 row_shr:2 row_mask:0xf bank_mask:0xf bound_ctrl:1
	s_nop 1
	v_add_f32_dpp v66, v66, v66 row_shr:4 row_mask:0xf bank_mask:0xf bound_ctrl:1
	s_nop 1
	v_add_f32_dpp v66, v66, v66 row_shr:8 row_mask:0xf bank_mask:0xf bound_ctrl:1
	s_nop 0
	v_readlane_b32 s9, v66, 15
	v_readlane_b32 s10, v66, 31
	v_readlane_b32 s11, v66, 47
	v_readlane_b32 vcc_lo, v66, 63
	s_nop 1
	v_mov_b32_e32 v66, s9
	v_add_f32_e32 v66, s10, v66
	v_add_f32_e32 v66, s11, v66
	v_add_f32_e32 v66, vcc_lo, v66
	v_mul_f32_e32 v66, 0x3a800000, v66
	v_add_f32_e32 v66, 0x3727c5ac, v66
	v_rsq_f32_e32 v118, v66
	s_nop 0
	v_mov_b32_e32 v119, v118
	v_pk_mul_f32 v[0:1], v[0:1], v[118:119]
	v_pk_mul_f32 v[2:3], v[2:3], v[118:119]
	v_pk_mul_f32 v[4:5], v[4:5], v[118:119]
	v_pk_mul_f32 v[6:7], v[6:7], v[118:119]
	v_pk_mul_f32 v[8:9], v[8:9], v[118:119]
	v_pk_mul_f32 v[10:11], v[10:11], v[118:119]
	v_pk_mul_f32 v[12:13], v[12:13], v[118:119]
	v_pk_mul_f32 v[14:15], v[14:15], v[118:119]
	v_pk_fma_f32 v[76:77], v[0:1], v[34:35], v[50:51]
	v_pk_fma_f32 v[78:79], v[2:3], v[36:37], v[52:53]
	v_pk_fma_f32 v[80:81], v[4:5], v[38:39], v[54:55]
	v_pk_fma_f32 v[82:83], v[6:7], v[40:41], v[56:57]
	v_pk_fma_f32 v[84:85], v[8:9], v[42:43], v[58:59]
	v_pk_fma_f32 v[86:87], v[10:11], v[44:45], v[60:61]
	v_pk_fma_f32 v[88:89], v[12:13], v[46:47], v[62:63]
	v_pk_fma_f32 v[90:91], v[14:15], v[48:49], v[64:65]
	v_cvt_pk_bf16_f32 v92, v76, v77
	v_cvt_pk_bf16_f32 v93, v78, v79
	v_cvt_pk_bf16_f32 v94, v80, v81
	v_cvt_pk_bf16_f32 v95, v82, v83
	v_cvt_pk_bf16_f32 v96, v84, v85
	v_cvt_pk_bf16_f32 v97, v86, v87
	v_cvt_pk_bf16_f32 v98, v88, v89
	v_cvt_pk_bf16_f32 v99, v90, v91
	global_store_dwordx2 v115, v[92:93], s[2:3] offset:0
	global_store_dwordx2 v115, v[94:95], s[2:3] offset:512
	global_store_dwordx2 v115, v[96:97], s[2:3] offset:1024
	global_store_dwordx2 v115, v[98:99], s[2:3] offset:1536
	s_add_u32 s2, s2, 0x400000
	s_addc_u32 s3, s3, 0
	s_add_u32 s0, s0, 0x800000
	s_addc_u32 s1, s1, 0
	global_load_dwordx4 v[0:3], v114, s[0:1] offset:0
	global_load_dwordx4 v[4:7], v114, s[0:1] offset:1024
	global_load_dwordx4 v[8:11], v114, s[0:1] offset:2048
	global_load_dwordx4 v[12:15], v114, s[0:1] offset:3072
	s_waitcnt vmcnt(8)
; __device__ __forceinline__ void phase_ln(float* R, const float* __restrict__ g, const float* __restrict__ b, bf16_t* xbf, float samp_scale, const float* __restrict__ part, int nsplit, bool f32_all) {
;     ...
;   for (int r = gw; r < MT; r += nw) {
;     float* row = R + (size_t)r * 1024;
;     f32x4 v[4];
; #pragma unroll
;     for (int i = 0; i < 4; ++i) v[i] = *(const f32x4*)(row + i * 256 + lane * 4);
;     if (r >= MP) {
;       for (int sp = 0; sp < nsplit; ++sp) {
;         const float* prow = part + ((size_t)sp * MS + (r - MP)) * 1024;
; #pragma unroll
;         for (int i = 0; i < 4; ++i) v[i] = v[i] + *(const f32x4*)(prow + i * 256 + lane * 4);
;       }
;     }
;     float s = 0.f;
; #pragma unroll
;     for (int i = 0; i < 4; ++i) s += v[i][0] + v[i][1] + v[i][2] + v[i][3];
; #pragma unroll
;     for (int o = 32; o >= 1; o >>= 1) s += __shfl_xor(s, o);
;     const float mean = s * (1.f / 1024.f);
;     float ss = 0.f;
; #pragma unroll
;     for (int i = 0; i < 4; ++i) { v[i] = v[i] - mean; ss += v[i][0] * v[i][0] + v[i][1] * v[i][1] + v[i][2] * v[i][2] + v[i][3] * v[i][3]; }
; #pragma unroll
;     for (int o = 32; o >= 1; o >>= 1) ss += __shfl_xor(ss, o);
;     const float rstd = rsqrtf(ss * (1.f / 1024.f) + LN_EPS);
; #pragma unroll
;     for (int i = 0; i < 4; ++i) {
;       const f32x4 y = v[i] * rstd * gv[i] + bv[i];
;       if (r >= MP) *(f32x4*)(row + i * 256 + lane * 4) = y * samp_scale;
;       else if (f32_all) *(f32x4*)(row + i * 256 + lane * 4) = y;
;       if (xbf) {
;         u32x2 wv;
;         wv[0] = cvt_pk_bf16(y[0], y[1]); wv[1] = cvt_pk_bf16(y[2], y[3]);
;         *(u32x2*)(xbf + (size_t)r * 1024 + i * 256 + lane * 4) = wv;
;       }
;     }
	v_pk_add_f32 v[66:67], v[18:19], v[20:21]
	v_pk_add_f32 v[68:69], v[22:23], v[24:25]
	v_pk_add_f32 v[70:71], v[26:27], v[28:29]
	v_pk_add_f32 v[72:73], v[30:31], v[32:33]
	v_pk_add_f32 v[66:67], v[66:67], v[68:69]
	v_pk_add_f32 v[70:71], v[70:71], v[72:73]
	v_pk_add_f32 v[66:67], v[66:67], v[70:71]
	v_add_f32_e32 v66, v66, v67
	s_nop 1
	v_add_f32_dpp v66, v66, v66 row_shr:1 row_mask:0xf bank_mask:0xf bound_ctrl:1
	s_nop 1
	v_add_f32_dpp v66, v66, v66 row_shr:2 row_mask:0xf bank_mask:0xf bound_ctrl:1
	s_nop 1
	v_add_f32_dpp v66, v66, v66 row_shr:4 row_mask:0xf bank_mask:0xf bound_ctrl:1
	s_nop 1
	v_add_f32_dpp v66, v66, v66 row_shr:8 row_mask:0xf bank_mask:0xf bound_ctrl:1
	s_nop 0
	v_readlane_b32 s9, v66, 15
	v_readlane_b32 s10, v66, 31
	v_readlane_b32 s11, v66, 47
	v_readlane_b32 vcc_lo, v66, 63
	s_nop 1
	v_mov_b32_e32 v66, s9
	v_add_f32_e32 v66, s10, v66
	v_add_f32_e32 v66, s11, v66
	v_add_f32_e32 v66, vcc_lo, v66
	v_mul_f32_e32 v116, 0x3a800000, v66
	v_mov_b32_e32 v117, v116
	v_pk_add_f32 v[18:19], v[18:19], v[116:117] neg_lo:[0,1] neg_hi:[0,1]
	v_pk_add_f32 v[20:21], v[20:21], v[116:117] neg_lo:[0,1] neg_hi:[0,1]
	v_pk_add_f32 v[22:23], v[22:23], v[116:117] neg_lo:[0,1] neg_hi:[0,1]
	v_pk_add_f32 v[24:25], v[24:25], v[116:117] neg_lo:[0,1] neg_hi:[0,1]
	v_pk_add_f32 v[26:27], v[26:27], v[116:117] neg_lo:[0,1] neg_hi:[0,1]
	v_pk_add_f32 v[28:29], v[28:29], v[116:117] neg_lo:[0,1] neg_hi:[0,1]
	v_pk_add_f32 v[30:31], v[30:31], v[116:117] neg_lo:[0,1] neg_hi:[0,1]
	v_pk_add_f32 v[32:33], v[32:33], v[116:117] neg_lo:[0,1] neg_hi:[0,1]
	v_pk_mul_f32 v[66:67], v[18:19], v[18:19]
	v_pk_mul_f32 v[68:69], v[20:21], v[20:21]
	v_pk_fma_f32 v[66:67], v[22:23], v[22:23], v[66:67]
	v_pk_fma_f32 v[68:69], v[24:25], v[24:25], v[68:69]
	v_pk_fma_f32 v[66:67], v[26:27], v[26:27], v[66:67]
	v_pk_fma_f32 v[68:69], v[28:29], v[28:29], v[68:69]
	v_pk_fma_f32 v[66:67], v[30:31], v[30:31], v[66:67]
	v_pk_fma_f32 v[68:69], v[32:33], v[32:33], v[68:69]
	v_pk_add_f32 v[66:67], v[66:67], v[68:69]
	v_add_f32_e32 v66, v66, v67
	s_nop 1
	v_add_f32_dpp v66, v66, v66 row_shr:1 row_mask:0xf bank_mask:0xf bound_ctrl:1
	s_nop 1
	v_add_f32_dpp v66, v66, v66 row_shr:2 row_mask:0xf bank_mask:0xf bound_ctrl:1
	s_nop 1
	v_add_f32_dpp v66, v66, v66 row_shr:4 row_mask:0xf bank_mask:0xf bound_ctrl:1
	s_nop 1
	v_add_f32_dpp v66, v66, v66 row_shr:8 row_mask:0xf bank_mask:0xf bound_ctrl:1
	s_nop 0
	v_readlane_b32 s9, v66, 15
	v_readlane_b32 s10, v66, 31
	v_readlane_b32 s11, v66, 47
	v_readlane_b32 vcc_lo, v66, 63
	s_nop 1
	v_mov_b32_e32 v66, s9
	v_add_f32_e32 v66, s10, v66
	v_add_f32_e32 v66, s11, v66
	v_add_f32_e32 v66, vcc_lo, v66
	v_mul_f32_e32 v66, 0x3a800000, v66
	v_add_f32_e32 v66, 0x3727c5ac, v66
	v_rsq_f32_e32 v118, v66
	s_nop 0
	v_mov_b32_e32 v119, v118
	v_pk_mul_f32 v[18:19], v[18:19], v[118:119]
	v_pk_mul_f32 v[20:21], v[20:21], v[118:119]
	v_pk_mul_f32 v[22:23], v[22:23], v[118:119]
	v_pk_mul_f32 v[24:25], v[24:25], v[118:119]
	v_pk_mul_f32 v[26:27], v[26:27], v[118:119]
	v_pk_mul_f32 v[28:29], v[28:29], v[118:119]
	v_pk_mul_f32 v[30:31], v[30:31], v[118:119]
	v_pk_mul_f32 v[32:33], v[32:33], v[118:119]
	v_pk_fma_f32 v[76:77], v[18:19], v[34:35], v[50:51]
	v_pk_fma_f32 v[78:79], v[20:21], v[36:37], v[52:53]
	v_pk_fma_f32 v[80:81], v[22:23], v[38:39], v[54:55]
	v_pk_fma_f32 v[82:83], v[24:25], v[40:41], v[56:57]
	v_pk_fma_f32 v[84:85], v[26:27], v[42:43], v[58:59]
	v_pk_fma_f32 v[86:87], v[28:29], v[44:45], v[60:61]
	v_pk_fma_f32 v[88:89], v[30:31], v[46:47], v[62:63]
	v_pk_fma_f32 v[90:91], v[32:33], v[48:49], v[64:65]
	v_cvt_pk_bf16_f32 v92, v76, v77
	v_cvt_pk_bf16_f32 v93, v78, v79
	v_cvt_pk_bf16_f32 v94, v80, v81
	v_cvt_pk_bf16_f32 v95, v82, v83
	v_cvt_pk_bf16_f32 v96, v84, v85
	v_cvt_pk_bf16_f32 v97, v86, v87
	v_cvt_pk_bf16_f32 v98, v88, v89
	v_cvt_pk_bf16_f32 v99, v90, v91
	global_store_dwordx2 v115, v[92:93], s[2:3] offset:0
	global_store_dwordx2 v115, v[94:95], s[2:3] offset:512
	global_store_dwordx2 v115, v[96:97], s[2:3] offset:1024
	global_store_dwordx2 v115, v[98:99], s[2:3] offset:1536
	s_add_u32 s2, s2, 0x400000
	s_addc_u32 s3, s3, 0
	s_add_u32 s0, s0, 0x800000
	s_addc_u32 s1, s1, 0
	global_load_dwordx4 v[18:21], v114, s[0:1] offset:0
	global_load_dwordx4 v[22:25], v114, s[0:1] offset:1024
	global_load_dwordx4 v[26:29], v114, s[0:1] offset:2048
	global_load_dwordx4 v[30:33], v114, s[0:1] offset:3072
	s_waitcnt vmcnt(8)
; __device__ __forceinline__ void phase_ln(float* R, const float* __restrict__ g, const float* __restrict__ b, bf16_t* xbf, float samp_scale, const float* __restrict__ part, int nsplit, bool f32_all) {
;     ...
;   for (int r = gw; r < MT; r += nw) {
;     float* row = R + (size_t)r * 1024;
;     f32x4 v[4];
; #pragma unroll
;     for (int i = 0; i < 4; ++i) v[i] = *(const f32x4*)(row + i * 256 + lane * 4);
;     if (r >= MP) {
;       for (int sp = 0; sp < nsplit; ++sp) {
;         const float* prow = part + ((size_t)sp * MS + (r - MP)) * 1024;
; #pragma unroll
;         for (int i = 0; i < 4; ++i) v[i] = v[i] + *(const f32x4*)(prow + i * 256 + lane * 4);
;       }
;     }
;     float s = 0.f;
; #pragma unroll
;     for (int i = 0; i < 4; ++i) s += v[i][0] + v[i][1] + v[i][2] + v[i][3];
; #pragma unroll
;     for (int o = 32; o >= 1; o >>= 1) s += __shfl_xor(s, o);
;     const float mean = s * (1.f / 1024.f);
;     float ss = 0.f;
; #pragma unroll
;     for (int i = 0; i < 4; ++i) { v[i] = v[i] - mean; ss += v[i][0] * v[i][0] + v[i][1] * v[i][1] + v[i][2] * v[i][2] + v[i][3] * v[i][3]; }
; #pragma unroll
;     for (int o = 32; o >= 1; o >>= 1) ss += __shfl_xor(ss, o);
;     const float rstd = rsqrtf(ss * (1.f / 1024.f) + LN_EPS);
; #pragma unroll
;     for (int i = 0; i < 4; ++i) {
;       const f32x4 y = v[i] * rstd * gv[i] + bv[i];
;       if (r >= MP) *(f32x4*)(row + i * 256 + lane * 4) = y * samp_scale;
;       else if (f32_all) *(f32x4*)(row + i * 256 + lane * 4) = y;
;       if (xbf) {
;         u32x2 wv;
;         wv[0] = cvt_pk_bf16(y[0], y[1]); wv[1] = cvt_pk_bf16(y[2], y[3]);
;         *(u32x2*)(xbf + (size_t)r * 1024 + i * 256 + lane * 4) = wv;
;       }
;     }
	v_pk_add_f32 v[66:67], v[0:1], v[2:3]
	v_pk_add_f32 v[68:69], v[4:5], v[6:7]
	v_pk_add_f32 v[70:71], v[8:9], v[10:11]
	v_pk_add_f32 v[72:73], v[12:13], v[14:15]
	v_pk_add_f32 v[66:67], v[66:67], v[68:69]
	v_pk_add_f32 v[70:71], v[70:71], v[72:73]
	v_pk_add_f32 v[66:67], v[66:67], v[70:71]
	v_add_f32_e32 v66, v66, v67
	s_nop 1
	v_add_f32_dpp v66, v66, v66 row_shr:1 row_mask:0xf bank_mask:0xf bound_ctrl:1
	s_nop 1
	v_add_f32_dpp v66, v66, v66 row_shr:2 row_mask:0xf bank_mask:0xf bound_ctrl:1
	s_nop 1
	v_add_f32_dpp v66, v66, v66 row_shr:4 row_mask:0xf bank_mask:0xf bound_ctrl:1
	s_nop 1
	v_add_f32_dpp v66, v66, v66 row_shr:8 row_mask:0xf bank_mask:0xf bound_ctrl:1
	s_nop 0
	v_readlane_b32 s9, v66, 15
	v_readlane_b32 s10, v66, 31
	v_readlane_b32 s11, v66, 47
	v_readlane_b32 vcc_lo, v66, 63
	s_nop 1
	v_mov_b32_e32 v66, s9
	v_add_f32_e32 v66, s10, v66
	v_add_f32_e32 v66, s11, v66
	v_add_f32_e32 v66, vcc_lo, v66
	v_mul_f32_e32 v116, 0x3a800000, v66
	v_mov_b32_e32 v117, v116
	v_pk_add_f32 v[0:1], v[0:1], v[116:117] neg_lo:[0,1] neg_hi:[0,1]
	v_pk_add_f32 v[2:3], v[2:3], v[116:117] neg_lo:[0,1] neg_hi:[0,1]
	v_pk_add_f32 v[4:5], v[4:5], v[116:117] neg_lo:[0,1] neg_hi:[0,1]
	v_pk_add_f32 v[6:7], v[6:7], v[116:117] neg_lo:[0,1] neg_hi:[0,1]
	v_pk_add_f32 v[8:9], v[8:9], v[116:117] neg_lo:[0,1] neg_hi:[0,1]
	v_pk_add_f32 v[10:11], v[10:11], v[116:117] neg_lo:[0,1] neg_hi:[0,1]
	v_pk_add_f32 v[12:13], v[12:13], v[116:117] neg_lo:[0,1] neg_hi:[0,1]
	v_pk_add_f32 v[14:15], v[14:15], v[116:117] neg_lo:[0,1] neg_hi:[0,1]
	v_pk_mul_f32 v[66:67], v[0:1], v[0:1]
	v_pk_mul_f32 v[68:69], v[2:3], v[2:3]
	v_pk_fma_f32 v[66:67], v[4:5], v[4:5], v[66:67]
	v_pk_fma_f32 v[68:69], v[6:7], v[6:7], v[68:69]
	v_pk_fma_f32 v[66:67], v[8:9], v[8:9], v[66:67]
	v_pk_fma_f32 v[68:69], v[10:11], v[10:11], v[68:69]
	v_pk_fma_f32 v[66:67], v[12:13], v[12:13], v[66:67]
	v_pk_fma_f32 v[68:69], v[14:15], v[14:15], v[68:69]
	v_pk_add_f32 v[66:67], v[66:67], v[68:69]
	v_add_f32_e32 v66, v66, v67
	s_nop 1
	v_add_f32_dpp v66, v66, v66 row_shr:1 row_mask:0xf bank_mask:0xf bound_ctrl:1
	s_nop 1
	v_add_f32_dpp v66, v66, v66 row_shr:2 row_mask:0xf bank_mask:0xf bound_ctrl:1
	s_nop 1
	v_add_f32_dpp v66, v66, v66 row_shr:4 row_mask:0xf bank_mask:0xf bound_ctrl:1
	s_nop 1
	v_add_f32_dpp v66, v66, v66 row_shr:8 row_mask:0xf bank_mask:0xf bound_ctrl:1
	s_nop 0
	v_readlane_b32 s9, v66, 15
	v_readlane_b32 s10, v66, 31
	v_readlane_b32 s11, v66, 47
	v_readlane_b32 vcc_lo, v66, 63
	s_nop 1
	v_mov_b32_e32 v66, s9
	v_add_f32_e32 v66, s10, v66
	v_add_f32_e32 v66, s11, v66
	v_add_f32_e32 v66, vcc_lo, v66
	v_mul_f32_e32 v66, 0x3a800000, v66
	v_add_f32_e32 v66, 0x3727c5ac, v66
	v_rsq_f32_e32 v118, v66
	s_nop 0
	v_mov_b32_e32 v119, v118
	v_pk_mul_f32 v[0:1], v[0:1], v[118:119]
	v_pk_mul_f32 v[2:3], v[2:3], v[118:119]
	v_pk_mul_f32 v[4:5], v[4:5], v[118:119]
	v_pk_mul_f32 v[6:7], v[6:7], v[118:119]
	v_pk_mul_f32 v[8:9], v[8:9], v[118:119]
	v_pk_mul_f32 v[10:11], v[10:11], v[118:119]
	v_pk_mul_f32 v[12:13], v[12:13], v[118:119]
	v_pk_mul_f32 v[14:15], v[14:15], v[118:119]
	v_pk_fma_f32 v[76:77], v[0:1], v[34:35], v[50:51]
	v_pk_fma_f32 v[78:79], v[2:3], v[36:37], v[52:53]
	v_pk_fma_f32 v[80:81], v[4:5], v[38:39], v[54:55]
	v_pk_fma_f32 v[82:83], v[6:7], v[40:41], v[56:57]
	v_pk_fma_f32 v[84:85], v[8:9], v[42:43], v[58:59]
	v_pk_fma_f32 v[86:87], v[10:11], v[44:45], v[60:61]
	v_pk_fma_f32 v[88:89], v[12:13], v[46:47], v[62:63]
	v_pk_fma_f32 v[90:91], v[14:15], v[48:49], v[64:65]
	v_cvt_pk_bf16_f32 v92, v76, v77
	v_cvt_pk_bf16_f32 v93, v78, v79
	v_cvt_pk_bf16_f32 v94, v80, v81
	v_cvt_pk_bf16_f32 v95, v82, v83
	v_cvt_pk_bf16_f32 v96, v84, v85
	v_cvt_pk_bf16_f32 v97, v86, v87
	v_cvt_pk_bf16_f32 v98, v88, v89
	v_cvt_pk_bf16_f32 v99, v90, v91
	global_store_dwordx2 v115, v[92:93], s[2:3] offset:0
	global_store_dwordx2 v115, v[94:95], s[2:3] offset:512
	global_store_dwordx2 v115, v[96:97], s[2:3] offset:1024
	global_store_dwordx2 v115, v[98:99], s[2:3] offset:1536
	s_add_u32 s2, s2, 0x400000
	s_addc_u32 s3, s3, 0
	s_waitcnt vmcnt(4)
	v_pk_add_f32 v[66:67], v[18:19], v[20:21]
	v_pk_add_f32 v[68:69], v[22:23], v[24:25]
	v_pk_add_f32 v[70:71], v[26:27], v[28:29]
	v_pk_add_f32 v[72:73], v[30:31], v[32:33]
	v_pk_add_f32 v[66:67], v[66:67], v[68:69]
	v_pk_add_f32 v[70:71], v[70:71], v[72:73]
	v_pk_add_f32 v[66:67], v[66:67], v[70:71]
	v_add_f32_e32 v66, v66, v67
	s_nop 1
	v_add_f32_dpp v66, v66, v66 row_shr:1 row_mask:0xf bank_mask:0xf bound_ctrl:1
	s_nop 1
	v_add_f32_dpp v66, v66, v66 row_shr:2 row_mask:0xf bank_mask:0xf bound_ctrl:1
	s_nop 1
	v_add_f32_dpp v66, v66, v66 row_shr:4 row_mask:0xf bank_mask:0xf bound_ctrl:1
	s_nop 1
	v_add_f32_dpp v66, v66, v66 row_shr:8 row_mask:0xf bank_mask:0xf bound_ctrl:1
	s_nop 0
	v_readlane_b32 s9, v66, 15
	v_readlane_b32 s10, v66, 31
	v_readlane_b32 s11, v66, 47
	v_readlane_b32 vcc_lo, v66, 63
	s_nop 1
	v_mov_b32_e32 v66, s9
	v_add_f32_e32 v66, s10, v66
	v_add_f32_e32 v66, s11, v66
	v_add_f32_e32 v66, vcc_lo, v66
	v_mul_f32_e32 v116, 0x3a800000, v66
	v_mov_b32_e32 v117, v116
	v_pk_add_f32 v[18:19], v[18:19], v[116:117] neg_lo:[0,1] neg_hi:[0,1]
	v_pk_add_f32 v[20:21], v[20:21], v[116:117] neg_lo:[0,1] neg_hi:[0,1]
	v_pk_add_f32 v[22:23], v[22:23], v[116:117] neg_lo:[0,1] neg_hi:[0,1]
	v_pk_add_f32 v[24:25], v[24:25], v[116:117] neg_lo:[0,1] neg_hi:[0,1]
	v_pk_add_f32 v[26:27], v[26:27], v[116:117] neg_lo:[0,1] neg_hi:[0,1]
	v_pk_add_f32 v[28:29], v[28:29], v[116:117] neg_lo:[0,1] neg_hi:[0,1]
	v_pk_add_f32 v[30:31], v[30:31], v[116:117] neg_lo:[0,1] neg_hi:[0,1]
	v_pk_add_f32 v[32:33], v[32:33], v[116:117] neg_lo:[0,1] neg_hi:[0,1]
	v_pk_mul_f32 v[66:67], v[18:19], v[18:19]
; __device__ __forceinline__ void phase_ln(float* R, const float* __restrict__ g, const float* __restrict__ b, bf16_t* xbf, float samp_scale, const float* __restrict__ part, int nsplit, bool f32_all) {
;     ...
;   for (int r = gw; r < MT; r += nw) {
;     float* row = R + (size_t)r * 1024;
;     f32x4 v[4];
; #pragma unroll
;     for (int i = 0; i < 4; ++i) v[i] = *(const f32x4*)(row + i * 256 + lane * 4);
;     if (r >= MP) {
;       for (int sp = 0; sp < nsplit; ++sp) {
;         const float* prow = part + ((size_t)sp * MS + (r - MP)) * 1024;
; #pragma unroll
;         for (int i = 0; i < 4; ++i) v[i] = v[i] + *(const f32x4*)(prow + i * 256 + lane * 4);
;       }
;     }
	v_pk_mul_f32 v[68:69], v[20:21], v[20:21]
	v_pk_fma_f32 v[66:67], v[22:23], v[22:23], v[66:67]
	v_pk_fma_f32 v[68:69], v[24:25], v[24:25], v[68:69]
	v_pk_fma_f32 v[66:67], v[26:27], v[26:27], v[66:67]
	v_pk_fma_f32 v[68:69], v[28:29], v[28:29], v[68:69]
	v_pk_fma_f32 v[66:67], v[30:31], v[30:31], v[66:67]
	v_pk_fma_f32 v[68:69], v[32:33], v[32:33], v[68:69]
	v_pk_add_f32 v[66:67], v[66:67], v[68:69]
	v_add_f32_e32 v66, v66, v67
	s_nop 1
	v_add_f32_dpp v66, v66, v66 row_shr:1 row_mask:0xf bank_mask:0xf bound_ctrl:1
	s_nop 1
	v_add_f32_dpp v66, v66, v66 row_shr:2 row_mask:0xf bank_mask:0xf bound_ctrl:1
	s_nop 1
	v_add_f32_dpp v66, v66, v66 row_shr:4 row_mask:0xf bank_mask:0xf bound_ctrl:1
	s_nop 1
	v_add_f32_dpp v66, v66, v66 row_shr:8 row_mask:0xf bank_mask:0xf bound_ctrl:1
	s_nop 0
	v_readlane_b32 s9, v66, 15
	v_readlane_b32 s10, v66, 31
	v_readlane_b32 s11, v66, 47
	v_readlane_b32 vcc_lo, v66, 63
	s_nop 1
	v_mov_b32_e32 v66, s9
	v_add_f32_e32 v66, s10, v66
	v_add_f32_e32 v66, s11, v66
	v_add_f32_e32 v66, vcc_lo, v66
	v_mul_f32_e32 v66, 0x3a800000, v66
	v_add_f32_e32 v66, 0x3727c5ac, v66
	v_rsq_f32_e32 v118, v66
	s_nop 0
	v_mov_b32_e32 v119, v118
	v_pk_mul_f32 v[18:19], v[18:19], v[118:119]
	v_pk_mul_f32 v[20:21], v[20:21], v[118:119]
	v_pk_mul_f32 v[22:23], v[22:23], v[118:119]
	v_pk_mul_f32 v[24:25], v[24:25], v[118:119]
	v_pk_mul_f32 v[26:27], v[26:27], v[118:119]
	v_pk_mul_f32 v[28:29], v[28:29], v[118:119]
	v_pk_mul_f32 v[30:31], v[30:31], v[118:119]
	v_pk_mul_f32 v[32:33], v[32:33], v[118:119]
	v_pk_fma_f32 v[76:77], v[18:19], v[34:35], v[50:51]
	v_pk_fma_f32 v[78:79], v[20:21], v[36:37], v[52:53]
	v_pk_fma_f32 v[80:81], v[22:23], v[38:39], v[54:55]
	v_pk_fma_f32 v[82:83], v[24:25], v[40:41], v[56:57]
	v_pk_fma_f32 v[84:85], v[26:27], v[42:43], v[58:59]
	v_pk_fma_f32 v[86:87], v[28:29], v[44:45], v[60:61]
	v_pk_fma_f32 v[88:89], v[30:31], v[46:47], v[62:63]
	v_pk_fma_f32 v[90:91], v[32:33], v[48:49], v[64:65]
	v_cvt_pk_bf16_f32 v92, v76, v77
	v_cvt_pk_bf16_f32 v93, v78, v79
	v_cvt_pk_bf16_f32 v94, v80, v81
	v_cvt_pk_bf16_f32 v95, v82, v83
	v_cvt_pk_bf16_f32 v96, v84, v85
	v_cvt_pk_bf16_f32 v97, v86, v87
	v_cvt_pk_bf16_f32 v98, v88, v89
	v_cvt_pk_bf16_f32 v99, v90, v91
	global_store_dwordx2 v115, v[92:93], s[2:3] offset:0
	global_store_dwordx2 v115, v[94:95], s[2:3] offset:512
	global_store_dwordx2 v115, v[96:97], s[2:3] offset:1024
	global_store_dwordx2 v115, v[98:99], s[2:3] offset:1536
	s_add_u32 s2, s2, 0x400000
	s_addc_u32 s3, s3, 0
	v_readfirstlane_b32 s10, v244
	v_readlane_b32 s9, v254, 6
	s_lshr_b32 s10, s10, 6
	s_cmp_ge_u32 s10, 2
	s_cbranch_scc1 .Lln1_done
	s_lshl_b32 s9, s9, 1
	s_add_i32 s9, s9, s10
	s_lshl_b32 s11, s9, 12
	s_add_u32 s11, s11, 0x8000000
	s_add_u32 s0, s4, s11
	s_addc_u32 s1, s5, 0
	s_lshl_b32 s11, s9, 11
	s_add_u32 s11, s11, 0x79c0000
	s_add_u32 s2, s6, s11
	s_addc_u32 s3, s7, 0
	s_lshl_b32 s11, s9, 12
	s_add_u32 s11, s11, 0x1e482000
	s_add_u32 s10, s6, s11
	s_addc_u32 s11, s7, 0
	global_load_dwordx4 v[0:3], v114, s[0:1] offset:0
	global_load_dwordx4 v[4:7], v114, s[0:1] offset:1024
	global_load_dwordx4 v[8:11], v114, s[0:1] offset:2048
	global_load_dwordx4 v[12:15], v114, s[0:1] offset:3072
	global_load_dwordx4 v[18:21], v114, s[10:11] offset:0
	global_load_dwordx4 v[22:25], v114, s[10:11] offset:1024
	global_load_dwordx4 v[26:29], v114, s[10:11] offset:2048
	global_load_dwordx4 v[30:33], v114, s[10:11] offset:3072
	s_add_u32 s10, s10, 0x200000
	s_addc_u32 s11, s11, 0
	global_load_dwordx4 v[66:69], v114, s[10:11] offset:0
	global_load_dwordx4 v[70:73], v114, s[10:11] offset:1024
	global_load_dwordx4 v[74:77], v114, s[10:11] offset:2048
	global_load_dwordx4 v[78:81], v114, s[10:11] offset:3072
	s_add_u32 s10, s10, 0x200000
	s_addc_u32 s11, s11, 0
	global_load_dwordx4 v[82:85], v114, s[10:11] offset:0
	global_load_dwordx4 v[86:89], v114, s[10:11] offset:1024
	global_load_dwordx4 v[90:93], v114, s[10:11] offset:2048
	global_load_dwordx4 v[94:97], v114, s[10:11] offset:3072
	s_add_u32 s10, s10, 0x200000
	s_addc_u32 s11, s11, 0
	global_load_dwordx4 v[98:101], v114, s[10:11] offset:0
	global_load_dwordx4 v[102:105], v114, s[10:11] offset:1024
	global_load_dwordx4 v[106:109], v114, s[10:11] offset:2048
	global_load_dwordx4 v[110:113], v114, s[10:11] offset:3072
	s_add_u32 s10, s10, 0x200000
	s_addc_u32 s11, s11, 0
	s_waitcnt vmcnt(0)
; __device__ __forceinline__ void phase_ln(float* R, const float* __restrict__ g, const float* __restrict__ b, bf16_t* xbf, float samp_scale, const float* __restrict__ part, int nsplit, bool f32_all) {
;     ...
;     if (r >= MP) {
;       for (int sp = 0; sp < nsplit; ++sp) {
;         const float* prow = part + ((size_t)sp * MS + (r - MP)) * 1024;
; #pragma unroll
;         for (int i = 0; i < 4; ++i) v[i] = v[i] + *(const f32x4*)(prow + i * 256 + lane * 4);
;       }
;     }
;     float s = 0.f;
; #pragma unroll
;     for (int i = 0; i < 4; ++i) s += v[i][0] + v[i][1] + v[i][2] + v[i][3];
; #pragma unroll
;     for (int o = 32; o >= 1; o >>= 1) s += __shfl_xor(s, o);
;     const float mean = s * (1.f / 1024.f);
;     float ss = 0.f;
; #pragma unroll
;     for (int i = 0; i < 4; ++i) { v[i] = v[i] - mean; ss += v[i][0] * v[i][0] + v[i][1] * v[i][1] + v[i][2] * v[i][2] + v[i][3] * v[i][3]; }
; #pragma unroll
;     for (int o = 32; o >= 1; o >>= 1) ss += __shfl_xor(ss, o);
;     const float rstd = rsqrtf(ss * (1.f / 1024.f) + LN_EPS);
; #pragma unroll
;     for (int i = 0; i < 4; ++i) {
;       const f32x4 y = v[i] * rstd * gv[i] + bv[i];
;       if (r >= MP) *(f32x4*)(row + i * 256 + lane * 4) = y * samp_scale;
;       else if (f32_all) *(f32x4*)(row + i * 256 + lane * 4) = y;
;       if (xbf) {
;         u32x2 wv;
;         wv[0] = cvt_pk_bf16(y[0], y[1]); wv[1] = cvt_pk_bf16(y[2], y[3]);
;         *(u32x2*)(xbf + (size_t)r * 1024 + i * 256 + lane * 4) = wv;
;       }
;     }
	v_pk_add_f32 v[0:1], v[0:1], v[18:19]
	v_pk_add_f32 v[2:3], v[2:3], v[20:21]
	v_pk_add_f32 v[4:5], v[4:5], v[22:23]
	v_pk_add_f32 v[6:7], v[6:7], v[24:25]
	v_pk_add_f32 v[8:9], v[8:9], v[26:27]
	v_pk_add_f32 v[10:11], v[10:11], v[28:29]
	v_pk_add_f32 v[12:13], v[12:13], v[30:31]
	v_pk_add_f32 v[14:15], v[14:15], v[32:33]
	v_pk_add_f32 v[0:1], v[0:1], v[66:67]
	v_pk_add_f32 v[2:3], v[2:3], v[68:69]
	v_pk_add_f32 v[4:5], v[4:5], v[70:71]
	v_pk_add_f32 v[6:7], v[6:7], v[72:73]
	v_pk_add_f32 v[8:9], v[8:9], v[74:75]
	v_pk_add_f32 v[10:11], v[10:11], v[76:77]
	v_pk_add_f32 v[12:13], v[12:13], v[78:79]
	v_pk_add_f32 v[14:15], v[14:15], v[80:81]
	v_pk_add_f32 v[0:1], v[0:1], v[82:83]
	v_pk_add_f32 v[2:3], v[2:3], v[84:85]
	v_pk_add_f32 v[4:5], v[4:5], v[86:87]
	v_pk_add_f32 v[6:7], v[6:7], v[88:89]
	v_pk_add_f32 v[8:9], v[8:9], v[90:91]
	v_pk_add_f32 v[10:11], v[10:11], v[92:93]
	v_pk_add_f32 v[12:13], v[12:13], v[94:95]
	v_pk_add_f32 v[14:15], v[14:15], v[96:97]
	v_pk_add_f32 v[0:1], v[0:1], v[98:99]
	v_pk_add_f32 v[2:3], v[2:3], v[100:101]
	v_pk_add_f32 v[4:5], v[4:5], v[102:103]
	v_pk_add_f32 v[6:7], v[6:7], v[104:105]
	v_pk_add_f32 v[8:9], v[8:9], v[106:107]
	v_pk_add_f32 v[10:11], v[10:11], v[108:109]
	v_pk_add_f32 v[12:13], v[12:13], v[110:111]
	v_pk_add_f32 v[14:15], v[14:15], v[112:113]
	v_pk_add_f32 v[66:67], v[0:1], v[2:3]
	v_pk_add_f32 v[68:69], v[4:5], v[6:7]
	v_pk_add_f32 v[70:71], v[8:9], v[10:11]
	v_pk_add_f32 v[72:73], v[12:13], v[14:15]
	v_pk_add_f32 v[66:67], v[66:67], v[68:69]
	v_pk_add_f32 v[70:71], v[70:71], v[72:73]
	v_pk_add_f32 v[66:67], v[66:67], v[70:71]
	v_add_f32_e32 v66, v66, v67
	s_nop 1
	v_add_f32_dpp v66, v66, v66 row_shr:1 row_mask:0xf bank_mask:0xf bound_ctrl:1
	s_nop 1
	v_add_f32_dpp v66, v66, v66 row_shr:2 row_mask:0xf bank_mask:0xf bound_ctrl:1
	s_nop 1
	v_add_f32_dpp v66, v66, v66 row_shr:4 row_mask:0xf bank_mask:0xf bound_ctrl:1
	s_nop 1
	v_add_f32_dpp v66, v66, v66 row_shr:8 row_mask:0xf bank_mask:0xf bound_ctrl:1
	s_nop 0
	v_readlane_b32 s9, v66, 15
	v_readlane_b32 s10, v66, 31
	v_readlane_b32 s11, v66, 47
	v_readlane_b32 vcc_lo, v66, 63
	s_nop 1
	v_mov_b32_e32 v66, s9
	v_add_f32_e32 v66, s10, v66
	v_add_f32_e32 v66, s11, v66
	v_add_f32_e32 v66, vcc_lo, v66
	v_mul_f32_e32 v116, 0x3a800000, v66
	v_mov_b32_e32 v117, v116
	v_pk_add_f32 v[0:1], v[0:1], v[116:117] neg_lo:[0,1] neg_hi:[0,1]
	v_pk_add_f32 v[2:3], v[2:3], v[116:117] neg_lo:[0,1] neg_hi:[0,1]
	v_pk_add_f32 v[4:5], v[4:5], v[116:117] neg_lo:[0,1] neg_hi:[0,1]
	v_pk_add_f32 v[6:7], v[6:7], v[116:117] neg_lo:[0,1] neg_hi:[0,1]
	v_pk_add_f32 v[8:9], v[8:9], v[116:117] neg_lo:[0,1] neg_hi:[0,1]
	v_pk_add_f32 v[10:11], v[10:11], v[116:117] neg_lo:[0,1] neg_hi:[0,1]
	v_pk_add_f32 v[12:13], v[12:13], v[116:117] neg_lo:[0,1] neg_hi:[0,1]
	v_pk_add_f32 v[14:15], v[14:15], v[116:117] neg_lo:[0,1] neg_hi:[0,1]
	v_pk_mul_f32 v[66:67], v[0:1], v[0:1]
	v_pk_mul_f32 v[68:69], v[2:3], v[2:3]
	v_pk_fma_f32 v[66:67], v[4:5], v[4:5], v[66:67]
	v_pk_fma_f32 v[68:69], v[6:7], v[6:7], v[68:69]
	v_pk_fma_f32 v[66:67], v[8:9], v[8:9], v[66:67]
	v_pk_fma_f32 v[68:69], v[10:11], v[10:11], v[68:69]
	v_pk_fma_f32 v[66:67], v[12:13], v[12:13], v[66:67]
	v_pk_fma_f32 v[68:69], v[14:15], v[14:15], v[68:69]
	v_pk_add_f32 v[66:67], v[66:67], v[68:69]
	v_add_f32_e32 v66, v66, v67
	s_nop 1
	v_add_f32_dpp v66, v66, v66 row_shr:1 row_mask:0xf bank_mask:0xf bound_ctrl:1
	s_nop 1
	v_add_f32_dpp v66, v66, v66 row_shr:2 row_mask:0xf bank_mask:0xf bound_ctrl:1
	s_nop 1
	v_add_f32_dpp v66, v66, v66 row_shr:4 row_mask:0xf bank_mask:0xf bound_ctrl:1
	s_nop 1
	v_add_f32_dpp v66, v66, v66 row_shr:8 row_mask:0xf bank_mask:0xf bound_ctrl:1
	s_nop 0
	v_readlane_b32 s9, v66, 15
	v_readlane_b32 s10, v66, 31
	v_readlane_b32 s11, v66, 47
	v_readlane_b32 vcc_lo, v66, 63
	s_nop 1
	v_mov_b32_e32 v66, s9
	v_add_f32_e32 v66, s10, v66
	v_add_f32_e32 v66, s11, v66
	v_add_f32_e32 v66, vcc_lo, v66
	v_mul_f32_e32 v66, 0x3a800000, v66
	v_add_f32_e32 v66, 0x3727c5ac, v66
	v_rsq_f32_e32 v118, v66
	s_nop 0
	v_mov_b32_e32 v119, v118
	v_pk_mul_f32 v[0:1], v[0:1], v[118:119]
	v_pk_mul_f32 v[2:3], v[2:3], v[118:119]
	v_pk_mul_f32 v[4:5], v[4:5], v[118:119]
	v_pk_mul_f32 v[6:7], v[6:7], v[118:119]
	v_pk_mul_f32 v[8:9], v[8:9], v[118:119]
	v_pk_mul_f32 v[10:11], v[10:11], v[118:119]
	v_pk_mul_f32 v[12:13], v[12:13], v[118:119]
	v_pk_mul_f32 v[14:15], v[14:15], v[118:119]
	v_pk_fma_f32 v[76:77], v[0:1], v[34:35], v[50:51]
	v_pk_fma_f32 v[78:79], v[2:3], v[36:37], v[52:53]
	v_pk_fma_f32 v[80:81], v[4:5], v[38:39], v[54:55]
	v_pk_fma_f32 v[82:83], v[6:7], v[40:41], v[56:57]
	v_pk_fma_f32 v[84:85], v[8:9], v[42:43], v[58:59]
	v_pk_fma_f32 v[86:87], v[10:11], v[44:45], v[60:61]
	v_pk_fma_f32 v[88:89], v[12:13], v[46:47], v[62:63]
	v_pk_fma_f32 v[90:91], v[14:15], v[48:49], v[64:65]
	s_mov_b32 s9, 0x3fb504f3
	v_mov_b32_e32 v120, s9
	v_mov_b32_e32 v121, s9
	v_pk_mul_f32 v[0:1], v[76:77], v[120:121]
	v_pk_mul_f32 v[2:3], v[78:79], v[120:121]
	v_pk_mul_f32 v[4:5], v[80:81], v[120:121]
	v_pk_mul_f32 v[6:7], v[82:83], v[120:121]
	v_pk_mul_f32 v[8:9], v[84:85], v[120:121]
	v_pk_mul_f32 v[10:11], v[86:87], v[120:121]
	v_pk_mul_f32 v[12:13], v[88:89], v[120:121]
	v_pk_mul_f32 v[14:15], v[90:91], v[120:121]
	global_store_dwordx4 v114, v[0:3], s[0:1] offset:0
	global_store_dwordx4 v114, v[4:7], s[0:1] offset:1024
	global_store_dwordx4 v114, v[8:11], s[0:1] offset:2048
	global_store_dwordx4 v114, v[12:15], s[0:1] offset:3072
	v_cvt_pk_bf16_f32 v92, v76, v77
	v_cvt_pk_bf16_f32 v93, v78, v79
	v_cvt_pk_bf16_f32 v94, v80, v81
	v_cvt_pk_bf16_f32 v95, v82, v83
	v_cvt_pk_bf16_f32 v96, v84, v85
	v_cvt_pk_bf16_f32 v97, v86, v87
	v_cvt_pk_bf16_f32 v98, v88, v89
	v_cvt_pk_bf16_f32 v99, v90, v91
	global_store_dwordx2 v115, v[92:93], s[2:3] offset:0
	global_store_dwordx2 v115, v[94:95], s[2:3] offset:512
	global_store_dwordx2 v115, v[96:97], s[2:3] offset:1024
	global_store_dwordx2 v115, v[98:99], s[2:3] offset:1536

; __device__ __forceinline__ int otid() { int t = threadIdx.x; asm volatile("" : "+v"(t)); return t; }
; __device__ __forceinline__ void phase_ln(float* R, const float* __restrict__ g, const float* __restrict__ b, bf16_t* xbf, float samp_scale, const float* __restrict__ part, int nsplit, bool f32_all) {
;   const int tid = otid(), lane = tid & 63, gw = blockIdx.x * 8 + (tid >> 6), nw = gridDim.x * 8;
;   f32x4 gv[4], bv[4];
; #pragma unroll
;   for (int i = 0; i < 4; ++i) { gv[i] = *(const f32x4*)(g + i * 256 + lane * 4); bv[i] = *(const f32x4*)(b + i * 256 + lane * 4); }
;   for (int r = gw; r < MT; r += nw) {
;     float* row = R + (size_t)r * 1024;
;     f32x4 v[4];
; #pragma unroll
;     for (int i = 0; i < 4; ++i) v[i] = *(const f32x4*)(row + i * 256 + lane * 4);
.Lln1_orig:
	v_readlane_b32 s0, v255, 22
	v_readlane_b32 s6, v254, 2
	v_readlane_b32 s1, v255, 23
	v_readlane_b32 s7, v254, 3
	s_lshl_b32 s8, s0, 10
	v_readlane_b32 s0, v255, 20
	v_mov_b32_e32 v34, v244
	s_waitcnt lgkmcnt(0)
	s_barrier
	v_readlane_b32 s0, v254, 15
	v_ashrrev_i32_e32 v0, 6, v34
	v_readlane_b32 s1, v255, 21
	v_add_u32_e32 v50, s0, v0
	s_mov_b32 s0, 0x8200
	s_mov_b32 s9, s1
	v_cmp_gt_i32_e32 vcc, s0, v50
	s_and_saveexec_b64 s[4:5], vcc
	s_cbranch_execz .LBB0_3733
	s_load_dwordx4 s[0:3], s[6:7], 0x78
	s_lshl_b64 s[10:11], s[8:9], 2
	v_lshlrev_b32_e32 v0, 4, v34
	v_and_b32_e32 v16, 0x3f0, v0
	v_xor_b32_e32 v35, 32, v252
	s_waitcnt lgkmcnt(0)
	s_add_u32 s0, s0, s10
	s_addc_u32 s1, s1, s11
	s_add_u32 s2, s2, s10
	global_load_dwordx4 v[0:3], v16, s[0:1]
	s_addc_u32 s3, s3, s11
	global_load_dwordx4 v[4:7], v16, s[0:1] offset:1024
	global_load_dwordx4 v[8:11], v16, s[2:3]
	global_load_dwordx4 v[12:15], v16, s[2:3] offset:1024
	global_load_dwordx4 v[18:21], v16, s[0:1] offset:2048
	global_load_dwordx4 v[22:25], v16, s[0:1] offset:3072
	global_load_dwordx4 v[26:29], v16, s[2:3] offset:2048
	global_load_dwordx4 v[30:33], v16, s[2:3] offset:3072
	s_load_dwordx4 s[0:3], s[6:7], 0xa8
	s_mov_b64 s[6:7], 0x1e482000
	v_ashrrev_i32_e32 v51, 31, v50
	s_waitcnt lgkmcnt(0)
	v_lshl_add_u64 v[36:37], s[2:3], 0, v[16:17]
	v_and_b32_e32 v16, 64, v252
	v_add_u32_e32 v16, 64, v16
	v_cmp_lt_i32_e32 vcc, v35, v16
	v_lshl_add_u64 v[52:53], v[36:37], 0, s[6:7]
	v_lshlrev_b64 v[36:37], 11, v[50:51]
	v_cndmask_b32_e32 v35, v252, v35, vcc
	v_lshlrev_b32_e32 v60, 2, v35
	v_xor_b32_e32 v35, 16, v252
	v_cmp_lt_i32_e32 vcc, v35, v16
	s_nop 1
	v_cndmask_b32_e32 v35, v252, v35, vcc
	v_lshlrev_b32_e32 v61, 2, v35
	v_xor_b32_e32 v35, 8, v252
	v_cmp_lt_i32_e32 vcc, v35, v16
	s_nop 1
	v_cndmask_b32_e32 v35, v252, v35, vcc
	v_lshlrev_b32_e32 v62, 2, v35
	v_xor_b32_e32 v35, 4, v252
	v_cmp_lt_i32_e32 vcc, v35, v16
	s_nop 1
	v_cndmask_b32_e32 v35, v252, v35, vcc
	v_lshlrev_b32_e32 v63, 2, v35
	v_xor_b32_e32 v35, 2, v252
	v_cmp_lt_i32_e32 vcc, v35, v16
	s_nop 1
	v_cndmask_b32_e32 v35, v252, v35, vcc
	v_lshlrev_b32_e32 v64, 2, v35
	v_xor_b32_e32 v35, 1, v252
	v_cmp_lt_i32_e32 vcc, v35, v16
	s_nop 1
	v_cndmask_b32_e32 v16, v252, v35, vcc
	v_lshlrev_b32_e32 v65, 2, v16
	v_and_b32_e32 v16, 63, v34
	v_lshl_or_b32 v36, v16, 3, v36
	v_lshl_add_u64 v[34:35], s[2:3], 0, v[36:37]
	s_mov_b64 s[2:3], 0x39c0000
	v_lshl_add_u64 v[54:55], v[34:35], 0, s[2:3]
	v_lshlrev_b64 v[34:35], 12, v[50:51]
	v_lshl_or_b32 v34, v16, 4, v34
	v_lshl_add_u64 v[56:57], s[0:1], 0, v[34:35]
	s_mov_b64 s[2:3], 0
	s_branch .LBB0_3723

; #define LAS __attribute__((address_space(3)))
; template <class T> __device__ __forceinline__ T launder(T p) { asm volatile("" : "+s"(p)); return p; }
; __device__ __forceinline__ unsigned xb_ld(unsigned* p) { return __hip_atomic_load(p, __ATOMIC_RELAXED, __HIP_MEMORY_SCOPE_AGENT); }
; __device__ __forceinline__ unsigned xb_xcc_id() { return (unsigned)__builtin_amdgcn_s_getreg((3 << 11) | 20) & 0xFu; }
; __device__ __forceinline__ void xcd_barrier_complete(unsigned* bar, unsigned x, unsigned& nloc, unsigned& nx) {
;   const unsigned G = gridDim.x * gridDim.y * gridDim.z;
;   unsigned sum, cnt, mine, sp = 0u;
;   for (;;) {
;     sum = 0u; cnt = 0u; mine = 0u;
; #pragma unroll
;     for (unsigned j = 0; j < 16; ++j) { const unsigned c = xb_ld(&bar[XB_XCNT(j)]); sum += c; cnt += (c > 0u) ? 1u : 0u; mine = (j == x) ? c : mine; }
; __device__ __forceinline__ void xcd_barrier(KP kp, volatile LAS unsigned* st) {
;   asm volatile("s_waitcnt vmcnt(0)" ::: "memory");
;   __syncthreads();
;   if (threadIdx.x == 0) {
;     unsigned* bar = (unsigned*)(launder(kp)->ws + W_BAR);
;     const unsigned x = xb_xcc_id();
;     __builtin_amdgcn_s_waitcnt(0);
;     unsigned nloc = st[0], nx = st[1];
;     if (nloc == 0u) { xcd_barrier_complete(bar, x, nloc, nx); st[0] = nloc; st[1] = nx; }
.Lln1_end:
	s_waitcnt vmcnt(0)
	s_barrier
	s_mov_b64 s[0:1], exec
	v_readlane_b32 s2, v254, 4
	v_readlane_b32 s3, v254, 5
	s_and_b64 s[2:3], s[0:1], s[2:3]
	s_mov_b64 exec, s[2:3]
	s_cbranch_execz .LBB0_3785
	v_readlane_b32 s2, v254, 2
	v_readlane_b32 s3, v254, 3
	v_readlane_b32 s5, v254, 49
	s_load_dwordx2 s[2:3], s[2:3], 0xb0
	s_getreg_b32 s4, hwreg(HW_REG_XCC_ID, 0, 4)
	v_mov_b32_e32 v0, s5
	s_waitcnt vmcnt(0) expcnt(0) lgkmcnt(0)
	ds_read_b32 v2, v0
	v_readlane_b32 s5, v254, 50
	s_and_b32 s52, s4, 15
	s_waitcnt lgkmcnt(0)
	v_cmp_ne_u32_e32 vcc, 0, v2
	v_mov_b32_e32 v0, s5
	ds_read_b32 v0, v0
	s_cbranch_vccnz .LBB0_3749
	s_add_u32 s4, s2, 0x1f482200
	s_addc_u32 s5, s3, 0
	s_add_u32 s6, s2, 0x1f482400
	s_addc_u32 s7, s3, 0
	s_add_u32 s10, s2, 0x1f482500
	s_addc_u32 s11, s3, 0
	s_add_u32 s12, s2, 0x1f482600
	s_addc_u32 s13, s3, 0
	s_add_u32 s14, s2, 0x1f482700
	s_addc_u32 s15, s3, 0
	s_add_u32 s20, s2, 0x1f482800
	s_addc_u32 s21, s3, 0
	s_add_u32 s22, s2, 0x1f482900
	s_addc_u32 s23, s3, 0
	s_add_u32 s24, s2, 0x1f482a00
	s_addc_u32 s25, s3, 0
	s_add_u32 s26, s2, 0x1f482b00
	s_addc_u32 s27, s3, 0
	s_add_u32 s28, s2, 0x1f482c00
	s_addc_u32 s29, s3, 0
	s_add_u32 s30, s2, 0x1f482d00
	s_addc_u32 s31, s3, 0
	s_add_u32 s34, s2, 0x1f482e00
	s_addc_u32 s35, s3, 0
	s_add_u32 s36, s2, 0x1f482f00
	s_addc_u32 s37, s3, 0
	s_add_u32 s38, s2, 0x1f483000
	s_addc_u32 s39, s3, 0
	s_add_u32 s40, s2, 0x1f483100
	s_addc_u32 s41, s3, 0
	s_add_u32 s42, s2, 0x1f483200
	s_addc_u32 s43, s3, 0
	s_add_u32 s44, s2, 0x1f483300
	s_addc_u32 s45, s3, 0
	s_mov_b32 s53, 1
	s_branch .LBB0_3737

; __device__ __forceinline__ int otid() { int t = threadIdx.x; asm volatile("" : "+v"(t)); return t; }
; __device__ __forceinline__ void phase_ln(float* R, const float* __restrict__ g, const float* __restrict__ b, bf16_t* xbf, float samp_scale, const float* __restrict__ part, int nsplit, bool f32_all) {
;   const int tid = otid(), lane = tid & 63, gw = blockIdx.x * 8 + (tid >> 6), nw = gridDim.x * 8;
;   f32x4 gv[4], bv[4];
; #pragma unroll
;   for (int i = 0; i < 4; ++i) { gv[i] = *(const f32x4*)(g + i * 256 + lane * 4); bv[i] = *(const f32x4*)(b + i * 256 + lane * 4); }
;   for (int r = gw; r < MT; r += nw) {
;     float* row = R + (size_t)r * 1024;
;     f32x4 v[4];
; #pragma unroll
;     for (int i = 0; i < 4; ++i) v[i] = *(const f32x4*)(row + i * 256 + lane * 4);
;     if (r >= MP) {
;       for (int sp = 0; sp < nsplit; ++sp) {
;         const float* prow = part + ((size_t)sp * MS + (r - MP)) * 1024;
; #pragma unroll
;         for (int i = 0; i < 4; ++i) v[i] = v[i] + *(const f32x4*)(prow + i * 256 + lane * 4);
;       }
;     }
;     float s = 0.f;
; #pragma unroll
;     for (int i = 0; i < 4; ++i) s += v[i][0] + v[i][1] + v[i][2] + v[i][3];
; #pragma unroll
;     for (int o = 32; o >= 1; o >>= 1) s += __shfl_xor(s, o);
;     const float mean = s * (1.f / 1024.f);
;     float ss = 0.f;
; #pragma unroll
;     for (int i = 0; i < 4; ++i) { v[i] = v[i] - mean; ss += v[i][0] * v[i][0] + v[i][1] * v[i][1] + v[i][2] * v[i][2] + v[i][3] * v[i][3]; }
; #pragma unroll
;     for (int o = 32; o >= 1; o >>= 1) ss += __shfl_xor(ss, o);
;     const float rstd = rsqrtf(ss * (1.f / 1024.f) + LN_EPS);
; #pragma unroll
;     for (int i = 0; i < 4; ++i) {
;       const f32x4 y = v[i] * rstd * gv[i] + bv[i];
;       if (r >= MP) *(f32x4*)(row + i * 256 + lane * 4) = y * samp_scale;
;       else if (f32_all) *(f32x4*)(row + i * 256 + lane * 4) = y;
;       if (xbf) {
;         u32x2 wv;
;         wv[0] = cvt_pk_bf16(y[0], y[1]); wv[1] = cvt_pk_bf16(y[2], y[3]);
;         *(u32x2*)(xbf + (size_t)r * 1024 + i * 256 + lane * 4) = wv;
;       }
;     }
.LBB0_3944:
	s_or_b64 exec, exec, s[0:1]
	v_readlane_b32 s0, v254, 51
	s_nop 0
	s_cmp_lg_u32 s0, 0
	s_cbranch_scc1 .Lln2_orig
	v_readlane_b32 s6, v254, 2
	v_readlane_b32 s7, v254, 3
	v_readlane_b32 s8, v255, 22
	s_waitcnt lgkmcnt(0)
	s_barrier
	s_load_dwordx4 s[0:3], s[6:7], 0x98
	s_load_dwordx4 s[4:7], s[6:7], 0xa8
	v_readlane_b32 s9, v254, 15
	v_readfirstlane_b32 s10, v244
	v_lshlrev_b32_e32 v114, 4, v252
	v_lshlrev_b32_e32 v115, 3, v252
	s_lshr_b32 s10, s10, 6
	s_add_i32 s9, s9, s10
	s_lshl_b32 s11, s8, 12
	s_waitcnt lgkmcnt(0)
	s_add_u32 s0, s0, s11
	s_addc_u32 s1, s1, 0
	s_add_u32 s2, s2, s11
	s_addc_u32 s3, s3, 0
	global_load_dwordx4 v[34:37], v114, s[0:1] offset:0
	global_load_dwordx4 v[38:41], v114, s[0:1] offset:1024
	global_load_dwordx4 v[42:45], v114, s[0:1] offset:2048
	global_load_dwordx4 v[46:49], v114, s[0:1] offset:3072
	global_load_dwordx4 v[50:53], v114, s[2:3] offset:0
	global_load_dwordx4 v[54:57], v114, s[2:3] offset:1024
	global_load_dwordx4 v[58:61], v114, s[2:3] offset:2048
	global_load_dwordx4 v[62:65], v114, s[2:3] offset:3072
	s_lshl_b32 s11, s9, 12
	s_add_u32 s0, s4, s11
	s_addc_u32 s1, s5, 0
	s_lshl_b32 s11, s9, 11
	s_add_u32 s11, s11, 0x39c0000
	s_add_u32 s2, s6, s11
	s_addc_u32 s3, s7, 0
	global_load_dwordx4 v[0:3], v114, s[0:1] offset:0
	global_load_dwordx4 v[4:7], v114, s[0:1] offset:1024
	global_load_dwordx4 v[8:11], v114, s[0:1] offset:2048
	global_load_dwordx4 v[12:15], v114, s[0:1] offset:3072
	s_add_u32 s0, s0, 0x800000
	s_addc_u32 s1, s1, 0
	global_load_dwordx4 v[18:21], v114, s[0:1] offset:0
	global_load_dwordx4 v[22:25], v114, s[0:1] offset:1024
	global_load_dwordx4 v[26:29], v114, s[0:1] offset:2048
	global_load_dwordx4 v[30:33], v114, s[0:1] offset:3072
	s_waitcnt vmcnt(4)
	v_pk_add_f32 v[66:67], v[0:1], v[2:3]
	v_pk_add_f32 v[68:69], v[4:5], v[6:7]
	v_pk_add_f32 v[70:71], v[8:9], v[10:11]
	v_pk_add_f32 v[72:73], v[12:13], v[14:15]
	v_pk_add_f32 v[66:67], v[66:67], v[68:69]
	v_pk_add_f32 v[70:71], v[70:71], v[72:73]
	v_pk_add_f32 v[66:67], v[66:67], v[70:71]
	v_add_f32_e32 v66, v66, v67
	s_nop 1
	v_add_f32_dpp v66, v66, v66 row_shr:1 row_mask:0xf bank_mask:0xf bound_ctrl:1
	s_nop 1
	v_add_f32_dpp v66, v66, v66 row_shr:2 row_mask:0xf bank_mask:0xf bound_ctrl:1
	s_nop 1
	v_add_f32_dpp v66, v66, v66 row_shr:4 row_mask:0xf bank_mask:0xf bound_ctrl:1
	s_nop 1
	v_add_f32_dpp v66, v66, v66 row_shr:8 row_mask:0xf bank_mask:0xf bound_ctrl:1
	s_nop 0
	v_readlane_b32 s9, v66, 15
	v_readlane_b32 s10, v66, 31
	v_readlane_b32 s11, v66, 47
	v_readlane_b32 vcc_lo, v66, 63
	s_nop 1
	v_mov_b32_e32 v66, s9
	v_add_f32_e32 v66, s10, v66
	v_add_f32_e32 v66, s11, v66
	v_add_f32_e32 v66, vcc_lo, v66
	v_mul_f32_e32 v116, 0x3a800000, v66
	v_mov_b32_e32 v117, v116
	v_pk_add_f32 v[0:1], v[0:1], v[116:117] neg_lo:[0,1] neg_hi:[0,1]
	v_pk_add_f32 v[2:3], v[2:3], v[116:117] neg_lo:[0,1] neg_hi:[0,1]
	v_pk_add_f32 v[4:5], v[4:5], v[116:117] neg_lo:[0,1] neg_hi:[0,1]
	v_pk_add_f32 v[6:7], v[6:7], v[116:117] neg_lo:[0,1] neg_hi:[0,1]
	v_pk_add_f32 v[8:9], v[8:9], v[116:117] neg_lo:[0,1] neg_hi:[0,1]
	v_pk_add_f32 v[10:11], v[10:11], v[116:117] neg_lo:[0,1] neg_hi:[0,1]
	v_pk_add_f32 v[12:13], v[12:13], v[116:117] neg_lo:[0,1] neg_hi:[0,1]
	v_pk_add_f32 v[14:15], v[14:15], v[116:117] neg_lo:[0,1] neg_hi:[0,1]
	v_pk_mul_f32 v[66:67], v[0:1], v[0:1]
	v_pk_mul_f32 v[68:69], v[2:3], v[2:3]
	v_pk_fma_f32 v[66:67], v[4:5], v[4:5], v[66:67]
	v_pk_fma_f32 v[68:69], v[6:7], v[6:7], v[68:69]
	v_pk_fma_f32 v[66:67], v[8:9], v[8:9], v[66:67]
	v_pk_fma_f32 v[68:69], v[10:11], v[10:11], v[68:69]
	v_pk_fma_f32 v[66:67], v[12:13], v[12:13], v[66:67]
	v_pk_fma_f32 v[68:69], v[14:15], v[14:15], v[68:69]
	v_pk_add_f32 v[66:67], v[66:67], v[68:69]
	v_add_f32_e32 v66, v66, v67
	s_nop 1
	v_add_f32_dpp v66, v66, v66 row_shr:1 row_mask:0xf bank_mask:0xf bound_ctrl:1
	s_nop 1
	v_add_f32_dpp v66, v66, v66 row_shr:2 row_mask:0xf bank_mask:0xf bound_ctrl:1
	s_nop 1
	v_add_f32_dpp v66, v66, v66 row_shr:4 row_mask:0xf bank_mask:0xf bound_ctrl:1
	s_nop 1
	v_add_f32_dpp v66, v66, v66 row_shr:8 row_mask:0xf bank_mask:0xf bound_ctrl:1
	s_nop 0
	v_readlane_b32 s9, v66, 15
	v_readlane_b32 s10, v66, 31
	v_readlane_b32 s11, v66, 47
	v_readlane_b32 vcc_lo, v66, 63
	s_nop 1
	v_mov_b32_e32 v66, s9
	v_add_f32_e32 v66, s10, v66
	v_add_f32_e32 v66, s11, v66
	v_add_f32_e32 v66, vcc_lo, v66
	v_mul_f32_e32 v66, 0x3a800000, v66
	v_add_f32_e32 v66, 0x3727c5ac, v66
	v_rsq_f32_e32 v118, v66
	s_nop 0
	v_mov_b32_e32 v119, v118
	v_pk_mul_f32 v[0:1], v[0:1], v[118:119]
	v_pk_mul_f32 v[2:3], v[2:3], v[118:119]
	v_pk_mul_f32 v[4:5], v[4:5], v[118:119]
	v_pk_mul_f32 v[6:7], v[6:7], v[118:119]
	v_pk_mul_f32 v[8:9], v[8:9], v[118:119]
	v_pk_mul_f32 v[10:11], v[10:11], v[118:119]
	v_pk_mul_f32 v[12:13], v[12:13], v[118:119]
	v_pk_mul_f32 v[14:15], v[14:15], v[118:119]
	v_pk_fma_f32 v[76:77], v[0:1], v[34:35], v[50:51]
	v_pk_fma_f32 v[78:79], v[2:3], v[36:37], v[52:53]
	v_pk_fma_f32 v[80:81], v[4:5], v[38:39], v[54:55]
	v_pk_fma_f32 v[82:83], v[6:7], v[40:41], v[56:57]
	v_pk_fma_f32 v[84:85], v[8:9], v[42:43], v[58:59]
	v_pk_fma_f32 v[86:87], v[10:11], v[44:45], v[60:61]
	v_pk_fma_f32 v[88:89], v[12:13], v[46:47], v[62:63]
	v_pk_fma_f32 v[90:91], v[14:15], v[48:49], v[64:65]
	s_cmp_lg_u32 s8, 0
	s_cbranch_scc1 .Lln2_f32_0
	v_cvt_pk_bf16_f32 v92, v76, v77
	v_cvt_pk_bf16_f32 v93, v78, v79
	v_cvt_pk_bf16_f32 v94, v80, v81
	v_cvt_pk_bf16_f32 v95, v82, v83
	v_cvt_pk_bf16_f32 v96, v84, v85
	v_cvt_pk_bf16_f32 v97, v86, v87
	v_cvt_pk_bf16_f32 v98, v88, v89
	v_cvt_pk_bf16_f32 v99, v90, v91
	global_store_dwordx2 v115, v[92:93], s[2:3] offset:0
	global_store_dwordx2 v115, v[94:95], s[2:3] offset:512
	global_store_dwordx2 v115, v[96:97], s[2:3] offset:1024
	global_store_dwordx2 v115, v[98:99], s[2:3] offset:1536
	s_branch .Lln2_st_0
; __device__ __forceinline__ void phase_ln(float* R, const float* __restrict__ g, const float* __restrict__ b, bf16_t* xbf, float samp_scale, const float* __restrict__ part, int nsplit, bool f32_all) {
;     ...
;     float s = 0.f;
; #pragma unroll
;     for (int i = 0; i < 4; ++i) s += v[i][0] + v[i][1] + v[i][2] + v[i][3];
; #pragma unroll
;     for (int o = 32; o >= 1; o >>= 1) s += __shfl_xor(s, o);
;     const float mean = s * (1.f / 1024.f);
;     float ss = 0.f;
; #pragma unroll
;     for (int i = 0; i < 4; ++i) { v[i] = v[i] - mean; ss += v[i][0] * v[i][0] + v[i][1] * v[i][1] + v[i][2] * v[i][2] + v[i][3] * v[i][3]; }
; #pragma unroll
;     for (int o = 32; o >= 1; o >>= 1) ss += __shfl_xor(ss, o);
;     const float rstd = rsqrtf(ss * (1.f / 1024.f) + LN_EPS);
; #pragma unroll
;     for (int i = 0; i < 4; ++i) {
;       const f32x4 y = v[i] * rstd * gv[i] + bv[i];
;       if (r >= MP) *(f32x4*)(row + i * 256 + lane * 4) = y * samp_scale;
;       else if (f32_all) *(f32x4*)(row + i * 256 + lane * 4) = y;
;       if (xbf) {
;         u32x2 wv;
;         wv[0] = cvt_pk_bf16(y[0], y[1]); wv[1] = cvt_pk_bf16(y[2], y[3]);
;         *(u32x2*)(xbf + (size_t)r * 1024 + i * 256 + lane * 4) = wv;
;       }
;     }
.Lln2_f32_0:
	s_sub_u32 s10, s0, 0x800000
	s_subb_u32 s11, s1, 0
	global_store_dwordx4 v114, v[76:79], s[10:11] offset:0
	global_store_dwordx4 v114, v[80:83], s[10:11] offset:1024
	global_store_dwordx4 v114, v[84:87], s[10:11] offset:2048
	global_store_dwordx4 v114, v[88:91], s[10:11] offset:3072
.Lln2_st_0:
	s_add_u32 s2, s2, 0x400000
	s_addc_u32 s3, s3, 0
	s_add_u32 s0, s0, 0x800000
	s_addc_u32 s1, s1, 0
	global_load_dwordx4 v[0:3], v114, s[0:1] offset:0
	global_load_dwordx4 v[4:7], v114, s[0:1] offset:1024
	global_load_dwordx4 v[8:11], v114, s[0:1] offset:2048
	global_load_dwordx4 v[12:15], v114, s[0:1] offset:3072
	s_waitcnt vmcnt(8)
	v_pk_add_f32 v[66:67], v[18:19], v[20:21]
	v_pk_add_f32 v[68:69], v[22:23], v[24:25]
	v_pk_add_f32 v[70:71], v[26:27], v[28:29]
	v_pk_add_f32 v[72:73], v[30:31], v[32:33]
	v_pk_add_f32 v[66:67], v[66:67], v[68:69]
	v_pk_add_f32 v[70:71], v[70:71], v[72:73]
	v_pk_add_f32 v[66:67], v[66:67], v[70:71]
	v_add_f32_e32 v66, v66, v67
	s_nop 1
	v_add_f32_dpp v66, v66, v66 row_shr:1 row_mask:0xf bank_mask:0xf bound_ctrl:1
	s_nop 1
	v_add_f32_dpp v66, v66, v66 row_shr:2 row_mask:0xf bank_mask:0xf bound_ctrl:1
	s_nop 1
	v_add_f32_dpp v66, v66, v66 row_shr:4 row_mask:0xf bank_mask:0xf bound_ctrl:1
	s_nop 1
	v_add_f32_dpp v66, v66, v66 row_shr:8 row_mask:0xf bank_mask:0xf bound_ctrl:1
	s_nop 0
	v_readlane_b32 s9, v66, 15
	v_readlane_b32 s10, v66, 31
	v_readlane_b32 s11, v66, 47
	v_readlane_b32 vcc_lo, v66, 63
	s_nop 1
	v_mov_b32_e32 v66, s9
	v_add_f32_e32 v66, s10, v66
	v_add_f32_e32 v66, s11, v66
	v_add_f32_e32 v66, vcc_lo, v66
	v_mul_f32_e32 v116, 0x3a800000, v66
	v_mov_b32_e32 v117, v116
	v_pk_add_f32 v[18:19], v[18:19], v[116:117] neg_lo:[0,1] neg_hi:[0,1]
	v_pk_add_f32 v[20:21], v[20:21], v[116:117] neg_lo:[0,1] neg_hi:[0,1]
	v_pk_add_f32 v[22:23], v[22:23], v[116:117] neg_lo:[0,1] neg_hi:[0,1]
	v_pk_add_f32 v[24:25], v[24:25], v[116:117] neg_lo:[0,1] neg_hi:[0,1]
	v_pk_add_f32 v[26:27], v[26:27], v[116:117] neg_lo:[0,1] neg_hi:[0,1]
	v_pk_add_f32 v[28:29], v[28:29], v[116:117] neg_lo:[0,1] neg_hi:[0,1]
	v_pk_add_f32 v[30:31], v[30:31], v[116:117] neg_lo:[0,1] neg_hi:[0,1]
	v_pk_add_f32 v[32:33], v[32:33], v[116:117] neg_lo:[0,1] neg_hi:[0,1]
	v_pk_mul_f32 v[66:67], v[18:19], v[18:19]
	v_pk_mul_f32 v[68:69], v[20:21], v[20:21]
	v_pk_fma_f32 v[66:67], v[22:23], v[22:23], v[66:67]
	v_pk_fma_f32 v[68:69], v[24:25], v[24:25], v[68:69]
	v_pk_fma_f32 v[66:67], v[26:27], v[26:27], v[66:67]
	v_pk_fma_f32 v[68:69], v[28:29], v[28:29], v[68:69]
	v_pk_fma_f32 v[66:67], v[30:31], v[30:31], v[66:67]
	v_pk_fma_f32 v[68:69], v[32:33], v[32:33], v[68:69]
	v_pk_add_f32 v[66:67], v[66:67], v[68:69]
	v_add_f32_e32 v66, v66, v67
	s_nop 1
	v_add_f32_dpp v66, v66, v66 row_shr:1 row_mask:0xf bank_mask:0xf bound_ctrl:1
	s_nop 1
	v_add_f32_dpp v66, v66, v66 row_shr:2 row_mask:0xf bank_mask:0xf bound_ctrl:1
	s_nop 1
	v_add_f32_dpp v66, v66, v66 row_shr:4 row_mask:0xf bank_mask:0xf bound_ctrl:1
	s_nop 1
	v_add_f32_dpp v66, v66, v66 row_shr:8 row_mask:0xf bank_mask:0xf bound_ctrl:1
	s_nop 0
	v_readlane_b32 s9, v66, 15
	v_readlane_b32 s10, v66, 31
	v_readlane_b32 s11, v66, 47
	v_readlane_b32 vcc_lo, v66, 63
	s_nop 1
	v_mov_b32_e32 v66, s9
	v_add_f32_e32 v66, s10, v66
	v_add_f32_e32 v66, s11, v66
	v_add_f32_e32 v66, vcc_lo, v66
	v_mul_f32_e32 v66, 0x3a800000, v66
	v_add_f32_e32 v66, 0x3727c5ac, v66
	v_rsq_f32_e32 v118, v66
	s_nop 0
	v_mov_b32_e32 v119, v118
	v_pk_mul_f32 v[18:19], v[18:19], v[118:119]
	v_pk_mul_f32 v[20:21], v[20:21], v[118:119]
	v_pk_mul_f32 v[22:23], v[22:23], v[118:119]
	v_pk_mul_f32 v[24:25], v[24:25], v[118:119]
	v_pk_mul_f32 v[26:27], v[26:27], v[118:119]
	v_pk_mul_f32 v[28:29], v[28:29], v[118:119]
	v_pk_mul_f32 v[30:31], v[30:31], v[118:119]
	v_pk_mul_f32 v[32:33], v[32:33], v[118:119]
	v_pk_fma_f32 v[76:77], v[18:19], v[34:35], v[50:51]
	v_pk_fma_f32 v[78:79], v[20:21], v[36:37], v[52:53]
	v_pk_fma_f32 v[80:81], v[22:23], v[38:39], v[54:55]
	v_pk_fma_f32 v[82:83], v[24:25], v[40:41], v[56:57]
	v_pk_fma_f32 v[84:85], v[26:27], v[42:43], v[58:59]
	v_pk_fma_f32 v[86:87], v[28:29], v[44:45], v[60:61]
	v_pk_fma_f32 v[88:89], v[30:31], v[46:47], v[62:63]
	v_pk_fma_f32 v[90:91], v[32:33], v[48:49], v[64:65]
	s_cmp_lg_u32 s8, 0
	s_cbranch_scc1 .Lln2_f32_1
	v_cvt_pk_bf16_f32 v92, v76, v77
	v_cvt_pk_bf16_f32 v93, v78, v79
	v_cvt_pk_bf16_f32 v94, v80, v81
	v_cvt_pk_bf16_f32 v95, v82, v83
	v_cvt_pk_bf16_f32 v96, v84, v85
	v_cvt_pk_bf16_f32 v97, v86, v87
	v_cvt_pk_bf16_f32 v98, v88, v89
	v_cvt_pk_bf16_f32 v99, v90, v91
	global_store_dwordx2 v115, v[92:93], s[2:3] offset:0
	global_store_dwordx2 v115, v[94:95], s[2:3] offset:512
	global_store_dwordx2 v115, v[96:97], s[2:3] offset:1024
	global_store_dwordx2 v115, v[98:99], s[2:3] offset:1536
	s_branch .Lln2_st_1

; __device__ __forceinline__ void phase_ln(float* R, const float* __restrict__ g, const float* __restrict__ b, bf16_t* xbf, float samp_scale, const float* __restrict__ part, int nsplit, bool f32_all) {
;     ...
;   for (int r = gw; r < MT; r += nw) {
;     float* row = R + (size_t)r * 1024;
;     f32x4 v[4];
; #pragma unroll
;     for (int i = 0; i < 4; ++i) v[i] = *(const f32x4*)(row + i * 256 + lane * 4);
;     if (r >= MP) {
;       for (int sp = 0; sp < nsplit; ++sp) {
;         const float* prow = part + ((size_t)sp * MS + (r - MP)) * 1024;
; #pragma unroll
;         for (int i = 0; i < 4; ++i) v[i] = v[i] + *(const f32x4*)(prow + i * 256 + lane * 4);
;       }
;     }
;     float s = 0.f;
; #pragma unroll
;     for (int i = 0; i < 4; ++i) s += v[i][0] + v[i][1] + v[i][2] + v[i][3];
; #pragma unroll
;     for (int o = 32; o >= 1; o >>= 1) s += __shfl_xor(s, o);
;     const float mean = s * (1.f / 1024.f);
;     float ss = 0.f;
; #pragma unroll
;     for (int i = 0; i < 4; ++i) { v[i] = v[i] - mean; ss += v[i][0] * v[i][0] + v[i][1] * v[i][1] + v[i][2] * v[i][2] + v[i][3] * v[i][3]; }
; #pragma unroll
;     for (int o = 32; o >= 1; o >>= 1) ss += __shfl_xor(ss, o);
;     const float rstd = rsqrtf(ss * (1.f / 1024.f) + LN_EPS);
; #pragma unroll
;     for (int i = 0; i < 4; ++i) {
;       const f32x4 y = v[i] * rstd * gv[i] + bv[i];
;       if (r >= MP) *(f32x4*)(row + i * 256 + lane * 4) = y * samp_scale;
;       else if (f32_all) *(f32x4*)(row + i * 256 + lane * 4) = y;
;       if (xbf) {
;         u32x2 wv;
;         wv[0] = cvt_pk_bf16(y[0], y[1]); wv[1] = cvt_pk_bf16(y[2], y[3]);
;         *(u32x2*)(xbf + (size_t)r * 1024 + i * 256 + lane * 4) = wv;
;       }
;     }
.Lln2_st_1:
	s_add_u32 s2, s2, 0x400000
	s_addc_u32 s3, s3, 0
	s_add_u32 s0, s0, 0x800000
	s_addc_u32 s1, s1, 0
	global_load_dwordx4 v[18:21], v114, s[0:1] offset:0
	global_load_dwordx4 v[22:25], v114, s[0:1] offset:1024
	global_load_dwordx4 v[26:29], v114, s[0:1] offset:2048
	global_load_dwordx4 v[30:33], v114, s[0:1] offset:3072
	s_waitcnt vmcnt(8)
	v_pk_add_f32 v[66:67], v[0:1], v[2:3]
	v_pk_add_f32 v[68:69], v[4:5], v[6:7]
	v_pk_add_f32 v[70:71], v[8:9], v[10:11]
	v_pk_add_f32 v[72:73], v[12:13], v[14:15]
	v_pk_add_f32 v[66:67], v[66:67], v[68:69]
	v_pk_add_f32 v[70:71], v[70:71], v[72:73]
	v_pk_add_f32 v[66:67], v[66:67], v[70:71]
	v_add_f32_e32 v66, v66, v67
	s_nop 1
	v_add_f32_dpp v66, v66, v66 row_shr:1 row_mask:0xf bank_mask:0xf bound_ctrl:1
	s_nop 1
	v_add_f32_dpp v66, v66, v66 row_shr:2 row_mask:0xf bank_mask:0xf bound_ctrl:1
	s_nop 1
	v_add_f32_dpp v66, v66, v66 row_shr:4 row_mask:0xf bank_mask:0xf bound_ctrl:1
	s_nop 1
	v_add_f32_dpp v66, v66, v66 row_shr:8 row_mask:0xf bank_mask:0xf bound_ctrl:1
	s_nop 0
	v_readlane_b32 s9, v66, 15
	v_readlane_b32 s10, v66, 31
	v_readlane_b32 s11, v66, 47
	v_readlane_b32 vcc_lo, v66, 63
	s_nop 1
	v_mov_b32_e32 v66, s9
	v_add_f32_e32 v66, s10, v66
	v_add_f32_e32 v66, s11, v66
	v_add_f32_e32 v66, vcc_lo, v66
	v_mul_f32_e32 v116, 0x3a800000, v66
	v_mov_b32_e32 v117, v116
	v_pk_add_f32 v[0:1], v[0:1], v[116:117] neg_lo:[0,1] neg_hi:[0,1]
	v_pk_add_f32 v[2:3], v[2:3], v[116:117] neg_lo:[0,1] neg_hi:[0,1]
	v_pk_add_f32 v[4:5], v[4:5], v[116:117] neg_lo:[0,1] neg_hi:[0,1]
	v_pk_add_f32 v[6:7], v[6:7], v[116:117] neg_lo:[0,1] neg_hi:[0,1]
	v_pk_add_f32 v[8:9], v[8:9], v[116:117] neg_lo:[0,1] neg_hi:[0,1]
	v_pk_add_f32 v[10:11], v[10:11], v[116:117] neg_lo:[0,1] neg_hi:[0,1]
	v_pk_add_f32 v[12:13], v[12:13], v[116:117] neg_lo:[0,1] neg_hi:[0,1]
	v_pk_add_f32 v[14:15], v[14:15], v[116:117] neg_lo:[0,1] neg_hi:[0,1]
	v_pk_mul_f32 v[66:67], v[0:1], v[0:1]
	v_pk_mul_f32 v[68:69], v[2:3], v[2:3]
	v_pk_fma_f32 v[66:67], v[4:5], v[4:5], v[66:67]
	v_pk_fma_f32 v[68:69], v[6:7], v[6:7], v[68:69]
	v_pk_fma_f32 v[66:67], v[8:9], v[8:9], v[66:67]
	v_pk_fma_f32 v[68:69], v[10:11], v[10:11], v[68:69]
	v_pk_fma_f32 v[66:67], v[12:13], v[12:13], v[66:67]
	v_pk_fma_f32 v[68:69], v[14:15], v[14:15], v[68:69]
	v_pk_add_f32 v[66:67], v[66:67], v[68:69]
	v_add_f32_e32 v66, v66, v67
	s_nop 1
	v_add_f32_dpp v66, v66, v66 row_shr:1 row_mask:0xf bank_mask:0xf bound_ctrl:1
	s_nop 1
	v_add_f32_dpp v66, v66, v66 row_shr:2 row_mask:0xf bank_mask:0xf bound_ctrl:1
	s_nop 1
	v_add_f32_dpp v66, v66, v66 row_shr:4 row_mask:0xf bank_mask:0xf bound_ctrl:1
	s_nop 1
	v_add_f32_dpp v66, v66, v66 row_shr:8 row_mask:0xf bank_mask:0xf bound_ctrl:1
	s_nop 0
	v_readlane_b32 s9, v66, 15
	v_readlane_b32 s10, v66, 31
	v_readlane_b32 s11, v66, 47
	v_readlane_b32 vcc_lo, v66, 63
	s_nop 1
	v_mov_b32_e32 v66, s9
	v_add_f32_e32 v66, s10, v66
	v_add_f32_e32 v66, s11, v66
	v_add_f32_e32 v66, vcc_lo, v66
	v_mul_f32_e32 v66, 0x3a800000, v66
	v_add_f32_e32 v66, 0x3727c5ac, v66
	v_rsq_f32_e32 v118, v66
	s_nop 0
	v_mov_b32_e32 v119, v118
	v_pk_mul_f32 v[0:1], v[0:1], v[118:119]
	v_pk_mul_f32 v[2:3], v[2:3], v[118:119]
	v_pk_mul_f32 v[4:5], v[4:5], v[118:119]
	v_pk_mul_f32 v[6:7], v[6:7], v[118:119]
	v_pk_mul_f32 v[8:9], v[8:9], v[118:119]
	v_pk_mul_f32 v[10:11], v[10:11], v[118:119]
	v_pk_mul_f32 v[12:13], v[12:13], v[118:119]
	v_pk_mul_f32 v[14:15], v[14:15], v[118:119]
	v_pk_fma_f32 v[76:77], v[0:1], v[34:35], v[50:51]
	v_pk_fma_f32 v[78:79], v[2:3], v[36:37], v[52:53]
	v_pk_fma_f32 v[80:81], v[4:5], v[38:39], v[54:55]
	v_pk_fma_f32 v[82:83], v[6:7], v[40:41], v[56:57]
	v_pk_fma_f32 v[84:85], v[8:9], v[42:43], v[58:59]
	v_pk_fma_f32 v[86:87], v[10:11], v[44:45], v[60:61]
	v_pk_fma_f32 v[88:89], v[12:13], v[46:47], v[62:63]
	v_pk_fma_f32 v[90:91], v[14:15], v[48:49], v[64:65]
	s_cmp_lg_u32 s8, 0
	s_cbranch_scc1 .Lln2_f32_2
	v_cvt_pk_bf16_f32 v92, v76, v77
	v_cvt_pk_bf16_f32 v93, v78, v79
	v_cvt_pk_bf16_f32 v94, v80, v81
	v_cvt_pk_bf16_f32 v95, v82, v83
	v_cvt_pk_bf16_f32 v96, v84, v85
	v_cvt_pk_bf16_f32 v97, v86, v87
	v_cvt_pk_bf16_f32 v98, v88, v89
	v_cvt_pk_bf16_f32 v99, v90, v91
	global_store_dwordx2 v115, v[92:93], s[2:3] offset:0
	global_store_dwordx2 v115, v[94:95], s[2:3] offset:512
	global_store_dwordx2 v115, v[96:97], s[2:3] offset:1024
	global_store_dwordx2 v115, v[98:99], s[2:3] offset:1536
	s_branch .Lln2_st_2

; __device__ __forceinline__ void phase_ln(float* R, const float* __restrict__ g, const float* __restrict__ b, bf16_t* xbf, float samp_scale, const float* __restrict__ part, int nsplit, bool f32_all) {
;     ...
;   for (int r = gw; r < MT; r += nw) {
;     float* row = R + (size_t)r * 1024;
;     f32x4 v[4];
; #pragma unroll
;     for (int i = 0; i < 4; ++i) v[i] = *(const f32x4*)(row + i * 256 + lane * 4);
;     if (r >= MP) {
;       for (int sp = 0; sp < nsplit; ++sp) {
;         const float* prow = part + ((size_t)sp * MS + (r - MP)) * 1024;
; #pragma unroll
;         for (int i = 0; i < 4; ++i) v[i] = v[i] + *(const f32x4*)(prow + i * 256 + lane * 4);
;       }
;     }
;     float s = 0.f;
; #pragma unroll
;     for (int i = 0; i < 4; ++i) s += v[i][0] + v[i][1] + v[i][2] + v[i][3];
; #pragma unroll
;     for (int o = 32; o >= 1; o >>= 1) s += __shfl_xor(s, o);
;     const float mean = s * (1.f / 1024.f);
;     float ss = 0.f;
; #pragma unroll
;     for (int i = 0; i < 4; ++i) { v[i] = v[i] - mean; ss += v[i][0] * v[i][0] + v[i][1] * v[i][1] + v[i][2] * v[i][2] + v[i][3] * v[i][3]; }
; #pragma unroll
;     for (int o = 32; o >= 1; o >>= 1) ss += __shfl_xor(ss, o);
;     const float rstd = rsqrtf(ss * (1.f / 1024.f) + LN_EPS);
; #pragma unroll
;     for (int i = 0; i < 4; ++i) {
;       const f32x4 y = v[i] * rstd * gv[i] + bv[i];
;       if (r >= MP) *(f32x4*)(row + i * 256 + lane * 4) = y * samp_scale;
;       else if (f32_all) *(f32x4*)(row + i * 256 + lane * 4) = y;
;       if (xbf) {
;         u32x2 wv;
;         wv[0] = cvt_pk_bf16(y[0], y[1]); wv[1] = cvt_pk_bf16(y[2], y[3]);
;         *(u32x2*)(xbf + (size_t)r * 1024 + i * 256 + lane * 4) = wv;
;       }
;     }
.Lln2_st_14:
	s_add_u32 s2, s2, 0x400000
	s_addc_u32 s3, s3, 0
	s_waitcnt vmcnt(4)
	v_pk_add_f32 v[66:67], v[18:19], v[20:21]
	v_pk_add_f32 v[68:69], v[22:23], v[24:25]
	v_pk_add_f32 v[70:71], v[26:27], v[28:29]
	v_pk_add_f32 v[72:73], v[30:31], v[32:33]
	v_pk_add_f32 v[66:67], v[66:67], v[68:69]
	v_pk_add_f32 v[70:71], v[70:71], v[72:73]
	v_pk_add_f32 v[66:67], v[66:67], v[70:71]
	v_add_f32_e32 v66, v66, v67
	s_nop 1
	v_add_f32_dpp v66, v66, v66 row_shr:1 row_mask:0xf bank_mask:0xf bound_ctrl:1
	s_nop 1
	v_add_f32_dpp v66, v66, v66 row_shr:2 row_mask:0xf bank_mask:0xf bound_ctrl:1
	s_nop 1
	v_add_f32_dpp v66, v66, v66 row_shr:4 row_mask:0xf bank_mask:0xf bound_ctrl:1
	s_nop 1
	v_add_f32_dpp v66, v66, v66 row_shr:8 row_mask:0xf bank_mask:0xf bound_ctrl:1
	s_nop 0
	v_readlane_b32 s9, v66, 15
	v_readlane_b32 s10, v66, 31
	v_readlane_b32 s11, v66, 47
	v_readlane_b32 vcc_lo, v66, 63
	s_nop 1
	v_mov_b32_e32 v66, s9
	v_add_f32_e32 v66, s10, v66
	v_add_f32_e32 v66, s11, v66
	v_add_f32_e32 v66, vcc_lo, v66
	v_mul_f32_e32 v116, 0x3a800000, v66
	v_mov_b32_e32 v117, v116
	v_pk_add_f32 v[18:19], v[18:19], v[116:117] neg_lo:[0,1] neg_hi:[0,1]
	v_pk_add_f32 v[20:21], v[20:21], v[116:117] neg_lo:[0,1] neg_hi:[0,1]
	v_pk_add_f32 v[22:23], v[22:23], v[116:117] neg_lo:[0,1] neg_hi:[0,1]
	v_pk_add_f32 v[24:25], v[24:25], v[116:117] neg_lo:[0,1] neg_hi:[0,1]
	v_pk_add_f32 v[26:27], v[26:27], v[116:117] neg_lo:[0,1] neg_hi:[0,1]
	v_pk_add_f32 v[28:29], v[28:29], v[116:117] neg_lo:[0,1] neg_hi:[0,1]
	v_pk_add_f32 v[30:31], v[30:31], v[116:117] neg_lo:[0,1] neg_hi:[0,1]
	v_pk_add_f32 v[32:33], v[32:33], v[116:117] neg_lo:[0,1] neg_hi:[0,1]
	v_pk_mul_f32 v[66:67], v[18:19], v[18:19]
	v_pk_mul_f32 v[68:69], v[20:21], v[20:21]
	v_pk_fma_f32 v[66:67], v[22:23], v[22:23], v[66:67]
	v_pk_fma_f32 v[68:69], v[24:25], v[24:25], v[68:69]
	v_pk_fma_f32 v[66:67], v[26:27], v[26:27], v[66:67]
	v_pk_fma_f32 v[68:69], v[28:29], v[28:29], v[68:69]
	v_pk_fma_f32 v[66:67], v[30:31], v[30:31], v[66:67]
	v_pk_fma_f32 v[68:69], v[32:33], v[32:33], v[68:69]
	v_pk_add_f32 v[66:67], v[66:67], v[68:69]
	v_add_f32_e32 v66, v66, v67
	s_nop 1
	v_add_f32_dpp v66, v66, v66 row_shr:1 row_mask:0xf bank_mask:0xf bound_ctrl:1
	s_nop 1
	v_add_f32_dpp v66, v66, v66 row_shr:2 row_mask:0xf bank_mask:0xf bound_ctrl:1
	s_nop 1
	v_add_f32_dpp v66, v66, v66 row_shr:4 row_mask:0xf bank_mask:0xf bound_ctrl:1
	s_nop 1
	v_add_f32_dpp v66, v66, v66 row_shr:8 row_mask:0xf bank_mask:0xf bound_ctrl:1
	s_nop 0
	v_readlane_b32 s9, v66, 15
	v_readlane_b32 s10, v66, 31
	v_readlane_b32 s11, v66, 47
	v_readlane_b32 vcc_lo, v66, 63
	s_nop 1
	v_mov_b32_e32 v66, s9
	v_add_f32_e32 v66, s10, v66
	v_add_f32_e32 v66, s11, v66
	v_add_f32_e32 v66, vcc_lo, v66
	v_mul_f32_e32 v66, 0x3a800000, v66
	v_add_f32_e32 v66, 0x3727c5ac, v66
	v_rsq_f32_e32 v118, v66
	s_nop 0
	v_mov_b32_e32 v119, v118
	v_pk_mul_f32 v[18:19], v[18:19], v[118:119]
	v_pk_mul_f32 v[20:21], v[20:21], v[118:119]
	v_pk_mul_f32 v[22:23], v[22:23], v[118:119]
	v_pk_mul_f32 v[24:25], v[24:25], v[118:119]
	v_pk_mul_f32 v[26:27], v[26:27], v[118:119]
	v_pk_mul_f32 v[28:29], v[28:29], v[118:119]
	v_pk_mul_f32 v[30:31], v[30:31], v[118:119]
	v_pk_mul_f32 v[32:33], v[32:33], v[118:119]
	v_pk_fma_f32 v[76:77], v[18:19], v[34:35], v[50:51]
	v_pk_fma_f32 v[78:79], v[20:21], v[36:37], v[52:53]
	v_pk_fma_f32 v[80:81], v[22:23], v[38:39], v[54:55]
	v_pk_fma_f32 v[82:83], v[24:25], v[40:41], v[56:57]
	v_pk_fma_f32 v[84:85], v[26:27], v[42:43], v[58:59]
	v_pk_fma_f32 v[86:87], v[28:29], v[44:45], v[60:61]
	v_pk_fma_f32 v[88:89], v[30:31], v[46:47], v[62:63]
	v_pk_fma_f32 v[90:91], v[32:33], v[48:49], v[64:65]
	s_cmp_lg_u32 s8, 0
	s_cbranch_scc1 .Lln2_f32_15
	v_cvt_pk_bf16_f32 v92, v76, v77
	v_cvt_pk_bf16_f32 v93, v78, v79
	v_cvt_pk_bf16_f32 v94, v80, v81
	v_cvt_pk_bf16_f32 v95, v82, v83
	v_cvt_pk_bf16_f32 v96, v84, v85
	v_cvt_pk_bf16_f32 v97, v86, v87
	v_cvt_pk_bf16_f32 v98, v88, v89
	v_cvt_pk_bf16_f32 v99, v90, v91
	global_store_dwordx2 v115, v[92:93], s[2:3] offset:0
	global_store_dwordx2 v115, v[94:95], s[2:3] offset:512
	global_store_dwordx2 v115, v[96:97], s[2:3] offset:1024
	global_store_dwordx2 v115, v[98:99], s[2:3] offset:1536
	s_branch .Lln2_st_15
.Lln2_f32_15:
	global_store_dwordx4 v114, v[76:79], s[0:1] offset:0
	global_store_dwordx4 v114, v[80:83], s[0:1] offset:1024
	global_store_dwordx4 v114, v[84:87], s[0:1] offset:2048
	global_store_dwordx4 v114, v[88:91], s[0:1] offset:3072
; __device__ __forceinline__ void phase_ln(float* R, const float* __restrict__ g, const float* __restrict__ b, bf16_t* xbf, float samp_scale, const float* __restrict__ part, int nsplit, bool f32_all) {
;     ...
;   for (int r = gw; r < MT; r += nw) {
;     float* row = R + (size_t)r * 1024;
;     f32x4 v[4];
; #pragma unroll
;     for (int i = 0; i < 4; ++i) v[i] = *(const f32x4*)(row + i * 256 + lane * 4);
;     if (r >= MP) {
;       for (int sp = 0; sp < nsplit; ++sp) {
;         const float* prow = part + ((size_t)sp * MS + (r - MP)) * 1024;
; #pragma unroll
;         for (int i = 0; i < 4; ++i) v[i] = v[i] + *(const f32x4*)(prow + i * 256 + lane * 4);
;       }
;     }
.Lln2_st_15:
	s_add_u32 s2, s2, 0x400000
	s_addc_u32 s3, s3, 0
	v_readfirstlane_b32 s10, v244
	v_readlane_b32 s9, v254, 6
	s_lshr_b32 s10, s10, 6
	s_cmp_ge_u32 s10, 2
	s_cbranch_scc1 .Lln2_done
	s_lshl_b32 s9, s9, 1
	s_add_i32 s9, s9, s10
	s_lshl_b32 s11, s9, 12
	s_add_u32 s11, s11, 0x8000000
	s_add_u32 s0, s4, s11
	s_addc_u32 s1, s5, 0
	s_lshl_b32 s11, s9, 11
	s_add_u32 s11, s11, 0x79c0000
	s_add_u32 s2, s6, s11
	s_addc_u32 s3, s7, 0
	s_lshl_b32 s11, s9, 12
	s_add_u32 s11, s11, 0x1e482000
	s_add_u32 s10, s6, s11
	s_addc_u32 s11, s7, 0
	global_load_dwordx4 v[0:3], v114, s[0:1] offset:0
	global_load_dwordx4 v[4:7], v114, s[0:1] offset:1024
	global_load_dwordx4 v[8:11], v114, s[0:1] offset:2048
	global_load_dwordx4 v[12:15], v114, s[0:1] offset:3072
	global_load_dwordx4 v[18:21], v114, s[10:11] offset:0
	global_load_dwordx4 v[22:25], v114, s[10:11] offset:1024
	global_load_dwordx4 v[26:29], v114, s[10:11] offset:2048
	global_load_dwordx4 v[30:33], v114, s[10:11] offset:3072
	s_add_u32 s10, s10, 0x200000
	s_addc_u32 s11, s11, 0
	global_load_dwordx4 v[66:69], v114, s[10:11] offset:0
	global_load_dwordx4 v[70:73], v114, s[10:11] offset:1024
	global_load_dwordx4 v[74:77], v114, s[10:11] offset:2048
	global_load_dwordx4 v[78:81], v114, s[10:11] offset:3072
	s_add_u32 s10, s10, 0x200000
	s_addc_u32 s11, s11, 0
	global_load_dwordx4 v[82:85], v114, s[10:11] offset:0
	global_load_dwordx4 v[86:89], v114, s[10:11] offset:1024
	global_load_dwordx4 v[90:93], v114, s[10:11] offset:2048
	global_load_dwordx4 v[94:97], v114, s[10:11] offset:3072
	s_add_u32 s10, s10, 0x200000
	s_addc_u32 s11, s11, 0
	global_load_dwordx4 v[98:101], v114, s[10:11] offset:0
	global_load_dwordx4 v[102:105], v114, s[10:11] offset:1024
	global_load_dwordx4 v[106:109], v114, s[10:11] offset:2048
	global_load_dwordx4 v[110:113], v114, s[10:11] offset:3072
	s_add_u32 s10, s10, 0x200000
	s_addc_u32 s11, s11, 0
	s_waitcnt vmcnt(0)
	v_pk_add_f32 v[0:1], v[0:1], v[18:19]
	v_pk_add_f32 v[2:3], v[2:3], v[20:21]
	v_pk_add_f32 v[4:5], v[4:5], v[22:23]
	v_pk_add_f32 v[6:7], v[6:7], v[24:25]
	v_pk_add_f32 v[8:9], v[8:9], v[26:27]
	v_pk_add_f32 v[10:11], v[10:11], v[28:29]
	v_pk_add_f32 v[12:13], v[12:13], v[30:31]
	v_pk_add_f32 v[14:15], v[14:15], v[32:33]
	v_pk_add_f32 v[0:1], v[0:1], v[66:67]
	v_pk_add_f32 v[2:3], v[2:3], v[68:69]
	v_pk_add_f32 v[4:5], v[4:5], v[70:71]
	v_pk_add_f32 v[6:7], v[6:7], v[72:73]
	v_pk_add_f32 v[8:9], v[8:9], v[74:75]
	v_pk_add_f32 v[10:11], v[10:11], v[76:77]
	v_pk_add_f32 v[12:13], v[12:13], v[78:79]
	v_pk_add_f32 v[14:15], v[14:15], v[80:81]
	v_pk_add_f32 v[0:1], v[0:1], v[82:83]
	v_pk_add_f32 v[2:3], v[2:3], v[84:85]
	v_pk_add_f32 v[4:5], v[4:5], v[86:87]
	v_pk_add_f32 v[6:7], v[6:7], v[88:89]
	v_pk_add_f32 v[8:9], v[8:9], v[90:91]
	v_pk_add_f32 v[10:11], v[10:11], v[92:93]
	v_pk_add_f32 v[12:13], v[12:13], v[94:95]
	v_pk_add_f32 v[14:15], v[14:15], v[96:97]
	v_pk_add_f32 v[0:1], v[0:1], v[98:99]
	v_pk_add_f32 v[2:3], v[2:3], v[100:101]
	v_pk_add_f32 v[4:5], v[4:5], v[102:103]
	v_pk_add_f32 v[6:7], v[6:7], v[104:105]
	v_pk_add_f32 v[8:9], v[8:9], v[106:107]
	v_pk_add_f32 v[10:11], v[10:11], v[108:109]
	v_pk_add_f32 v[12:13], v[12:13], v[110:111]
	v_pk_add_f32 v[14:15], v[14:15], v[112:113]
	global_load_dwordx4 v[18:21], v114, s[10:11] offset:0
	global_load_dwordx4 v[22:25], v114, s[10:11] offset:1024
	global_load_dwordx4 v[26:29], v114, s[10:11] offset:2048
	global_load_dwordx4 v[30:33], v114, s[10:11] offset:3072
	s_add_u32 s10, s10, 0x200000
	s_addc_u32 s11, s11, 0
	global_load_dwordx4 v[66:69], v114, s[10:11] offset:0
	global_load_dwordx4 v[70:73], v114, s[10:11] offset:1024
	global_load_dwordx4 v[74:77], v114, s[10:11] offset:2048
	global_load_dwordx4 v[78:81], v114, s[10:11] offset:3072
	s_add_u32 s10, s10, 0x200000
	s_addc_u32 s11, s11, 0
	global_load_dwordx4 v[82:85], v114, s[10:11] offset:0
	global_load_dwordx4 v[86:89], v114, s[10:11] offset:1024
	global_load_dwordx4 v[90:93], v114, s[10:11] offset:2048
	global_load_dwordx4 v[94:97], v114, s[10:11] offset:3072
	s_add_u32 s10, s10, 0x200000
	s_addc_u32 s11, s11, 0
	global_load_dwordx4 v[98:101], v114, s[10:11] offset:0
	global_load_dwordx4 v[102:105], v114, s[10:11] offset:1024
	global_load_dwordx4 v[106:109], v114, s[10:11] offset:2048
	global_load_dwordx4 v[110:113], v114, s[10:11] offset:3072
	s_add_u32 s10, s10, 0x200000
	s_addc_u32 s11, s11, 0
	s_waitcnt vmcnt(0)
; __device__ __forceinline__ void phase_ln(float* R, const float* __restrict__ g, const float* __restrict__ b, bf16_t* xbf, float samp_scale, const float* __restrict__ part, int nsplit, bool f32_all) {
;     ...
;     if (r >= MP) {
;       for (int sp = 0; sp < nsplit; ++sp) {
;         const float* prow = part + ((size_t)sp * MS + (r - MP)) * 1024;
; #pragma unroll
;         for (int i = 0; i < 4; ++i) v[i] = v[i] + *(const f32x4*)(prow + i * 256 + lane * 4);
;       }
;     }
;     float s = 0.f;
; #pragma unroll
;     for (int i = 0; i < 4; ++i) s += v[i][0] + v[i][1] + v[i][2] + v[i][3];
; #pragma unroll
;     for (int o = 32; o >= 1; o >>= 1) s += __shfl_xor(s, o);
;     const float mean = s * (1.f / 1024.f);
;     float ss = 0.f;
; #pragma unroll
;     for (int i = 0; i < 4; ++i) { v[i] = v[i] - mean; ss += v[i][0] * v[i][0] + v[i][1] * v[i][1] + v[i][2] * v[i][2] + v[i][3] * v[i][3]; }
; #pragma unroll
;     for (int o = 32; o >= 1; o >>= 1) ss += __shfl_xor(ss, o);
;     const float rstd = rsqrtf(ss * (1.f / 1024.f) + LN_EPS);
; #pragma unroll
;     for (int i = 0; i < 4; ++i) {
;       const f32x4 y = v[i] * rstd * gv[i] + bv[i];
;       if (r >= MP) *(f32x4*)(row + i * 256 + lane * 4) = y * samp_scale;
;       else if (f32_all) *(f32x4*)(row + i * 256 + lane * 4) = y;
;       if (xbf) {
;         u32x2 wv;
;         wv[0] = cvt_pk_bf16(y[0], y[1]); wv[1] = cvt_pk_bf16(y[2], y[3]);
;         *(u32x2*)(xbf + (size_t)r * 1024 + i * 256 + lane * 4) = wv;
;       }
;     }
	v_pk_add_f32 v[0:1], v[0:1], v[18:19]
	v_pk_add_f32 v[2:3], v[2:3], v[20:21]
	v_pk_add_f32 v[4:5], v[4:5], v[22:23]
	v_pk_add_f32 v[6:7], v[6:7], v[24:25]
	v_pk_add_f32 v[8:9], v[8:9], v[26:27]
	v_pk_add_f32 v[10:11], v[10:11], v[28:29]
	v_pk_add_f32 v[12:13], v[12:13], v[30:31]
	v_pk_add_f32 v[14:15], v[14:15], v[32:33]
	v_pk_add_f32 v[0:1], v[0:1], v[66:67]
	v_pk_add_f32 v[2:3], v[2:3], v[68:69]
	v_pk_add_f32 v[4:5], v[4:5], v[70:71]
	v_pk_add_f32 v[6:7], v[6:7], v[72:73]
	v_pk_add_f32 v[8:9], v[8:9], v[74:75]
	v_pk_add_f32 v[10:11], v[10:11], v[76:77]
	v_pk_add_f32 v[12:13], v[12:13], v[78:79]
	v_pk_add_f32 v[14:15], v[14:15], v[80:81]
	v_pk_add_f32 v[0:1], v[0:1], v[82:83]
	v_pk_add_f32 v[2:3], v[2:3], v[84:85]
	v_pk_add_f32 v[4:5], v[4:5], v[86:87]
	v_pk_add_f32 v[6:7], v[6:7], v[88:89]
	v_pk_add_f32 v[8:9], v[8:9], v[90:91]
	v_pk_add_f32 v[10:11], v[10:11], v[92:93]
	v_pk_add_f32 v[12:13], v[12:13], v[94:95]
	v_pk_add_f32 v[14:15], v[14:15], v[96:97]
	v_pk_add_f32 v[0:1], v[0:1], v[98:99]
	v_pk_add_f32 v[2:3], v[2:3], v[100:101]
	v_pk_add_f32 v[4:5], v[4:5], v[102:103]
	v_pk_add_f32 v[6:7], v[6:7], v[104:105]
	v_pk_add_f32 v[8:9], v[8:9], v[106:107]
	v_pk_add_f32 v[10:11], v[10:11], v[108:109]
	v_pk_add_f32 v[12:13], v[12:13], v[110:111]
	v_pk_add_f32 v[14:15], v[14:15], v[112:113]
	v_pk_add_f32 v[66:67], v[0:1], v[2:3]
	v_pk_add_f32 v[68:69], v[4:5], v[6:7]
	v_pk_add_f32 v[70:71], v[8:9], v[10:11]
	v_pk_add_f32 v[72:73], v[12:13], v[14:15]
	v_pk_add_f32 v[66:67], v[66:67], v[68:69]
	v_pk_add_f32 v[70:71], v[70:71], v[72:73]
	v_pk_add_f32 v[66:67], v[66:67], v[70:71]
	v_add_f32_e32 v66, v66, v67
	s_nop 1
	v_add_f32_dpp v66, v66, v66 row_shr:1 row_mask:0xf bank_mask:0xf bound_ctrl:1
	s_nop 1
	v_add_f32_dpp v66, v66, v66 row_shr:2 row_mask:0xf bank_mask:0xf bound_ctrl:1
	s_nop 1
	v_add_f32_dpp v66, v66, v66 row_shr:4 row_mask:0xf bank_mask:0xf bound_ctrl:1
	s_nop 1
	v_add_f32_dpp v66, v66, v66 row_shr:8 row_mask:0xf bank_mask:0xf bound_ctrl:1
	s_nop 0
	v_readlane_b32 s9, v66, 15
	v_readlane_b32 s10, v66, 31
	v_readlane_b32 s11, v66, 47
	v_readlane_b32 vcc_lo, v66, 63
	s_nop 1
	v_mov_b32_e32 v66, s9
	v_add_f32_e32 v66, s10, v66
	v_add_f32_e32 v66, s11, v66
	v_add_f32_e32 v66, vcc_lo, v66
	v_mul_f32_e32 v116, 0x3a800000, v66
	v_mov_b32_e32 v117, v116
	v_pk_add_f32 v[0:1], v[0:1], v[116:117] neg_lo:[0,1] neg_hi:[0,1]
	v_pk_add_f32 v[2:3], v[2:3], v[116:117] neg_lo:[0,1] neg_hi:[0,1]
	v_pk_add_f32 v[4:5], v[4:5], v[116:117] neg_lo:[0,1] neg_hi:[0,1]
	v_pk_add_f32 v[6:7], v[6:7], v[116:117] neg_lo:[0,1] neg_hi:[0,1]
	v_pk_add_f32 v[8:9], v[8:9], v[116:117] neg_lo:[0,1] neg_hi:[0,1]
	v_pk_add_f32 v[10:11], v[10:11], v[116:117] neg_lo:[0,1] neg_hi:[0,1]
	v_pk_add_f32 v[12:13], v[12:13], v[116:117] neg_lo:[0,1] neg_hi:[0,1]
	v_pk_add_f32 v[14:15], v[14:15], v[116:117] neg_lo:[0,1] neg_hi:[0,1]
	v_pk_mul_f32 v[66:67], v[0:1], v[0:1]
	v_pk_mul_f32 v[68:69], v[2:3], v[2:3]
	v_pk_fma_f32 v[66:67], v[4:5], v[4:5], v[66:67]
	v_pk_fma_f32 v[68:69], v[6:7], v[6:7], v[68:69]
	v_pk_fma_f32 v[66:67], v[8:9], v[8:9], v[66:67]
	v_pk_fma_f32 v[68:69], v[10:11], v[10:11], v[68:69]
	v_pk_fma_f32 v[66:67], v[12:13], v[12:13], v[66:67]
	v_pk_fma_f32 v[68:69], v[14:15], v[14:15], v[68:69]
	v_pk_add_f32 v[66:67], v[66:67], v[68:69]
	v_add_f32_e32 v66, v66, v67
	s_nop 1
	v_add_f32_dpp v66, v66, v66 row_shr:1 row_mask:0xf bank_mask:0xf bound_ctrl:1
	s_nop 1
	v_add_f32_dpp v66, v66, v66 row_shr:2 row_mask:0xf bank_mask:0xf bound_ctrl:1
	s_nop 1
	v_add_f32_dpp v66, v66, v66 row_shr:4 row_mask:0xf bank_mask:0xf bound_ctrl:1
	s_nop 1
	v_add_f32_dpp v66, v66, v66 row_shr:8 row_mask:0xf bank_mask:0xf bound_ctrl:1
	s_nop 0
	v_readlane_b32 s9, v66, 15
	v_readlane_b32 s10, v66, 31
	v_readlane_b32 s11, v66, 47
	v_readlane_b32 vcc_lo, v66, 63
	s_nop 1
	v_mov_b32_e32 v66, s9
	v_add_f32_e32 v66, s10, v66
	v_add_f32_e32 v66, s11, v66
	v_add_f32_e32 v66, vcc_lo, v66
	v_mul_f32_e32 v66, 0x3a800000, v66
	v_add_f32_e32 v66, 0x3727c5ac, v66
	v_rsq_f32_e32 v118, v66
	s_nop 0
	v_mov_b32_e32 v119, v118
	v_pk_mul_f32 v[0:1], v[0:1], v[118:119]
	v_pk_mul_f32 v[2:3], v[2:3], v[118:119]
	v_pk_mul_f32 v[4:5], v[4:5], v[118:119]
	v_pk_mul_f32 v[6:7], v[6:7], v[118:119]
	v_pk_mul_f32 v[8:9], v[8:9], v[118:119]
	v_pk_mul_f32 v[10:11], v[10:11], v[118:119]
	v_pk_mul_f32 v[12:13], v[12:13], v[118:119]
	v_pk_mul_f32 v[14:15], v[14:15], v[118:119]
	v_pk_fma_f32 v[76:77], v[0:1], v[34:35], v[50:51]
	v_pk_fma_f32 v[78:79], v[2:3], v[36:37], v[52:53]
	v_pk_fma_f32 v[80:81], v[4:5], v[38:39], v[54:55]
	v_pk_fma_f32 v[82:83], v[6:7], v[40:41], v[56:57]
	v_pk_fma_f32 v[84:85], v[8:9], v[42:43], v[58:59]
	v_pk_fma_f32 v[86:87], v[10:11], v[44:45], v[60:61]
	v_pk_fma_f32 v[88:89], v[12:13], v[46:47], v[62:63]
	v_pk_fma_f32 v[90:91], v[14:15], v[48:49], v[64:65]
	s_cmp_lg_u32 s8, 0
	s_cselect_b32 s9, 1.0, 0x3fb504f3
	v_mov_b32_e32 v120, s9
	v_mov_b32_e32 v121, s9
	v_pk_mul_f32 v[0:1], v[76:77], v[120:121]
	v_pk_mul_f32 v[2:3], v[78:79], v[120:121]
	v_pk_mul_f32 v[4:5], v[80:81], v[120:121]
	v_pk_mul_f32 v[6:7], v[82:83], v[120:121]
	v_pk_mul_f32 v[8:9], v[84:85], v[120:121]
	v_pk_mul_f32 v[10:11], v[86:87], v[120:121]
	v_pk_mul_f32 v[12:13], v[88:89], v[120:121]
	v_pk_mul_f32 v[14:15], v[90:91], v[120:121]
	global_store_dwordx4 v114, v[0:3], s[0:1] offset:0
	global_store_dwordx4 v114, v[4:7], s[0:1] offset:1024
	global_store_dwordx4 v114, v[8:11], s[0:1] offset:2048
	global_store_dwordx4 v114, v[12:15], s[0:1] offset:3072
	s_cmp_lg_u32 s8, 0
	s_cbranch_scc1 .Lln2_done
	v_cvt_pk_bf16_f32 v92, v76, v77
	v_cvt_pk_bf16_f32 v93, v78, v79
	v_cvt_pk_bf16_f32 v94, v80, v81
	v_cvt_pk_bf16_f32 v95, v82, v83
	v_cvt_pk_bf16_f32 v96, v84, v85
	v_cvt_pk_bf16_f32 v97, v86, v87
	v_cvt_pk_bf16_f32 v98, v88, v89
	v_cvt_pk_bf16_f32 v99, v90, v91
	global_store_dwordx2 v115, v[92:93], s[2:3] offset:0
	global_store_dwordx2 v115, v[94:95], s[2:3] offset:512
	global_store_dwordx2 v115, v[96:97], s[2:3] offset:1024
	global_store_dwordx2 v115, v[98:99], s[2:3] offset:1536

; __device__ __forceinline__ int otid() { int t = threadIdx.x; asm volatile("" : "+v"(t)); return t; }
; __device__ __forceinline__ void phase_ln(float* R, const float* __restrict__ g, const float* __restrict__ b, bf16_t* xbf, float samp_scale, const float* __restrict__ part, int nsplit, bool f32_all) {
;   const int tid = otid(), lane = tid & 63, gw = blockIdx.x * 8 + (tid >> 6), nw = gridDim.x * 8;
;   f32x4 gv[4], bv[4];
; #pragma unroll
;   for (int i = 0; i < 4; ++i) { gv[i] = *(const f32x4*)(g + i * 256 + lane * 4); bv[i] = *(const f32x4*)(b + i * 256 + lane * 4); }
;   for (int r = gw; r < MT; r += nw) {
;     float* row = R + (size_t)r * 1024;
;     f32x4 v[4];
; #pragma unroll
;     for (int i = 0; i < 4; ++i) v[i] = *(const f32x4*)(row + i * 256 + lane * 4);
.Lln2_orig:
	v_readlane_b32 s12, v254, 2
	v_readlane_b32 s13, v254, 3
	v_mov_b32_e32 v34, v244
	s_waitcnt lgkmcnt(0)
	s_barrier
	v_readlane_b32 s0, v254, 15
	v_ashrrev_i32_e32 v0, 6, v34
	s_nop 0
	v_add_u32_e32 v54, s0, v0
	s_mov_b32 s0, 0x8200
	v_cmp_gt_i32_e32 vcc, s0, v54
	s_and_saveexec_b64 s[10:11], vcc
	s_cbranch_execz .LBB0_3981
	s_load_dwordx8 s[0:7], s[12:13], 0x98
	s_lshl_b64 s[8:9], s[8:9], 2
	v_lshlrev_b32_e32 v0, 4, v34
	v_and_b32_e32 v16, 0x3f0, v0
	v_mov_b32_e32 v35, 0x3fb504f3
	s_waitcnt lgkmcnt(0)
	s_add_u32 s0, s0, s8
	s_addc_u32 s1, s1, s9
	s_add_u32 s2, s2, s8
	s_addc_u32 s3, s3, s9
	global_load_dwordx4 v[0:3], v16, s[0:1]
	global_load_dwordx4 v[4:7], v16, s[0:1] offset:1024
	global_load_dwordx4 v[8:11], v16, s[2:3]
	global_load_dwordx4 v[12:15], v16, s[2:3] offset:1024
	global_load_dwordx4 v[18:21], v16, s[0:1] offset:2048
	global_load_dwordx4 v[22:25], v16, s[0:1] offset:3072
	global_load_dwordx4 v[26:29], v16, s[2:3] offset:2048
	global_load_dwordx4 v[30:33], v16, s[2:3] offset:3072
	v_readlane_b32 s8, v255, 14
	v_readlane_b32 s9, v255, 15
	v_lshl_add_u64 v[36:37], s[6:7], 0, v[16:17]
	v_and_b32_e32 v16, 64, v252
	v_cndmask_b32_e64 v56, 1.0, v35, s[8:9]
	v_add_u32_e32 v16, 64, v16
	v_xor_b32_e32 v35, 32, v252
	v_cmp_lt_i32_e32 vcc, v35, v16
	s_add_u32 s2, s6, 0x39c0000
	s_addc_u32 s3, s7, 0
	v_cndmask_b32_e32 v35, v252, v35, vcc
	v_lshlrev_b32_e32 v68, 2, v35
	v_xor_b32_e32 v35, 16, v252
	v_cmp_lt_i32_e32 vcc, v35, v16
	s_and_b64 s[0:1], exec, s[8:9]
	s_cselect_b32 s1, s3, 0
	v_cndmask_b32_e32 v35, v252, v35, vcc
	v_lshlrev_b32_e32 v69, 2, v35
	v_xor_b32_e32 v35, 8, v252
	v_cmp_lt_i32_e32 vcc, v35, v16
	s_cselect_b32 s0, s2, 0
	s_mov_b64 s[2:3], 0x1e482000
	v_cndmask_b32_e32 v35, v252, v35, vcc
	v_lshlrev_b32_e32 v70, 2, v35
	v_xor_b32_e32 v35, 4, v252
	v_cmp_lt_i32_e32 vcc, v35, v16
	v_ashrrev_i32_e32 v55, 31, v54
	v_lshl_add_u64 v[58:59], v[36:37], 0, s[2:3]
	v_cndmask_b32_e32 v35, v252, v35, vcc
	v_lshlrev_b32_e32 v71, 2, v35
	v_xor_b32_e32 v35, 2, v252
	v_cmp_lt_i32_e32 vcc, v35, v16
	v_lshlrev_b64 v[36:37], 11, v[54:55]
	s_cmp_lg_u64 s[0:1], 0
	v_cndmask_b32_e32 v35, v252, v35, vcc
	v_lshlrev_b32_e32 v72, 2, v35
	v_xor_b32_e32 v35, 1, v252
	v_cmp_lt_i32_e32 vcc, v35, v16
	s_mov_b64 s[6:7], 0
	s_cselect_b64 s[8:9], -1, 0
	v_cndmask_b32_e32 v16, v252, v35, vcc
	v_lshlrev_b32_e32 v73, 2, v16
	v_and_b32_e32 v16, 63, v34
	v_lshl_or_b32 v36, v16, 3, v36
	v_lshl_add_u64 v[34:35], s[0:1], 0, v[36:37]
	s_mov_b64 s[0:1], 0x400
	v_lshl_add_u64 v[62:63], v[34:35], 0, s[0:1]
	v_lshlrev_b64 v[34:35], 12, v[54:55]
	v_lshl_or_b32 v34, v16, 4, v34
	v_mov_b32_e32 v60, v56
	v_mov_b32_e32 v61, v56
	v_lshl_add_u64 v[64:65], s[4:5], 0, v[34:35]
	s_branch .LBB0_3947

; #define LAS __attribute__((address_space(3)))
; __device__ __forceinline__ void xcd_barrier(KP kp, volatile LAS unsigned* st) {
;   asm volatile("s_waitcnt vmcnt(0)" ::: "memory");
;   __syncthreads();
;   if (threadIdx.x == 0) {
.Lln2_end:
	s_waitcnt vmcnt(0)
	s_barrier
	s_mov_b64 s[0:1], exec
	v_readlane_b32 s2, v254, 4
	v_readlane_b32 s3, v254, 5
	s_and_b64 s[2:3], s[0:1], s[2:3]
	s_mov_b64 exec, s[2:3]
	s_cbranch_execnz .LBB0_3982
	s_getpc_b64 s[98:99]
